# ATT: q-fragment loads issued with the K/V tile loads at the top of each unit; sink-load wait moved to first use
# speedup vs baseline: 1.0190x; 1.0048x over previous
; __device__ void att_phase(int wv, const Params& p, unsigned char* lds) {
;     ...
;         const int B = unit >> 2, kh = unit & 3;
;         const int sb = B < 64 ? 0 : (B < 128 ? 64 : 128), se = B < 64 ? 64 : (B < 128 ? 128 : 256);
; #pragma unroll
;         for (int ps = 0; ps < 6; ++ps) { const int idx = tid + ps * NTHR, s = idx >> 3, c8 = (idx & 7) * 8; const int kb = B - 1 + (s >> 7);
;             bf16x8 kv = {0, 0, 0, 0, 0, 0, 0, 0}, vv = {0, 0, 0, 0, 0, 0, 0, 0};
;             if (kb >= sb && kb < se) { const bf16_t* rp = qkv + (size_t)(kb * 128 + (s & 127)) * 1536 + 64 * kh + c8; kv = *(const bf16x8*)(rp + 1024); vv = *(const bf16x8*)(rp + 1280); }
;     ...
;             for (int kk = 0; kk < 2; ++kk) qf[kk] = *(const bf16x8*)(qkv + tokq * 1536 + 64 * h + 32 * kk + 8 * lq);
.LBB0_293:
	s_ashr_i32 s23, s21, 2
	s_and_b32 s6, s21, 3
	s_cmpk_lt_i32 s23, 0x80
	s_movk_i32 s1, 0x100
	s_cselect_b32 s0, 64, 0x80
	s_cselect_b32 s1, 0x80, s1
	s_cmp_lt_i32 s23, 64
	s_cselect_b32 s11, 0, s0
	s_cselect_b32 s10, 64, s1
	s_add_i32 s7, s23, -1
	s_and_b32 s0, s20, 3
	s_lshl_b32 s0, s0, 8
	s_add_i32 s0, s17, s0
	s_ashr_i32 s1, s0, 31
	s_lshl_b64 s[0:1], s[0:1], 1
	v_mov_b32_e32 v2, 0x60000
	s_mov_b64 s[48:49], 0xc000
	v_mad_i64_i32 v[110:111], s[46:47], s23, v2, v[104:105]
	s_nop 0
	v_lshl_add_u64 v[174:175], v[110:111], 0, s[0:1]
	v_add_co_u32_e32 v174, vcc, 0x83ec000, v174
	s_nop 1
	v_addc_co_u32_e32 v175, vcc, 0, v175, vcc
	global_load_dwordx4 v[20:23], v[174:175], off offset:1536
	global_load_dwordx4 v[24:27], v[174:175], off offset:1600
	v_lshl_add_u64 v[174:175], v[174:175], 0, s[48:49]
	global_load_dwordx4 v[28:31], v[174:175], off offset:1536
	global_load_dwordx4 v[32:35], v[174:175], off offset:1600
	v_lshl_add_u64 v[174:175], v[174:175], 0, s[48:49]
	global_load_dwordx4 v[36:39], v[174:175], off offset:1536
	global_load_dwordx4 v[40:43], v[174:175], off offset:1600
	v_lshl_add_u64 v[174:175], v[174:175], 0, s[48:49]
	global_load_dwordx4 v[44:47], v[174:175], off offset:1536
	global_load_dwordx4 v[48:51], v[174:175], off offset:1600
	s_lshl_b32 s36, s6, 7
	v_lshl_add_u64 v[12:13], v[102:103], 0, s[36:37]
	v_add_u32_e32 v10, s7, v115
	v_cmp_le_i32_e32 vcc, s11, v10
	v_cmp_gt_i32_e64 s[0:1], s10, v10
	s_and_b64 s[14:15], vcc, s[0:1]
	v_mov_b32_e32 v180, 0
	v_mov_b32_e32 v181, 0
	v_mov_b32_e32 v182, 0
	v_mov_b32_e32 v183, 0
	v_mov_b32_e32 v184, 0
	v_mov_b32_e32 v185, 0
	v_mov_b32_e32 v186, 0
	v_mov_b32_e32 v187, 0
	s_and_saveexec_b64 s[0:1], s[14:15]
	s_cbranch_execz .Latt_ld_0
	v_lshl_or_b32 v2, v10, 7, v116
	s_movk_i32 s14, 0xc00
	v_mad_u64_u32 v[2:3], s[14:15], v2, s14, v[12:13]
	global_load_dwordx4 v[180:183], v[2:3], off offset:2048
	global_load_dwordx4 v[184:187], v[2:3], off offset:2560

; __device__ void att_phase(int wv, const Params& p, unsigned char* lds) {
;     ...
;         for (int ps = 0; ps < 6; ++ps) { const int idx = tid + ps * NTHR, s = idx >> 3, c8 = (idx & 7) * 8; const int kb = B - 1 + (s >> 7);
;             bf16x8 kv = {0, 0, 0, 0, 0, 0, 0, 0}, vv = {0, 0, 0, 0, 0, 0, 0, 0};
;             if (kb >= sb && kb < se) { const bf16_t* rp = qkv + (size_t)(kb * 128 + (s & 127)) * 1536 + 64 * kh + c8; kv = *(const bf16x8*)(rp + 1024); vv = *(const bf16x8*)(rp + 1280); }
;             *(bf16x8*)(KL + s * KP + c8) = kv;
; #pragma unroll
;             for (int e = 0; e < 8; ++e) VTL[(c8 + e) * VP + s] = (bf16_t)vv[e]; }
;         __syncthreads();
;         const int gq = w >> 1, h = 4 * kh + gq;
;         const float slope = exp2f(-0.5f * (float)(h + 1)), sink = p.b_sinks[h];
;     ...
;             for (int kk = 0; kk < 2; ++kk) qf[kk] = *(const bf16x8*)(qkv + tokq * 1536 + 64 * h + 32 * kk + 8 * lq);
.Latt_ld_5:
	s_or_b64 exec, exec, s[0:1]
	s_mov_b32 s22, 0
	s_lshl_b32 s6, s6, 2
	s_add_i32 s6, s6, s16
	s_add_i32 s7, s6, 1
	s_waitcnt vmcnt(0)
	ds_write_b128 v129, v[180:183]
	ds_write_b16 v130, v184 offset:55296
	ds_write_b16_d16_hi v130, v184 offset:56080
	ds_write_b16 v130, v185 offset:56864
	ds_write_b16_d16_hi v130, v185 offset:57648
	ds_write_b16 v130, v186 offset:58432
	ds_write_b16_d16_hi v130, v186 offset:59216
	ds_write_b16 v130, v187 offset:60000
	ds_write_b16_d16_hi v130, v187 offset:60784
	ds_write_b128 v131, v[188:191]
	ds_write_b16 v132, v192 offset:55296
	ds_write_b16_d16_hi v132, v192 offset:56080
	ds_write_b16 v132, v193 offset:56864
	ds_write_b16_d16_hi v132, v193 offset:57648
	ds_write_b16 v132, v194 offset:58432
	ds_write_b16_d16_hi v132, v194 offset:59216
	ds_write_b16 v132, v195 offset:60000
	ds_write_b16_d16_hi v132, v195 offset:60784
	ds_write_b128 v133, v[196:199]
	ds_write_b16 v134, v200 offset:55296
	ds_write_b16_d16_hi v134, v200 offset:56080
	ds_write_b16 v134, v201 offset:56864
	ds_write_b16_d16_hi v134, v201 offset:57648
	ds_write_b16 v134, v202 offset:58432
	ds_write_b16_d16_hi v134, v202 offset:59216
	ds_write_b16 v134, v203 offset:60000
	ds_write_b16_d16_hi v134, v203 offset:60784
	ds_write_b128 v135, v[204:207]
	ds_write_b16 v136, v208 offset:55296
	ds_write_b16_d16_hi v136, v208 offset:56080
	ds_write_b16 v136, v209 offset:56864
	ds_write_b16_d16_hi v136, v209 offset:57648
	ds_write_b16 v136, v210 offset:58432
	ds_write_b16_d16_hi v136, v210 offset:59216
	ds_write_b16 v136, v211 offset:60000
	ds_write_b16_d16_hi v136, v211 offset:60784
	ds_write_b128 v137, v[212:215]
	ds_write_b16 v138, v216 offset:55296
	ds_write_b16_d16_hi v138, v216 offset:56080
	ds_write_b16 v138, v217 offset:56864
	ds_write_b16_d16_hi v138, v217 offset:57648
	ds_write_b16 v138, v218 offset:58432
	ds_write_b16_d16_hi v138, v218 offset:59216
	ds_write_b16 v138, v219 offset:60000
	ds_write_b16_d16_hi v138, v219 offset:60784
	ds_write_b128 v139, v[220:223]
	ds_write_b16 v140, v224 offset:55296
	ds_write_b16_d16_hi v140, v224 offset:56080
	ds_write_b16 v140, v225 offset:56864
	ds_write_b16_d16_hi v140, v225 offset:57648
	ds_write_b16 v140, v226 offset:58432
	ds_write_b16_d16_hi v140, v226 offset:59216
	ds_write_b16 v140, v227 offset:60000
	ds_write_b16_d16_hi v140, v227 offset:60784
	v_cvt_f32_i32_e32 v2, s7
	s_and_b32 s0, s20, 3
	s_lshl_b32 s0, s0, 8
	s_add_i32 s0, s17, s0
	s_ashr_i32 s1, s0, 31
	v_mul_f32_e32 v3, -0.5, v2
	s_mov_b32 s7, 0xc2fc0000
	s_lshl_b64 s[0:1], s[0:1], 1
	v_cmp_gt_f32_e32 vcc, s7, v3
	s_and_b64 s[14:15], vcc, exec
	s_cselect_b32 s14, 0xffffffc0, 0
	s_ashr_i32 s7, s6, 31
	s_lshl_b64 s[6:7], s[6:7], 2
	s_add_u32 s6, s58, s6
	s_addc_u32 s7, s59, s7
	s_waitcnt lgkmcnt(0)
	s_barrier
	global_load_dword v146, v0, s[6:7]
	v_mov_b32_e32 v3, 0x42800000
	v_cndmask_b32_e32 v3, 0, v3, vcc
	v_fmac_f32_e32 v3, -0.5, v2
	v_exp_f32_e32 v2, v3
	s_cmp_gt_i32 s23, s11
	s_cselect_b64 s[6:7], -1, 0
	s_cmp_le_i32 s23, s10
	v_ldexp_f32 v109, v2, s14
	s_cselect_b64 s[14:15], -1, 0
	s_and_b64 s[6:7], s[6:7], s[14:15]
	s_cmp_ge_i32 s23, s11
	s_cselect_b64 s[14:15], -1, 0
	s_cmp_lt_i32 s23, s10
	s_cselect_b64 s[46:47], -1, 0
	s_and_b64 s[14:15], s[14:15], s[46:47]
	s_add_i32 s36, s23, 1
	s_cmp_ge_i32 s36, s11
	s_cselect_b64 s[46:47], -1, 0
	s_cmp_lt_i32 s36, s10
	s_cselect_b64 s[10:11], -1, 0
	v_mov_b32_e32 v2, 0x60000
	s_and_b64 s[10:11], s[46:47], s[10:11]
	v_mad_i64_i32 v[110:111], s[46:47], s23, v2, v[104:105]
	v_mad_i64_i32 v[112:113], s[46:47], s23, v2, v[106:107]
	v_mov_b32_e32 v147, v128
	s_mov_b64 s[48:49], 0xc000
	v_lshl_add_u64 v[174:175], v[110:111], 0, s[0:1]
	v_add_co_u32_e32 v174, vcc, 0x83ec000, v174
	s_nop 1
	v_addc_co_u32_e32 v175, vcc, 0, v175, vcc
	v_mov_b32_e32 v180, v20
	v_mov_b32_e32 v181, v21
	v_mov_b32_e32 v182, v22
	v_mov_b32_e32 v183, v23
	v_mov_b32_e32 v184, v24
	v_mov_b32_e32 v185, v25
	v_mov_b32_e32 v186, v26
	v_mov_b32_e32 v187, v27
	v_lshl_add_u64 v[174:175], v[174:175], 0, s[48:49]
	v_mov_b32_e32 v188, v28
	v_mov_b32_e32 v189, v29
	v_mov_b32_e32 v190, v30
	v_mov_b32_e32 v191, v31
	v_mov_b32_e32 v192, v32
	v_mov_b32_e32 v193, v33
	v_mov_b32_e32 v194, v34
	v_mov_b32_e32 v195, v35
	v_lshl_add_u64 v[174:175], v[174:175], 0, s[48:49]
	v_mov_b32_e32 v196, v36
	v_mov_b32_e32 v197, v37
	v_mov_b32_e32 v198, v38
	v_mov_b32_e32 v199, v39
	v_mov_b32_e32 v200, v40
	v_mov_b32_e32 v201, v41
	v_mov_b32_e32 v202, v42
	v_mov_b32_e32 v203, v43
	v_lshl_add_u64 v[174:175], v[174:175], 0, s[48:49]
	v_mov_b32_e32 v204, v44
	v_mov_b32_e32 v205, v45
	v_mov_b32_e32 v206, v46
	v_mov_b32_e32 v207, v47
	v_mov_b32_e32 v208, v48
	v_mov_b32_e32 v209, v49
	v_mov_b32_e32 v210, v50
	v_mov_b32_e32 v211, v51
	s_and_b64 vcc, s[6:7], s[10:11]
	s_cbranch_vccz .Latt_general
; __device__ __forceinline__ f32x4 mfma16(bf16x8 a, bf16x8 b, f32x4 c) { return __builtin_amdgcn_mfma_f32_16x16x32_bf16(a, b, c, 0, 0, 0); }
; __device__ void att_phase(int wv, const Params& p, unsigned char* lds) {
;     ...
;             for (int cb = 0; cb < 24; ++cb) { f32x4 a = {0, 0, 0, 0};
; #pragma unroll
;                 for (int kk = 0; kk < 2; ++kk) { const bf16x8 kf = *(const bf16x8*)(KL + (16 * cb + lr) * KP + 32 * kk + 8 * lq); a = mfma16(kf, qf[kk], a); }
;                 sc[cb] = a; }
;             float mx = sink;
; #pragma unroll
;             for (int cb = 0; cb < 24; ++cb) { const int kb = B - 1 + (cb >> 3); const bool bval = (kb >= sb && kb < se);
; #pragma unroll
;                 for (int j = 0; j < 4; ++j) { const int krel = 16 * cb + 4 * lq + j - 128;
;                     int dist = qrow - krel; dist = dist < 0 ? -dist : dist;
;                     const float v = (bval && dist <= 128) ? sc[cb][j] * 0.125f - slope * (float)dist : -1e30f;
;                     sc[cb][j] = v; mx = fmaxf(mx, v); } }
	s_mov_b32 s46, 0x3e38aa3b
	s_and_b32 s47, s33, 1
	s_mul_i32 s22, s47, 0x2400
	v_add_u32_e32 v164, s22, v141
	s_lshl_b32 s22, s47, 7
	s_add_i32 s22, s22, 0xd800
	v_add_u32_e32 v165, s22, v142
	v_add_u32_e32 v166, s22, v143
	v_add_u32_e32 v167, s22, v144
	v_add_u32_e32 v168, s22, v145
	s_lshl_b32 s47, s47, 2
	v_and_b32_e32 v172, 15, v250
	v_lshrrev_b32_e32 v173, 4, v250
	v_lshlrev_b32_e32 v173, 2, v173
	v_sub_u32_e32 v108, v172, v173
	v_subrev_u32_e32 v110, 1, v108
	v_subrev_u32_e32 v111, 2, v108
	v_subrev_u32_e32 v177, 3, v108
	v_mul_f32_e32 v147, 0xc1000000, v109
	v_mul_f32_e32 v174, 0x43000000, v109
	v_mul_f32_e32 v176, 0x44800000, v109
	v_cvt_f32_i32_e32 v179, v108
	v_mul_f32_e32 v94, v147, v179
	v_mul_f32_e64 v98, v147, |v179|
	v_cvt_f32_i32_e32 v179, v110
	v_mul_f32_e32 v95, v147, v179
	v_mul_f32_e64 v99, v147, |v179|
	v_cvt_f32_i32_e32 v179, v111
	v_mul_f32_e32 v96, v147, v179
	v_mul_f32_e64 v100, v147, |v179|
	v_cvt_f32_i32_e32 v179, v177
	v_mul_f32_e32 v97, v147, v179
	v_mul_f32_e64 v101, v147, |v179|
	v_lshl_add_u64 v[248:249], v[112:113], 0, s[0:1]
	v_sub_f32_e32 v86, v94, v176
	v_sub_f32_e32 v87, v95, v176
	v_sub_f32_e32 v88, v96, v176
	v_sub_f32_e32 v89, v97, v176
	v_cmp_ge_i32_e32 vcc, 0, v108
	s_nop 1
	v_cndmask_b32_e32 v212, v252, v86, vcc
	v_cmp_ge_i32_e32 vcc, 0, v110
	s_nop 1
	v_cndmask_b32_e32 v213, v252, v87, vcc
	v_cmp_ge_i32_e32 vcc, 0, v111
	s_nop 1
	v_cndmask_b32_e32 v214, v252, v88, vcc
	v_cmp_ge_i32_e32 vcc, 0, v177
	s_nop 1
	v_cndmask_b32_e32 v215, v252, v89, vcc
	ds_read_b128 v[148:151], v164 offset:0
	ds_read_b128 v[152:155], v164 offset:64
	ds_read_b128 v[156:159], v164 offset:2304
	ds_read_b128 v[160:163], v164 offset:2368
	v_add_f32_e32 v90, v86, v174
	v_add_f32_e32 v91, v87, v174
	v_add_f32_e32 v92, v88, v174
	v_add_f32_e32 v93, v89, v174
	s_waitcnt lgkmcnt(2)
	v_mfma_f32_16x16x32_bf16 v[2:5], v[148:151], v[180:183], v[212:215]
	v_mfma_f32_16x16x32_bf16 v[2:5], v[152:155], v[184:187], v[2:5]
	ds_read_b128 v[148:151], v164 offset:4608
	ds_read_b128 v[152:155], v164 offset:4672
	v_add_f32_e32 v86, v90, v174
	v_add_f32_e32 v87, v91, v174
	v_add_f32_e32 v88, v92, v174
	v_add_f32_e32 v89, v93, v174
	s_waitcnt lgkmcnt(2)
	v_mfma_f32_16x16x32_bf16 v[6:9], v[156:159], v[180:183], v[90:93]
	v_mfma_f32_16x16x32_bf16 v[6:9], v[160:163], v[184:187], v[6:9]
	ds_read_b128 v[156:159], v164 offset:6912
	ds_read_b128 v[160:163], v164 offset:6976
	v_add_f32_e32 v90, v86, v174
	v_add_f32_e32 v91, v87, v174
	v_add_f32_e32 v92, v88, v174
	v_add_f32_e32 v93, v89, v174
	s_waitcnt lgkmcnt(2)
	v_mfma_f32_16x16x32_bf16 v[10:13], v[148:151], v[180:183], v[86:89]
	v_mfma_f32_16x16x32_bf16 v[10:13], v[152:155], v[184:187], v[10:13]
	ds_read_b128 v[148:151], v164 offset:9216
	ds_read_b128 v[152:155], v164 offset:9280
	v_add_f32_e32 v86, v90, v174
	v_add_f32_e32 v87, v91, v174
	v_add_f32_e32 v88, v92, v174
	v_add_f32_e32 v89, v93, v174
	s_waitcnt lgkmcnt(2)
	v_mfma_f32_16x16x32_bf16 v[14:17], v[156:159], v[180:183], v[90:93]
	v_mfma_f32_16x16x32_bf16 v[14:17], v[160:163], v[184:187], v[14:17]
	ds_read_b128 v[156:159], v164 offset:11520
	ds_read_b128 v[160:163], v164 offset:11584
	v_add_f32_e32 v90, v86, v174
	v_add_f32_e32 v91, v87, v174
	v_add_f32_e32 v92, v88, v174
	v_add_f32_e32 v93, v89, v174
	s_waitcnt lgkmcnt(2)
	v_mfma_f32_16x16x32_bf16 v[18:21], v[148:151], v[180:183], v[86:89]
	v_mfma_f32_16x16x32_bf16 v[18:21], v[152:155], v[184:187], v[18:21]
	ds_read_b128 v[148:151], v164 offset:13824
	ds_read_b128 v[152:155], v164 offset:13888
	v_add_f32_e32 v86, v90, v174
	v_add_f32_e32 v87, v91, v174
	v_add_f32_e32 v88, v92, v174
	v_add_f32_e32 v89, v93, v174
	s_waitcnt lgkmcnt(2)
	v_mfma_f32_16x16x32_bf16 v[22:25], v[156:159], v[180:183], v[90:93]
	v_mfma_f32_16x16x32_bf16 v[22:25], v[160:163], v[184:187], v[22:25]
	ds_read_b128 v[156:159], v164 offset:16128
	ds_read_b128 v[160:163], v164 offset:16192
	v_add_f32_e32 v90, v86, v174
	v_add_f32_e32 v91, v87, v174
	v_add_f32_e32 v92, v88, v174
	v_add_f32_e32 v93, v89, v174
	s_waitcnt lgkmcnt(2)
	v_mfma_f32_16x16x32_bf16 v[26:29], v[148:151], v[180:183], v[86:89]
	v_mfma_f32_16x16x32_bf16 v[26:29], v[152:155], v[184:187], v[26:29]
	ds_read_b128 v[148:151], v164 offset:18432
	ds_read_b128 v[152:155], v164 offset:18496
	s_waitcnt lgkmcnt(2)
	v_mfma_f32_16x16x32_bf16 v[30:33], v[156:159], v[180:183], v[90:93]
	v_mfma_f32_16x16x32_bf16 v[30:33], v[160:163], v[184:187], v[30:33]
	ds_read_b128 v[156:159], v164 offset:20736
	ds_read_b128 v[160:163], v164 offset:20800
	v_sub_f32_e64 v86, -v94, v174
	v_sub_f32_e64 v87, -v95, v174
	v_sub_f32_e64 v88, -v96, v174
	v_sub_f32_e64 v89, -v97, v174
	s_waitcnt lgkmcnt(2)
	v_mfma_f32_16x16x32_bf16 v[34:37], v[148:151], v[180:183], v[98:101]
	v_mfma_f32_16x16x32_bf16 v[34:37], v[152:155], v[184:187], v[34:37]
	ds_read_b128 v[148:151], v164 offset:23040
	ds_read_b128 v[152:155], v164 offset:23104
	v_sub_f32_e32 v90, v86, v174
	v_sub_f32_e32 v91, v87, v174
	v_sub_f32_e32 v92, v88, v174
	v_sub_f32_e32 v93, v89, v174
	s_waitcnt lgkmcnt(2)
	v_mfma_f32_16x16x32_bf16 v[38:41], v[156:159], v[180:183], v[86:89]
	v_mfma_f32_16x16x32_bf16 v[38:41], v[160:163], v[184:187], v[38:41]
	ds_read_b128 v[156:159], v164 offset:25344
	ds_read_b128 v[160:163], v164 offset:25408
	v_sub_f32_e32 v86, v90, v174
	v_sub_f32_e32 v87, v91, v174
	v_sub_f32_e32 v88, v92, v174
	v_sub_f32_e32 v89, v93, v174
	s_waitcnt lgkmcnt(2)
	v_mfma_f32_16x16x32_bf16 v[42:45], v[148:151], v[180:183], v[90:93]
	v_mfma_f32_16x16x32_bf16 v[42:45], v[152:155], v[184:187], v[42:45]
	ds_read_b128 v[148:151], v164 offset:27648
	ds_read_b128 v[152:155], v164 offset:27712
	v_sub_f32_e32 v90, v86, v174
	v_sub_f32_e32 v91, v87, v174
	v_sub_f32_e32 v92, v88, v174
	v_sub_f32_e32 v93, v89, v174
	s_waitcnt lgkmcnt(2)
; __device__ __forceinline__ f32x4 mfma16(bf16x8 a, bf16x8 b, f32x4 c) { return __builtin_amdgcn_mfma_f32_16x16x32_bf16(a, b, c, 0, 0, 0); }
; __device__ void att_phase(int wv, const Params& p, unsigned char* lds) {
;     ...
;                 for (int kk = 0; kk < 2; ++kk) { const bf16x8 kf = *(const bf16x8*)(KL + (16 * cb + lr) * KP + 32 * kk + 8 * lq); a = mfma16(kf, qf[kk], a); }
;                 sc[cb] = a; }
;             float mx = sink;
; #pragma unroll
;             for (int cb = 0; cb < 24; ++cb) { const int kb = B - 1 + (cb >> 3); const bool bval = (kb >= sb && kb < se);
; #pragma unroll
;                 for (int j = 0; j < 4; ++j) { const int krel = 16 * cb + 4 * lq + j - 128;
;                     int dist = qrow - krel; dist = dist < 0 ? -dist : dist;
;                     const float v = (bval && dist <= 128) ? sc[cb][j] * 0.125f - slope * (float)dist : -1e30f;
;                     sc[cb][j] = v; mx = fmaxf(mx, v); } }
;             mx = fmaxf(mx, __shfl_xor(mx, 16)); mx = fmaxf(mx, __shfl_xor(mx, 32));
;             float sum = 0.f;
; #pragma unroll
;             for (int cb = 0; cb < 24; ++cb)
; #pragma unroll
;                 for (int j = 0; j < 4; ++j) { const float e = __expf(sc[cb][j] - mx); sc[cb][j] = e; sum += e; }
;             sum += __shfl_xor(sum, 16); sum += __shfl_xor(sum, 32);
	v_mfma_f32_16x16x32_bf16 v[46:49], v[156:159], v[180:183], v[86:89]
	v_mfma_f32_16x16x32_bf16 v[46:49], v[160:163], v[184:187], v[46:49]
	ds_read_b128 v[156:159], v164 offset:29952
	ds_read_b128 v[160:163], v164 offset:30016
	v_sub_f32_e32 v86, v90, v174
	v_sub_f32_e32 v87, v91, v174
	v_sub_f32_e32 v88, v92, v174
	v_sub_f32_e32 v89, v93, v174
	s_waitcnt lgkmcnt(2)
	v_mfma_f32_16x16x32_bf16 v[50:53], v[148:151], v[180:183], v[90:93]
	v_mfma_f32_16x16x32_bf16 v[50:53], v[152:155], v[184:187], v[50:53]
	ds_read_b128 v[148:151], v164 offset:32256
	ds_read_b128 v[152:155], v164 offset:32320
	v_sub_f32_e32 v90, v86, v174
	v_sub_f32_e32 v91, v87, v174
	v_sub_f32_e32 v92, v88, v174
	v_sub_f32_e32 v93, v89, v174
	s_waitcnt lgkmcnt(2)
	v_mfma_f32_16x16x32_bf16 v[54:57], v[156:159], v[180:183], v[86:89]
	v_mfma_f32_16x16x32_bf16 v[54:57], v[160:163], v[184:187], v[54:57]
	ds_read_b128 v[156:159], v164 offset:34560
	ds_read_b128 v[160:163], v164 offset:34624
	v_sub_f32_e32 v86, v90, v174
	v_sub_f32_e32 v87, v91, v174
	v_sub_f32_e32 v88, v92, v174
	v_sub_f32_e32 v89, v93, v174
	s_waitcnt lgkmcnt(2)
	v_mfma_f32_16x16x32_bf16 v[58:61], v[148:151], v[180:183], v[90:93]
	v_mfma_f32_16x16x32_bf16 v[58:61], v[152:155], v[184:187], v[58:61]
	ds_read_b128 v[148:151], v164 offset:36864
	ds_read_b128 v[152:155], v164 offset:36928
	v_sub_f32_e32 v90, v86, v174
	v_sub_f32_e32 v91, v87, v174
	v_sub_f32_e32 v92, v88, v174
	v_sub_f32_e32 v93, v89, v174
	v_cmp_le_i32_e32 vcc, 0, v108
	s_nop 1
	v_cndmask_b32_e32 v212, v252, v90, vcc
	v_cmp_le_i32_e32 vcc, 0, v110
	s_nop 1
	v_cndmask_b32_e32 v213, v252, v91, vcc
	v_cmp_le_i32_e32 vcc, 0, v111
	s_nop 1
	v_cndmask_b32_e32 v214, v252, v92, vcc
	v_cmp_le_i32_e32 vcc, 0, v177
	s_nop 1
	v_cndmask_b32_e32 v215, v252, v93, vcc
	s_waitcnt lgkmcnt(2)
	v_mfma_f32_16x16x32_bf16 v[62:65], v[156:159], v[180:183], v[86:89]
	v_mfma_f32_16x16x32_bf16 v[62:65], v[160:163], v[184:187], v[62:65]
	s_waitcnt lgkmcnt(0)
	v_mfma_f32_16x16x32_bf16 v[66:69], v[148:151], v[180:183], v[212:215]
	v_mfma_f32_16x16x32_bf16 v[66:69], v[152:155], v[184:187], v[66:69]
	ds_read2_b64 v[216:219], v165 offset0:0 offset1:4
	ds_read2_b64 v[220:223], v166 offset0:0 offset1:4
	ds_read2_b64 v[224:227], v167 offset0:0 offset1:4
	ds_read2_b64 v[228:231], v168 offset0:0 offset1:4
	v_max3_f32 v169, v2, v3, v4
	v_max3_f32 v172, v5, v6, v7
	v_max3_f32 v169, v8, v9, v169
	v_max3_f32 v172, v10, v11, v172
	v_max3_f32 v169, v12, v13, v169
	v_max3_f32 v172, v14, v15, v172
	v_max3_f32 v169, v16, v17, v169
	v_max3_f32 v172, v18, v19, v172
	v_max3_f32 v169, v20, v21, v169
	v_max3_f32 v172, v22, v23, v172
	v_max3_f32 v169, v24, v25, v169
	v_max3_f32 v172, v26, v27, v172
	v_max3_f32 v169, v28, v29, v169
	v_max3_f32 v172, v30, v31, v172
	v_max3_f32 v169, v32, v33, v169
	v_max3_f32 v172, v34, v35, v172
	v_max3_f32 v169, v36, v37, v169
	v_max3_f32 v172, v38, v39, v172
	v_max3_f32 v169, v40, v41, v169
	v_max3_f32 v172, v42, v43, v172
	v_max3_f32 v169, v44, v45, v169
	v_max3_f32 v172, v46, v47, v172
	v_max3_f32 v169, v48, v49, v169
	v_max3_f32 v172, v50, v51, v172
	v_max3_f32 v169, v52, v53, v169
	v_max3_f32 v172, v54, v55, v172
	v_max3_f32 v169, v56, v57, v169
	v_max3_f32 v172, v58, v59, v172
	v_max3_f32 v169, v60, v61, v169
	v_max3_f32 v172, v62, v63, v172
	v_max3_f32 v169, v64, v65, v169
	v_max3_f32 v172, v66, v67, v172
	v_max3_f32 v169, v68, v69, v169
	v_max_f32_e32 v169, v169, v172
	v_mul_f32_e32 v169, 0x3e000000, v169
	s_waitcnt vmcnt(0)
	v_max_f32_e32 v169, v169, v146
	ds_bpermute_b32 v172, v1, v169
	s_waitcnt lgkmcnt(0)
	v_max_f32_e32 v169, v169, v172
	ds_bpermute_b32 v172, v114, v169
	s_waitcnt lgkmcnt(0)
	v_max_f32_e32 v169, v169, v172
	v_mul_f32_e32 v175, 0xbfb8aa3b, v169
	v_mov_b32_e32 v170, 0
	v_mov_b32_e32 v171, 0
	v_fma_f32 v2, v2, s46, v175
	v_fma_f32 v3, v3, s46, v175
	v_fma_f32 v4, v4, s46, v175
	v_fma_f32 v5, v5, s46, v175
	v_exp_f32_e32 v2, v2
	v_exp_f32_e32 v3, v3
	v_exp_f32_e32 v4, v4
	v_exp_f32_e32 v5, v5
	v_fma_f32 v6, v6, s46, v175
	v_fma_f32 v7, v7, s46, v175
	v_fma_f32 v8, v8, s46, v175
	v_fma_f32 v9, v9, s46, v175
	v_exp_f32_e32 v6, v6
	v_exp_f32_e32 v7, v7
	v_exp_f32_e32 v8, v8
	v_exp_f32_e32 v9, v9
	v_add_f32_e32 v171, v171, v2
	v_add_f32_e32 v170, v170, v3
	v_add_f32_e32 v171, v171, v4
	v_add_f32_e32 v170, v170, v5
	v_fma_f32 v10, v10, s46, v175
	v_fma_f32 v11, v11, s46, v175
	v_fma_f32 v12, v12, s46, v175
	v_fma_f32 v13, v13, s46, v175
	v_exp_f32_e32 v10, v10
	v_exp_f32_e32 v11, v11
	v_exp_f32_e32 v12, v12
	v_exp_f32_e32 v13, v13
	v_add_f32_e32 v171, v171, v6
	v_add_f32_e32 v170, v170, v7
	v_add_f32_e32 v171, v171, v8
	v_add_f32_e32 v170, v170, v9
	v_fma_f32 v14, v14, s46, v175
	v_fma_f32 v15, v15, s46, v175
	v_fma_f32 v16, v16, s46, v175
	v_fma_f32 v17, v17, s46, v175
	v_exp_f32_e32 v14, v14
	v_exp_f32_e32 v15, v15
	v_exp_f32_e32 v16, v16
	v_exp_f32_e32 v17, v17
	v_add_f32_e32 v171, v171, v10
	v_add_f32_e32 v170, v170, v11
	v_add_f32_e32 v171, v171, v12
	v_add_f32_e32 v170, v170, v13
	v_fma_f32 v18, v18, s46, v175
	v_fma_f32 v19, v19, s46, v175
	v_fma_f32 v20, v20, s46, v175
	v_fma_f32 v21, v21, s46, v175
	v_exp_f32_e32 v18, v18
	v_exp_f32_e32 v19, v19
	v_exp_f32_e32 v20, v20
	v_exp_f32_e32 v21, v21
	v_add_f32_e32 v171, v171, v14
	v_add_f32_e32 v170, v170, v15
	v_add_f32_e32 v171, v171, v16
	v_add_f32_e32 v170, v170, v17
	v_fma_f32 v22, v22, s46, v175
	v_fma_f32 v23, v23, s46, v175
	v_fma_f32 v24, v24, s46, v175
	v_fma_f32 v25, v25, s46, v175
	v_exp_f32_e32 v22, v22
	v_exp_f32_e32 v23, v23
	v_exp_f32_e32 v24, v24
	v_exp_f32_e32 v25, v25
	v_add_f32_e32 v171, v171, v18
	v_add_f32_e32 v170, v170, v19
	v_add_f32_e32 v171, v171, v20
	v_add_f32_e32 v170, v170, v21
; __device__ __forceinline__ unsigned cvt_pk_bf16_asm(float lo, float hi) { unsigned r; asm volatile("v_cvt_pk_bf16_f32 %0, %1, %2" : "=v"(r) : "v"(lo), "v"(hi)); return r; }
; __device__ __forceinline__ f32x4 mfma16(bf16x8 a, bf16x8 b, f32x4 c) { return __builtin_amdgcn_mfma_f32_16x16x32_bf16(a, b, c, 0, 0, 0); }
; __device__ void att_phase(int wv, const Params& p, unsigned char* lds) {
;     ...
;             for (int cb = 0; cb < 24; ++cb)
; #pragma unroll
;                 for (int j = 0; j < 4; ++j) { const float e = __expf(sc[cb][j] - mx); sc[cb][j] = e; sum += e; }
;             sum += __shfl_xor(sum, 16); sum += __shfl_xor(sum, 32);
;             sum += __expf(sink - mx);
;             const float inv = 1.0f / sum;
;             f32x4 oa[4];
; #pragma unroll
;             for (int db = 0; db < 4; ++db) oa[db] = (f32x4){0, 0, 0, 0};
; #pragma unroll
;             for (int ks = 0; ks < 12; ++ks) {
;                 union { bf16x8 v; unsigned u[4]; } pf;
;                 pf.u[0] = cvt_pk_bf16_asm(sc[2 * ks][0], sc[2 * ks][1]); pf.u[1] = cvt_pk_bf16_asm(sc[2 * ks][2], sc[2 * ks][3]);
;                 pf.u[2] = cvt_pk_bf16_asm(sc[2 * ks + 1][0], sc[2 * ks + 1][1]); pf.u[3] = cvt_pk_bf16_asm(sc[2 * ks + 1][2], sc[2 * ks + 1][3]);
; #pragma unroll
;                 for (int db = 0; db < 4; ++db) {
;                     union { bf16x8 v; u32x2 h2[2]; } vf;
;                     const bf16_t* vp = VTL + (16 * db + lr) * VP + 32 * ks + 4 * lq;
;                     vf.h2[0] = *(const u32x2*)vp; vf.h2[1] = *(const u32x2*)(vp + 16);
;                     oa[db] = mfma16(vf.v, pf.v, oa[db]); } }
	v_fma_f32 v26, v26, s46, v175
	v_fma_f32 v27, v27, s46, v175
	v_fma_f32 v28, v28, s46, v175
	v_fma_f32 v29, v29, s46, v175
	v_exp_f32_e32 v26, v26
	v_exp_f32_e32 v27, v27
	v_exp_f32_e32 v28, v28
	v_exp_f32_e32 v29, v29
	v_add_f32_e32 v171, v171, v22
	v_add_f32_e32 v170, v170, v23
	v_add_f32_e32 v171, v171, v24
	v_add_f32_e32 v170, v170, v25
	v_fma_f32 v30, v30, s46, v175
	v_fma_f32 v31, v31, s46, v175
	v_fma_f32 v32, v32, s46, v175
	v_fma_f32 v33, v33, s46, v175
	v_exp_f32_e32 v30, v30
	v_exp_f32_e32 v31, v31
	v_exp_f32_e32 v32, v32
	v_exp_f32_e32 v33, v33
	v_add_f32_e32 v171, v171, v26
	v_add_f32_e32 v170, v170, v27
	v_add_f32_e32 v171, v171, v28
	v_add_f32_e32 v170, v170, v29
	v_fma_f32 v34, v34, s46, v175
	v_fma_f32 v35, v35, s46, v175
	v_fma_f32 v36, v36, s46, v175
	v_fma_f32 v37, v37, s46, v175
	v_exp_f32_e32 v34, v34
	v_exp_f32_e32 v35, v35
	v_exp_f32_e32 v36, v36
	v_exp_f32_e32 v37, v37
	v_add_f32_e32 v171, v171, v30
	v_add_f32_e32 v170, v170, v31
	v_add_f32_e32 v171, v171, v32
	v_add_f32_e32 v170, v170, v33
	v_fma_f32 v38, v38, s46, v175
	v_fma_f32 v39, v39, s46, v175
	v_fma_f32 v40, v40, s46, v175
	v_fma_f32 v41, v41, s46, v175
	v_exp_f32_e32 v38, v38
	v_exp_f32_e32 v39, v39
	v_exp_f32_e32 v40, v40
	v_exp_f32_e32 v41, v41
	v_add_f32_e32 v171, v171, v34
	v_add_f32_e32 v170, v170, v35
	v_add_f32_e32 v171, v171, v36
	v_add_f32_e32 v170, v170, v37
	v_fma_f32 v42, v42, s46, v175
	v_fma_f32 v43, v43, s46, v175
	v_fma_f32 v44, v44, s46, v175
	v_fma_f32 v45, v45, s46, v175
	v_exp_f32_e32 v42, v42
	v_exp_f32_e32 v43, v43
	v_exp_f32_e32 v44, v44
	v_exp_f32_e32 v45, v45
	v_add_f32_e32 v171, v171, v38
	v_add_f32_e32 v170, v170, v39
	v_add_f32_e32 v171, v171, v40
	v_add_f32_e32 v170, v170, v41
	v_fma_f32 v46, v46, s46, v175
	v_fma_f32 v47, v47, s46, v175
	v_fma_f32 v48, v48, s46, v175
	v_fma_f32 v49, v49, s46, v175
	v_exp_f32_e32 v46, v46
	v_exp_f32_e32 v47, v47
	v_exp_f32_e32 v48, v48
	v_exp_f32_e32 v49, v49
	v_add_f32_e32 v171, v171, v42
	v_add_f32_e32 v170, v170, v43
	v_add_f32_e32 v171, v171, v44
	v_add_f32_e32 v170, v170, v45
	v_fma_f32 v50, v50, s46, v175
	v_fma_f32 v51, v51, s46, v175
	v_fma_f32 v52, v52, s46, v175
	v_fma_f32 v53, v53, s46, v175
	v_exp_f32_e32 v50, v50
	v_exp_f32_e32 v51, v51
	v_exp_f32_e32 v52, v52
	v_exp_f32_e32 v53, v53
	v_add_f32_e32 v171, v171, v46
	v_add_f32_e32 v170, v170, v47
	v_add_f32_e32 v171, v171, v48
	v_add_f32_e32 v170, v170, v49
	v_fma_f32 v54, v54, s46, v175
	v_fma_f32 v55, v55, s46, v175
	v_fma_f32 v56, v56, s46, v175
	v_fma_f32 v57, v57, s46, v175
	v_exp_f32_e32 v54, v54
	v_exp_f32_e32 v55, v55
	v_exp_f32_e32 v56, v56
	v_exp_f32_e32 v57, v57
	v_add_f32_e32 v171, v171, v50
	v_add_f32_e32 v170, v170, v51
	v_add_f32_e32 v171, v171, v52
	v_add_f32_e32 v170, v170, v53
	v_fma_f32 v58, v58, s46, v175
	v_fma_f32 v59, v59, s46, v175
	v_fma_f32 v60, v60, s46, v175
	v_fma_f32 v61, v61, s46, v175
	v_exp_f32_e32 v58, v58
	v_exp_f32_e32 v59, v59
	v_exp_f32_e32 v60, v60
	v_exp_f32_e32 v61, v61
	v_add_f32_e32 v171, v171, v54
	v_add_f32_e32 v170, v170, v55
	v_add_f32_e32 v171, v171, v56
	v_add_f32_e32 v170, v170, v57
	v_fma_f32 v62, v62, s46, v175
	v_fma_f32 v63, v63, s46, v175
	v_fma_f32 v64, v64, s46, v175
	v_fma_f32 v65, v65, s46, v175
	v_exp_f32_e32 v62, v62
	v_exp_f32_e32 v63, v63
	v_exp_f32_e32 v64, v64
	v_exp_f32_e32 v65, v65
	v_add_f32_e32 v171, v171, v58
	v_add_f32_e32 v170, v170, v59
	v_add_f32_e32 v171, v171, v60
	v_add_f32_e32 v170, v170, v61
	v_fma_f32 v66, v66, s46, v175
	v_fma_f32 v67, v67, s46, v175
	v_fma_f32 v68, v68, s46, v175
	v_fma_f32 v69, v69, s46, v175
	v_exp_f32_e32 v66, v66
	v_exp_f32_e32 v67, v67
	v_exp_f32_e32 v68, v68
	v_exp_f32_e32 v69, v69
	v_add_f32_e32 v171, v171, v62
	v_add_f32_e32 v170, v170, v63
	v_add_f32_e32 v171, v171, v64
	v_add_f32_e32 v170, v170, v65
	v_add_f32_e32 v171, v171, v66
	v_add_f32_e32 v170, v170, v67
	v_add_f32_e32 v171, v171, v68
	v_add_f32_e32 v170, v170, v69
	v_add_f32_e32 v170, v170, v171
	v_cvt_pk_bf16_f32 v2, v2, v3
	v_cvt_pk_bf16_f32 v3, v4, v5
	v_cvt_pk_bf16_f32 v4, v6, v7
	v_cvt_pk_bf16_f32 v5, v8, v9
	v_cvt_pk_bf16_f32 v10, v10, v11
	v_cvt_pk_bf16_f32 v11, v12, v13
	v_cvt_pk_bf16_f32 v12, v14, v15
	v_cvt_pk_bf16_f32 v13, v16, v17
	v_cvt_pk_bf16_f32 v18, v18, v19
	v_cvt_pk_bf16_f32 v19, v20, v21
	v_cvt_pk_bf16_f32 v20, v22, v23
	v_cvt_pk_bf16_f32 v21, v24, v25
	v_cvt_pk_bf16_f32 v26, v26, v27
	v_cvt_pk_bf16_f32 v27, v28, v29
	v_cvt_pk_bf16_f32 v28, v30, v31
	v_cvt_pk_bf16_f32 v29, v32, v33
	v_cvt_pk_bf16_f32 v34, v34, v35
	v_cvt_pk_bf16_f32 v35, v36, v37
	v_cvt_pk_bf16_f32 v36, v38, v39
	v_cvt_pk_bf16_f32 v37, v40, v41
	v_cvt_pk_bf16_f32 v42, v42, v43
	v_cvt_pk_bf16_f32 v43, v44, v45
	v_cvt_pk_bf16_f32 v44, v46, v47
	v_cvt_pk_bf16_f32 v45, v48, v49
	v_cvt_pk_bf16_f32 v50, v50, v51
	v_cvt_pk_bf16_f32 v51, v52, v53
	v_cvt_pk_bf16_f32 v52, v54, v55
	v_cvt_pk_bf16_f32 v53, v56, v57
	v_cvt_pk_bf16_f32 v58, v58, v59
	v_cvt_pk_bf16_f32 v59, v60, v61
	v_cvt_pk_bf16_f32 v60, v62, v63
	v_cvt_pk_bf16_f32 v61, v64, v65
	v_cvt_pk_bf16_f32 v66, v66, v67
	v_cvt_pk_bf16_f32 v67, v68, v69
	v_mov_b32_e32 v68, 0
	v_mov_b32_e32 v69, 0
	ds_bpermute_b32 v172, v1, v170
	v_sub_f32_e32 v173, v146, v169
	v_mul_f32_e32 v173, 0x3fb8aa3b, v173
	v_exp_f32_e32 v173, v173
	s_waitcnt lgkmcnt(0)
	v_add_f32_e32 v170, v170, v172
	ds_bpermute_b32 v172, v114, v170
	ds_read2_b64 v[232:235], v165 offset0:8 offset1:12
	ds_read2_b64 v[236:239], v166 offset0:8 offset1:12
	ds_read2_b64 v[240:243], v167 offset0:8 offset1:12
	ds_read2_b64 v[244:247], v168 offset0:8 offset1:12
	s_waitcnt lgkmcnt(4)
; __device__ __forceinline__ unsigned cvt_pk_bf16_asm(float lo, float hi) { unsigned r; asm volatile("v_cvt_pk_bf16_f32 %0, %1, %2" : "=v"(r) : "v"(lo), "v"(hi)); return r; }
; __device__ __forceinline__ f32x4 mfma16(bf16x8 a, bf16x8 b, f32x4 c) { return __builtin_amdgcn_mfma_f32_16x16x32_bf16(a, b, c, 0, 0, 0); }
; __device__ void att_phase(int wv, const Params& p, unsigned char* lds) {
;     ...
;             for (int cb = 0; cb < 24; ++cb) { f32x4 a = {0, 0, 0, 0};
; #pragma unroll
;                 for (int kk = 0; kk < 2; ++kk) { const bf16x8 kf = *(const bf16x8*)(KL + (16 * cb + lr) * KP + 32 * kk + 8 * lq); a = mfma16(kf, qf[kk], a); }
;     ...
;             f32x4 oa[4];
; #pragma unroll
;             for (int db = 0; db < 4; ++db) oa[db] = (f32x4){0, 0, 0, 0};
; #pragma unroll
;             for (int ks = 0; ks < 12; ++ks) {
;                 union { bf16x8 v; unsigned u[4]; } pf;
;                 pf.u[0] = cvt_pk_bf16_asm(sc[2 * ks][0], sc[2 * ks][1]); pf.u[1] = cvt_pk_bf16_asm(sc[2 * ks][2], sc[2 * ks][3]);
;                 pf.u[2] = cvt_pk_bf16_asm(sc[2 * ks + 1][0], sc[2 * ks + 1][1]); pf.u[3] = cvt_pk_bf16_asm(sc[2 * ks + 1][2], sc[2 * ks + 1][3]);
; #pragma unroll
;                 for (int db = 0; db < 4; ++db) {
;                     union { bf16x8 v; u32x2 h2[2]; } vf;
;                     const bf16_t* vp = VTL + (16 * db + lr) * VP + 32 * ks + 4 * lq;
;                     vf.h2[0] = *(const u32x2*)vp; vf.h2[1] = *(const u32x2*)(vp + 16);
;                     oa[db] = mfma16(vf.v, pf.v, oa[db]); } }
; #pragma unroll
;             for (int db = 0; db < 4; ++db) { const f32x4 o = oa[db] * inv; u32x2 wv; wv.x = cvt_pk_bf16_asm(o[0], o[1]); wv.y = cvt_pk_bf16_asm(o[2], o[3]);
;                 *(u32x2*)(qkv + tokq * 1536 + 64 * h + 16 * db + 4 * lq) = wv; }
	v_mfma_f32_16x16x32_bf16 v[70:73], v[216:219], v[2:5], 0
	v_mfma_f32_16x16x32_bf16 v[74:77], v[220:223], v[2:5], 0
	v_mfma_f32_16x16x32_bf16 v[78:81], v[224:227], v[2:5], 0
	v_mfma_f32_16x16x32_bf16 v[82:85], v[228:231], v[2:5], 0
	v_add_f32_e32 v170, v170, v172
	v_add_f32_e32 v170, v170, v173
	v_rcp_f32_e32 v147, v170
	s_nop 0
	v_fma_f32 v179, -v170, v147, 1.0
	v_fmac_f32_e32 v147, v179, v147
	ds_read2_b64 v[216:219], v165 offset0:16 offset1:20
	ds_read2_b64 v[220:223], v166 offset0:16 offset1:20
	ds_read2_b64 v[224:227], v167 offset0:16 offset1:20
	ds_read2_b64 v[228:231], v168 offset0:16 offset1:20
	s_waitcnt lgkmcnt(4)
	v_mfma_f32_16x16x32_bf16 v[70:73], v[232:235], v[10:13], v[70:73]
	v_mfma_f32_16x16x32_bf16 v[74:77], v[236:239], v[10:13], v[74:77]
	v_mfma_f32_16x16x32_bf16 v[78:81], v[240:243], v[10:13], v[78:81]
	v_mfma_f32_16x16x32_bf16 v[82:85], v[244:247], v[10:13], v[82:85]
	ds_read2_b64 v[232:235], v165 offset0:24 offset1:28
	ds_read2_b64 v[236:239], v166 offset0:24 offset1:28
	ds_read2_b64 v[240:243], v167 offset0:24 offset1:28
	ds_read2_b64 v[244:247], v168 offset0:24 offset1:28
	s_waitcnt lgkmcnt(4)
	v_mfma_f32_16x16x32_bf16 v[70:73], v[216:219], v[18:21], v[70:73]
	v_mfma_f32_16x16x32_bf16 v[74:77], v[220:223], v[18:21], v[74:77]
	v_mfma_f32_16x16x32_bf16 v[78:81], v[224:227], v[18:21], v[78:81]
	v_mfma_f32_16x16x32_bf16 v[82:85], v[228:231], v[18:21], v[82:85]
	ds_read2_b64 v[216:219], v165 offset0:32 offset1:36
	ds_read2_b64 v[220:223], v166 offset0:32 offset1:36
	ds_read2_b64 v[224:227], v167 offset0:32 offset1:36
	ds_read2_b64 v[228:231], v168 offset0:32 offset1:36
	s_waitcnt lgkmcnt(4)
	v_mfma_f32_16x16x32_bf16 v[70:73], v[232:235], v[26:29], v[70:73]
	v_mfma_f32_16x16x32_bf16 v[74:77], v[236:239], v[26:29], v[74:77]
	v_mfma_f32_16x16x32_bf16 v[78:81], v[240:243], v[26:29], v[78:81]
	v_mfma_f32_16x16x32_bf16 v[82:85], v[244:247], v[26:29], v[82:85]
	ds_read2_b64 v[232:235], v165 offset0:40 offset1:44
	ds_read2_b64 v[236:239], v166 offset0:40 offset1:44
	ds_read2_b64 v[240:243], v167 offset0:40 offset1:44
	ds_read2_b64 v[244:247], v168 offset0:40 offset1:44
	s_waitcnt lgkmcnt(4)
	v_mfma_f32_16x16x32_bf16 v[70:73], v[216:219], v[34:37], v[70:73]
	v_mfma_f32_16x16x32_bf16 v[74:77], v[220:223], v[34:37], v[74:77]
	v_mfma_f32_16x16x32_bf16 v[78:81], v[224:227], v[34:37], v[78:81]
	v_mfma_f32_16x16x32_bf16 v[82:85], v[228:231], v[34:37], v[82:85]
	ds_read2_b64 v[216:219], v165 offset0:48 offset1:52
	ds_read2_b64 v[220:223], v166 offset0:48 offset1:52
	ds_read2_b64 v[224:227], v167 offset0:48 offset1:52
	ds_read2_b64 v[228:231], v168 offset0:48 offset1:52
	s_waitcnt lgkmcnt(4)
	v_mfma_f32_16x16x32_bf16 v[70:73], v[232:235], v[42:45], v[70:73]
	v_mfma_f32_16x16x32_bf16 v[74:77], v[236:239], v[42:45], v[74:77]
	v_mfma_f32_16x16x32_bf16 v[78:81], v[240:243], v[42:45], v[78:81]
	v_mfma_f32_16x16x32_bf16 v[82:85], v[244:247], v[42:45], v[82:85]
	ds_read2_b64 v[232:235], v165 offset0:56 offset1:60
	ds_read2_b64 v[236:239], v166 offset0:56 offset1:60
	ds_read2_b64 v[240:243], v167 offset0:56 offset1:60
	ds_read2_b64 v[244:247], v168 offset0:56 offset1:60
	s_waitcnt lgkmcnt(4)
	v_mfma_f32_16x16x32_bf16 v[70:73], v[216:219], v[50:53], v[70:73]
	v_mfma_f32_16x16x32_bf16 v[74:77], v[220:223], v[50:53], v[74:77]
	v_mfma_f32_16x16x32_bf16 v[78:81], v[224:227], v[50:53], v[78:81]
	v_mfma_f32_16x16x32_bf16 v[82:85], v[228:231], v[50:53], v[82:85]
	ds_read2_b64 v[216:219], v165 offset0:64 offset1:64
	ds_read2_b64 v[220:223], v166 offset0:64 offset1:64
	ds_read2_b64 v[224:227], v167 offset0:64 offset1:64
	ds_read2_b64 v[228:231], v168 offset0:64 offset1:64
	s_waitcnt lgkmcnt(4)
	v_mfma_f32_16x16x32_bf16 v[70:73], v[232:235], v[58:61], v[70:73]
	v_mfma_f32_16x16x32_bf16 v[74:77], v[236:239], v[58:61], v[74:77]
	v_mfma_f32_16x16x32_bf16 v[78:81], v[240:243], v[58:61], v[78:81]
	v_mfma_f32_16x16x32_bf16 v[82:85], v[244:247], v[58:61], v[82:85]
	s_waitcnt lgkmcnt(0)
	v_mfma_f32_16x16x32_bf16 v[70:73], v[216:219], v[66:69], v[70:73]
	v_mfma_f32_16x16x32_bf16 v[74:77], v[220:223], v[66:69], v[74:77]
	v_mfma_f32_16x16x32_bf16 v[78:81], v[224:227], v[66:69], v[78:81]
	v_mfma_f32_16x16x32_bf16 v[82:85], v[228:231], v[66:69], v[82:85]
	s_nop 7
	s_nop 1
	v_mul_f32_e32 v70, v70, v147
	v_mul_f32_e32 v71, v71, v147
	v_mul_f32_e32 v72, v72, v147
	v_mul_f32_e32 v73, v73, v147
	v_mul_f32_e32 v74, v74, v147
	v_mul_f32_e32 v75, v75, v147
	v_mul_f32_e32 v76, v76, v147
	v_mul_f32_e32 v77, v77, v147
	v_mul_f32_e32 v78, v78, v147
	v_mul_f32_e32 v79, v79, v147
	v_mul_f32_e32 v80, v80, v147
	v_mul_f32_e32 v81, v81, v147
	v_mul_f32_e32 v82, v82, v147
	v_mul_f32_e32 v83, v83, v147
	v_mul_f32_e32 v84, v84, v147
	v_mul_f32_e32 v85, v85, v147
	v_cvt_pk_bf16_f32 v70, v70, v71
	v_cvt_pk_bf16_f32 v71, v72, v73
	v_cvt_pk_bf16_f32 v74, v74, v75
	v_cvt_pk_bf16_f32 v75, v76, v77
	v_cvt_pk_bf16_f32 v78, v78, v79
	v_cvt_pk_bf16_f32 v79, v80, v81
	v_cvt_pk_bf16_f32 v82, v82, v83
	v_cvt_pk_bf16_f32 v83, v84, v85
	global_store_dwordx2 v[248:249], v[70:71], off offset:-64
	global_store_dwordx2 v[248:249], v[74:75], off offset:-32
	global_store_dwordx2 v[248:249], v[78:79], off
	global_store_dwordx2 v[248:249], v[82:83], off offset:32
	v_lshl_add_u64 v[248:249], v[248:249], 0, s[48:49]
	v_sub_f32_e32 v86, v94, v176
	v_sub_f32_e32 v87, v95, v176
	v_sub_f32_e32 v88, v96, v176
	v_sub_f32_e32 v89, v97, v176
	v_cmp_ge_i32_e32 vcc, 0, v108
	s_nop 1
	v_cndmask_b32_e32 v212, v252, v86, vcc
	v_cmp_ge_i32_e32 vcc, 0, v110
	s_nop 1
	v_cndmask_b32_e32 v213, v252, v87, vcc
	v_cmp_ge_i32_e32 vcc, 0, v111
	s_nop 1
	v_cndmask_b32_e32 v214, v252, v88, vcc
	v_cmp_ge_i32_e32 vcc, 0, v177
	s_nop 1
	v_cndmask_b32_e32 v215, v252, v89, vcc
	ds_read_b128 v[148:151], v164 offset:2304
	ds_read_b128 v[152:155], v164 offset:2368
	ds_read_b128 v[156:159], v164 offset:4608
	ds_read_b128 v[160:163], v164 offset:4672
	v_add_f32_e32 v90, v86, v174
	v_add_f32_e32 v91, v87, v174
	v_add_f32_e32 v92, v88, v174
	v_add_f32_e32 v93, v89, v174
	s_waitcnt lgkmcnt(2)
; __device__ __forceinline__ f32x4 mfma16(bf16x8 a, bf16x8 b, f32x4 c) { return __builtin_amdgcn_mfma_f32_16x16x32_bf16(a, b, c, 0, 0, 0); }
; __device__ void att_phase(int wv, const Params& p, unsigned char* lds) {
;     ...
;             for (int cb = 0; cb < 24; ++cb) { f32x4 a = {0, 0, 0, 0};
; #pragma unroll
;                 for (int kk = 0; kk < 2; ++kk) { const bf16x8 kf = *(const bf16x8*)(KL + (16 * cb + lr) * KP + 32 * kk + 8 * lq); a = mfma16(kf, qf[kk], a); }
;                 sc[cb] = a; }
;             float mx = sink;
; #pragma unroll
;             for (int cb = 0; cb < 24; ++cb) { const int kb = B - 1 + (cb >> 3); const bool bval = (kb >= sb && kb < se);
; #pragma unroll
;                 for (int j = 0; j < 4; ++j) { const int krel = 16 * cb + 4 * lq + j - 128;
;                     int dist = qrow - krel; dist = dist < 0 ? -dist : dist;
;                     const float v = (bval && dist <= 128) ? sc[cb][j] * 0.125f - slope * (float)dist : -1e30f;
;                     sc[cb][j] = v; mx = fmaxf(mx, v); } }
	v_mfma_f32_16x16x32_bf16 v[2:5], v[148:151], v[188:191], v[212:215]
	v_mfma_f32_16x16x32_bf16 v[2:5], v[152:155], v[192:195], v[2:5]
	ds_read_b128 v[148:151], v164 offset:6912
	ds_read_b128 v[152:155], v164 offset:6976
	v_add_f32_e32 v86, v90, v174
	v_add_f32_e32 v87, v91, v174
	v_add_f32_e32 v88, v92, v174
	v_add_f32_e32 v89, v93, v174
	s_waitcnt lgkmcnt(2)
	v_mfma_f32_16x16x32_bf16 v[6:9], v[156:159], v[188:191], v[90:93]
	v_mfma_f32_16x16x32_bf16 v[6:9], v[160:163], v[192:195], v[6:9]
	ds_read_b128 v[156:159], v164 offset:9216
	ds_read_b128 v[160:163], v164 offset:9280
	v_add_f32_e32 v90, v86, v174
	v_add_f32_e32 v91, v87, v174
	v_add_f32_e32 v92, v88, v174
	v_add_f32_e32 v93, v89, v174
	s_waitcnt lgkmcnt(2)
	v_mfma_f32_16x16x32_bf16 v[10:13], v[148:151], v[188:191], v[86:89]
	v_mfma_f32_16x16x32_bf16 v[10:13], v[152:155], v[192:195], v[10:13]
	ds_read_b128 v[148:151], v164 offset:11520
	ds_read_b128 v[152:155], v164 offset:11584
	v_add_f32_e32 v86, v90, v174
	v_add_f32_e32 v87, v91, v174
	v_add_f32_e32 v88, v92, v174
	v_add_f32_e32 v89, v93, v174
	s_waitcnt lgkmcnt(2)
	v_mfma_f32_16x16x32_bf16 v[14:17], v[156:159], v[188:191], v[90:93]
	v_mfma_f32_16x16x32_bf16 v[14:17], v[160:163], v[192:195], v[14:17]
	ds_read_b128 v[156:159], v164 offset:13824
	ds_read_b128 v[160:163], v164 offset:13888
	v_add_f32_e32 v90, v86, v174
	v_add_f32_e32 v91, v87, v174
	v_add_f32_e32 v92, v88, v174
	v_add_f32_e32 v93, v89, v174
	s_waitcnt lgkmcnt(2)
	v_mfma_f32_16x16x32_bf16 v[18:21], v[148:151], v[188:191], v[86:89]
	v_mfma_f32_16x16x32_bf16 v[18:21], v[152:155], v[192:195], v[18:21]
	ds_read_b128 v[148:151], v164 offset:16128
	ds_read_b128 v[152:155], v164 offset:16192
	v_add_f32_e32 v86, v90, v174
	v_add_f32_e32 v87, v91, v174
	v_add_f32_e32 v88, v92, v174
	v_add_f32_e32 v89, v93, v174
	s_waitcnt lgkmcnt(2)
	v_mfma_f32_16x16x32_bf16 v[22:25], v[156:159], v[188:191], v[90:93]
	v_mfma_f32_16x16x32_bf16 v[22:25], v[160:163], v[192:195], v[22:25]
	ds_read_b128 v[156:159], v164 offset:18432
	ds_read_b128 v[160:163], v164 offset:18496
	v_add_f32_e32 v90, v86, v174
	v_add_f32_e32 v91, v87, v174
	v_add_f32_e32 v92, v88, v174
	v_add_f32_e32 v93, v89, v174
	s_waitcnt lgkmcnt(2)
	v_mfma_f32_16x16x32_bf16 v[26:29], v[148:151], v[188:191], v[86:89]
	v_mfma_f32_16x16x32_bf16 v[26:29], v[152:155], v[192:195], v[26:29]
	ds_read_b128 v[148:151], v164 offset:20736
	ds_read_b128 v[152:155], v164 offset:20800
	s_waitcnt lgkmcnt(2)
	v_mfma_f32_16x16x32_bf16 v[30:33], v[156:159], v[188:191], v[90:93]
	v_mfma_f32_16x16x32_bf16 v[30:33], v[160:163], v[192:195], v[30:33]
	ds_read_b128 v[156:159], v164 offset:23040
	ds_read_b128 v[160:163], v164 offset:23104
	v_sub_f32_e64 v86, -v94, v174
	v_sub_f32_e64 v87, -v95, v174
	v_sub_f32_e64 v88, -v96, v174
	v_sub_f32_e64 v89, -v97, v174
	s_waitcnt lgkmcnt(2)
	v_mfma_f32_16x16x32_bf16 v[34:37], v[148:151], v[188:191], v[98:101]
	v_mfma_f32_16x16x32_bf16 v[34:37], v[152:155], v[192:195], v[34:37]
	ds_read_b128 v[148:151], v164 offset:25344
	ds_read_b128 v[152:155], v164 offset:25408
	v_sub_f32_e32 v90, v86, v174
	v_sub_f32_e32 v91, v87, v174
	v_sub_f32_e32 v92, v88, v174
	v_sub_f32_e32 v93, v89, v174
	s_waitcnt lgkmcnt(2)
	v_mfma_f32_16x16x32_bf16 v[38:41], v[156:159], v[188:191], v[86:89]
	v_mfma_f32_16x16x32_bf16 v[38:41], v[160:163], v[192:195], v[38:41]
	ds_read_b128 v[156:159], v164 offset:27648
	ds_read_b128 v[160:163], v164 offset:27712
	v_sub_f32_e32 v86, v90, v174
	v_sub_f32_e32 v87, v91, v174
	v_sub_f32_e32 v88, v92, v174
	v_sub_f32_e32 v89, v93, v174
	s_waitcnt lgkmcnt(2)
	v_mfma_f32_16x16x32_bf16 v[42:45], v[148:151], v[188:191], v[90:93]
	v_mfma_f32_16x16x32_bf16 v[42:45], v[152:155], v[192:195], v[42:45]
	ds_read_b128 v[148:151], v164 offset:29952
	ds_read_b128 v[152:155], v164 offset:30016
	v_sub_f32_e32 v90, v86, v174
	v_sub_f32_e32 v91, v87, v174
	v_sub_f32_e32 v92, v88, v174
	v_sub_f32_e32 v93, v89, v174
	s_waitcnt lgkmcnt(2)
	v_mfma_f32_16x16x32_bf16 v[46:49], v[156:159], v[188:191], v[86:89]
	v_mfma_f32_16x16x32_bf16 v[46:49], v[160:163], v[192:195], v[46:49]
	ds_read_b128 v[156:159], v164 offset:32256
	ds_read_b128 v[160:163], v164 offset:32320
	v_sub_f32_e32 v86, v90, v174
	v_sub_f32_e32 v87, v91, v174
	v_sub_f32_e32 v88, v92, v174
	v_sub_f32_e32 v89, v93, v174
	s_waitcnt lgkmcnt(2)
	v_mfma_f32_16x16x32_bf16 v[50:53], v[148:151], v[188:191], v[90:93]
	v_mfma_f32_16x16x32_bf16 v[50:53], v[152:155], v[192:195], v[50:53]
	ds_read_b128 v[148:151], v164 offset:34560
	ds_read_b128 v[152:155], v164 offset:34624
	v_sub_f32_e32 v90, v86, v174
	v_sub_f32_e32 v91, v87, v174
	v_sub_f32_e32 v92, v88, v174
	v_sub_f32_e32 v93, v89, v174
	s_waitcnt lgkmcnt(2)
	v_mfma_f32_16x16x32_bf16 v[54:57], v[156:159], v[188:191], v[86:89]
	v_mfma_f32_16x16x32_bf16 v[54:57], v[160:163], v[192:195], v[54:57]
	ds_read_b128 v[156:159], v164 offset:36864
	ds_read_b128 v[160:163], v164 offset:36928
	v_sub_f32_e32 v86, v90, v174
	v_sub_f32_e32 v87, v91, v174
	v_sub_f32_e32 v88, v92, v174
	v_sub_f32_e32 v89, v93, v174
	s_waitcnt lgkmcnt(2)
	v_mfma_f32_16x16x32_bf16 v[58:61], v[148:151], v[188:191], v[90:93]
	v_mfma_f32_16x16x32_bf16 v[58:61], v[152:155], v[192:195], v[58:61]
	ds_read_b128 v[148:151], v164 offset:39168
	ds_read_b128 v[152:155], v164 offset:39232
	v_sub_f32_e32 v90, v86, v174
	v_sub_f32_e32 v91, v87, v174
	v_sub_f32_e32 v92, v88, v174
	v_sub_f32_e32 v93, v89, v174
	v_cmp_le_i32_e32 vcc, 0, v108
	s_nop 1
	v_cndmask_b32_e32 v212, v252, v90, vcc
	v_cmp_le_i32_e32 vcc, 0, v110
	s_nop 1
	v_cndmask_b32_e32 v213, v252, v91, vcc
	v_cmp_le_i32_e32 vcc, 0, v111
	s_nop 1
	v_cndmask_b32_e32 v214, v252, v92, vcc
	v_cmp_le_i32_e32 vcc, 0, v177
	s_nop 1
	v_cndmask_b32_e32 v215, v252, v93, vcc
	s_waitcnt lgkmcnt(2)
; __device__ __forceinline__ f32x4 mfma16(bf16x8 a, bf16x8 b, f32x4 c) { return __builtin_amdgcn_mfma_f32_16x16x32_bf16(a, b, c, 0, 0, 0); }
; __device__ void att_phase(int wv, const Params& p, unsigned char* lds) {
;     ...
;                 for (int kk = 0; kk < 2; ++kk) { const bf16x8 kf = *(const bf16x8*)(KL + (16 * cb + lr) * KP + 32 * kk + 8 * lq); a = mfma16(kf, qf[kk], a); }
;                 sc[cb] = a; }
;             float mx = sink;
; #pragma unroll
;             for (int cb = 0; cb < 24; ++cb) { const int kb = B - 1 + (cb >> 3); const bool bval = (kb >= sb && kb < se);
; #pragma unroll
;                 for (int j = 0; j < 4; ++j) { const int krel = 16 * cb + 4 * lq + j - 128;
;                     int dist = qrow - krel; dist = dist < 0 ? -dist : dist;
;                     const float v = (bval && dist <= 128) ? sc[cb][j] * 0.125f - slope * (float)dist : -1e30f;
;                     sc[cb][j] = v; mx = fmaxf(mx, v); } }
;             mx = fmaxf(mx, __shfl_xor(mx, 16)); mx = fmaxf(mx, __shfl_xor(mx, 32));
;             float sum = 0.f;
; #pragma unroll
;             for (int cb = 0; cb < 24; ++cb)
; #pragma unroll
;                 for (int j = 0; j < 4; ++j) { const float e = __expf(sc[cb][j] - mx); sc[cb][j] = e; sum += e; }
	v_mfma_f32_16x16x32_bf16 v[62:65], v[156:159], v[188:191], v[86:89]
	v_mfma_f32_16x16x32_bf16 v[62:65], v[160:163], v[192:195], v[62:65]
	s_waitcnt lgkmcnt(0)
	v_mfma_f32_16x16x32_bf16 v[66:69], v[148:151], v[188:191], v[212:215]
	v_mfma_f32_16x16x32_bf16 v[66:69], v[152:155], v[192:195], v[66:69]
	ds_read2_b64 v[216:219], v165 offset0:4 offset1:8
	ds_read2_b64 v[220:223], v166 offset0:4 offset1:8
	ds_read2_b64 v[224:227], v167 offset0:4 offset1:8
	ds_read2_b64 v[228:231], v168 offset0:4 offset1:8
	v_max3_f32 v169, v2, v3, v4
	v_max3_f32 v172, v5, v6, v7
	v_max3_f32 v169, v8, v9, v169
	v_max3_f32 v172, v10, v11, v172
	v_max3_f32 v169, v12, v13, v169
	v_max3_f32 v172, v14, v15, v172
	v_max3_f32 v169, v16, v17, v169
	v_max3_f32 v172, v18, v19, v172
	v_max3_f32 v169, v20, v21, v169
	v_max3_f32 v172, v22, v23, v172
	v_max3_f32 v169, v24, v25, v169
	v_max3_f32 v172, v26, v27, v172
	v_max3_f32 v169, v28, v29, v169
	v_max3_f32 v172, v30, v31, v172
	v_max3_f32 v169, v32, v33, v169
	v_max3_f32 v172, v34, v35, v172
	v_max3_f32 v169, v36, v37, v169
	v_max3_f32 v172, v38, v39, v172
	v_max3_f32 v169, v40, v41, v169
	v_max3_f32 v172, v42, v43, v172
	v_max3_f32 v169, v44, v45, v169
	v_max3_f32 v172, v46, v47, v172
	v_max3_f32 v169, v48, v49, v169
	v_max3_f32 v172, v50, v51, v172
	v_max3_f32 v169, v52, v53, v169
	v_max3_f32 v172, v54, v55, v172
	v_max3_f32 v169, v56, v57, v169
	v_max3_f32 v172, v58, v59, v172
	v_max3_f32 v169, v60, v61, v169
	v_max3_f32 v172, v62, v63, v172
	v_max3_f32 v169, v64, v65, v169
	v_max3_f32 v172, v66, v67, v172
	v_max3_f32 v169, v68, v69, v169
	v_max_f32_e32 v169, v169, v172
	v_mul_f32_e32 v169, 0x3e000000, v169
	v_max_f32_e32 v169, v169, v146
	ds_bpermute_b32 v172, v1, v169
	s_waitcnt lgkmcnt(0)
	v_max_f32_e32 v169, v169, v172
	ds_bpermute_b32 v172, v114, v169
	s_waitcnt lgkmcnt(0)
	v_max_f32_e32 v169, v169, v172
	v_mul_f32_e32 v175, 0xbfb8aa3b, v169
	v_mov_b32_e32 v170, 0
	v_mov_b32_e32 v171, 0
	v_fma_f32 v2, v2, s46, v175
	v_fma_f32 v3, v3, s46, v175
	v_fma_f32 v4, v4, s46, v175
	v_fma_f32 v5, v5, s46, v175
	v_exp_f32_e32 v2, v2
	v_exp_f32_e32 v3, v3
	v_exp_f32_e32 v4, v4
	v_exp_f32_e32 v5, v5
	v_fma_f32 v6, v6, s46, v175
	v_fma_f32 v7, v7, s46, v175
	v_fma_f32 v8, v8, s46, v175
	v_fma_f32 v9, v9, s46, v175
	v_exp_f32_e32 v6, v6
	v_exp_f32_e32 v7, v7
	v_exp_f32_e32 v8, v8
	v_exp_f32_e32 v9, v9
	v_add_f32_e32 v171, v171, v2
	v_add_f32_e32 v170, v170, v3
	v_add_f32_e32 v171, v171, v4
	v_add_f32_e32 v170, v170, v5
	v_fma_f32 v10, v10, s46, v175
	v_fma_f32 v11, v11, s46, v175
	v_fma_f32 v12, v12, s46, v175
	v_fma_f32 v13, v13, s46, v175
	v_exp_f32_e32 v10, v10
	v_exp_f32_e32 v11, v11
	v_exp_f32_e32 v12, v12
	v_exp_f32_e32 v13, v13
	v_add_f32_e32 v171, v171, v6
	v_add_f32_e32 v170, v170, v7
	v_add_f32_e32 v171, v171, v8
	v_add_f32_e32 v170, v170, v9
	v_fma_f32 v14, v14, s46, v175
	v_fma_f32 v15, v15, s46, v175
	v_fma_f32 v16, v16, s46, v175
	v_fma_f32 v17, v17, s46, v175
	v_exp_f32_e32 v14, v14
	v_exp_f32_e32 v15, v15
	v_exp_f32_e32 v16, v16
	v_exp_f32_e32 v17, v17
	v_add_f32_e32 v171, v171, v10
	v_add_f32_e32 v170, v170, v11
	v_add_f32_e32 v171, v171, v12
	v_add_f32_e32 v170, v170, v13
	v_fma_f32 v18, v18, s46, v175
	v_fma_f32 v19, v19, s46, v175
	v_fma_f32 v20, v20, s46, v175
	v_fma_f32 v21, v21, s46, v175
	v_exp_f32_e32 v18, v18
	v_exp_f32_e32 v19, v19
	v_exp_f32_e32 v20, v20
	v_exp_f32_e32 v21, v21
	v_add_f32_e32 v171, v171, v14
	v_add_f32_e32 v170, v170, v15
	v_add_f32_e32 v171, v171, v16
	v_add_f32_e32 v170, v170, v17
	v_fma_f32 v22, v22, s46, v175
	v_fma_f32 v23, v23, s46, v175
	v_fma_f32 v24, v24, s46, v175
	v_fma_f32 v25, v25, s46, v175
	v_exp_f32_e32 v22, v22
	v_exp_f32_e32 v23, v23
	v_exp_f32_e32 v24, v24
	v_exp_f32_e32 v25, v25
	v_add_f32_e32 v171, v171, v18
	v_add_f32_e32 v170, v170, v19
	v_add_f32_e32 v171, v171, v20
	v_add_f32_e32 v170, v170, v21
	v_fma_f32 v26, v26, s46, v175
	v_fma_f32 v27, v27, s46, v175
	v_fma_f32 v28, v28, s46, v175
	v_fma_f32 v29, v29, s46, v175
	v_exp_f32_e32 v26, v26
	v_exp_f32_e32 v27, v27
	v_exp_f32_e32 v28, v28
	v_exp_f32_e32 v29, v29
	v_add_f32_e32 v171, v171, v22
	v_add_f32_e32 v170, v170, v23
	v_add_f32_e32 v171, v171, v24
	v_add_f32_e32 v170, v170, v25
	v_fma_f32 v30, v30, s46, v175
	v_fma_f32 v31, v31, s46, v175
	v_fma_f32 v32, v32, s46, v175
	v_fma_f32 v33, v33, s46, v175
	v_exp_f32_e32 v30, v30
	v_exp_f32_e32 v31, v31
	v_exp_f32_e32 v32, v32
	v_exp_f32_e32 v33, v33
	v_add_f32_e32 v171, v171, v26
	v_add_f32_e32 v170, v170, v27
	v_add_f32_e32 v171, v171, v28
	v_add_f32_e32 v170, v170, v29
	v_fma_f32 v34, v34, s46, v175
	v_fma_f32 v35, v35, s46, v175
	v_fma_f32 v36, v36, s46, v175
	v_fma_f32 v37, v37, s46, v175
	v_exp_f32_e32 v34, v34
	v_exp_f32_e32 v35, v35
	v_exp_f32_e32 v36, v36
	v_exp_f32_e32 v37, v37
	v_add_f32_e32 v171, v171, v30
	v_add_f32_e32 v170, v170, v31
	v_add_f32_e32 v171, v171, v32
	v_add_f32_e32 v170, v170, v33
	v_fma_f32 v38, v38, s46, v175
	v_fma_f32 v39, v39, s46, v175
	v_fma_f32 v40, v40, s46, v175
	v_fma_f32 v41, v41, s46, v175
	v_exp_f32_e32 v38, v38
	v_exp_f32_e32 v39, v39
	v_exp_f32_e32 v40, v40
	v_exp_f32_e32 v41, v41
	v_add_f32_e32 v171, v171, v34
	v_add_f32_e32 v170, v170, v35
	v_add_f32_e32 v171, v171, v36
	v_add_f32_e32 v170, v170, v37
	v_fma_f32 v42, v42, s46, v175
	v_fma_f32 v43, v43, s46, v175
	v_fma_f32 v44, v44, s46, v175
	v_fma_f32 v45, v45, s46, v175
	v_exp_f32_e32 v42, v42
	v_exp_f32_e32 v43, v43
	v_exp_f32_e32 v44, v44
	v_exp_f32_e32 v45, v45
	v_add_f32_e32 v171, v171, v38
	v_add_f32_e32 v170, v170, v39
	v_add_f32_e32 v171, v171, v40
	v_add_f32_e32 v170, v170, v41
	v_fma_f32 v46, v46, s46, v175
	v_fma_f32 v47, v47, s46, v175
; __device__ __forceinline__ unsigned cvt_pk_bf16_asm(float lo, float hi) { unsigned r; asm volatile("v_cvt_pk_bf16_f32 %0, %1, %2" : "=v"(r) : "v"(lo), "v"(hi)); return r; }
; __device__ __forceinline__ f32x4 mfma16(bf16x8 a, bf16x8 b, f32x4 c) { return __builtin_amdgcn_mfma_f32_16x16x32_bf16(a, b, c, 0, 0, 0); }
; __device__ void att_phase(int wv, const Params& p, unsigned char* lds) {
;     ...
;             for (int cb = 0; cb < 24; ++cb)
; #pragma unroll
;                 for (int j = 0; j < 4; ++j) { const float e = __expf(sc[cb][j] - mx); sc[cb][j] = e; sum += e; }
;             sum += __shfl_xor(sum, 16); sum += __shfl_xor(sum, 32);
;             sum += __expf(sink - mx);
;             const float inv = 1.0f / sum;
;             f32x4 oa[4];
; #pragma unroll
;             for (int db = 0; db < 4; ++db) oa[db] = (f32x4){0, 0, 0, 0};
; #pragma unroll
;             for (int ks = 0; ks < 12; ++ks) {
;                 union { bf16x8 v; unsigned u[4]; } pf;
;                 pf.u[0] = cvt_pk_bf16_asm(sc[2 * ks][0], sc[2 * ks][1]); pf.u[1] = cvt_pk_bf16_asm(sc[2 * ks][2], sc[2 * ks][3]);
;                 pf.u[2] = cvt_pk_bf16_asm(sc[2 * ks + 1][0], sc[2 * ks + 1][1]); pf.u[3] = cvt_pk_bf16_asm(sc[2 * ks + 1][2], sc[2 * ks + 1][3]);
; #pragma unroll
;                 for (int db = 0; db < 4; ++db) {
;                     union { bf16x8 v; u32x2 h2[2]; } vf;
;                     const bf16_t* vp = VTL + (16 * db + lr) * VP + 32 * ks + 4 * lq;
;                     vf.h2[0] = *(const u32x2*)vp; vf.h2[1] = *(const u32x2*)(vp + 16);
;                     oa[db] = mfma16(vf.v, pf.v, oa[db]); } }
	v_fma_f32 v48, v48, s46, v175
	v_fma_f32 v49, v49, s46, v175
	v_exp_f32_e32 v46, v46
	v_exp_f32_e32 v47, v47
	v_exp_f32_e32 v48, v48
	v_exp_f32_e32 v49, v49
	v_add_f32_e32 v171, v171, v42
	v_add_f32_e32 v170, v170, v43
	v_add_f32_e32 v171, v171, v44
	v_add_f32_e32 v170, v170, v45
	v_fma_f32 v50, v50, s46, v175
	v_fma_f32 v51, v51, s46, v175
	v_fma_f32 v52, v52, s46, v175
	v_fma_f32 v53, v53, s46, v175
	v_exp_f32_e32 v50, v50
	v_exp_f32_e32 v51, v51
	v_exp_f32_e32 v52, v52
	v_exp_f32_e32 v53, v53
	v_add_f32_e32 v171, v171, v46
	v_add_f32_e32 v170, v170, v47
	v_add_f32_e32 v171, v171, v48
	v_add_f32_e32 v170, v170, v49
	v_fma_f32 v54, v54, s46, v175
	v_fma_f32 v55, v55, s46, v175
	v_fma_f32 v56, v56, s46, v175
	v_fma_f32 v57, v57, s46, v175
	v_exp_f32_e32 v54, v54
	v_exp_f32_e32 v55, v55
	v_exp_f32_e32 v56, v56
	v_exp_f32_e32 v57, v57
	v_add_f32_e32 v171, v171, v50
	v_add_f32_e32 v170, v170, v51
	v_add_f32_e32 v171, v171, v52
	v_add_f32_e32 v170, v170, v53
	v_fma_f32 v58, v58, s46, v175
	v_fma_f32 v59, v59, s46, v175
	v_fma_f32 v60, v60, s46, v175
	v_fma_f32 v61, v61, s46, v175
	v_exp_f32_e32 v58, v58
	v_exp_f32_e32 v59, v59
	v_exp_f32_e32 v60, v60
	v_exp_f32_e32 v61, v61
	v_add_f32_e32 v171, v171, v54
	v_add_f32_e32 v170, v170, v55
	v_add_f32_e32 v171, v171, v56
	v_add_f32_e32 v170, v170, v57
	v_fma_f32 v62, v62, s46, v175
	v_fma_f32 v63, v63, s46, v175
	v_fma_f32 v64, v64, s46, v175
	v_fma_f32 v65, v65, s46, v175
	v_exp_f32_e32 v62, v62
	v_exp_f32_e32 v63, v63
	v_exp_f32_e32 v64, v64
	v_exp_f32_e32 v65, v65
	v_add_f32_e32 v171, v171, v58
	v_add_f32_e32 v170, v170, v59
	v_add_f32_e32 v171, v171, v60
	v_add_f32_e32 v170, v170, v61
	v_fma_f32 v66, v66, s46, v175
	v_fma_f32 v67, v67, s46, v175
	v_fma_f32 v68, v68, s46, v175
	v_fma_f32 v69, v69, s46, v175
	v_exp_f32_e32 v66, v66
	v_exp_f32_e32 v67, v67
	v_exp_f32_e32 v68, v68
	v_exp_f32_e32 v69, v69
	v_add_f32_e32 v171, v171, v62
	v_add_f32_e32 v170, v170, v63
	v_add_f32_e32 v171, v171, v64
	v_add_f32_e32 v170, v170, v65
	v_add_f32_e32 v171, v171, v66
	v_add_f32_e32 v170, v170, v67
	v_add_f32_e32 v171, v171, v68
	v_add_f32_e32 v170, v170, v69
	v_add_f32_e32 v170, v170, v171
	v_cvt_pk_bf16_f32 v2, v2, v3
	v_cvt_pk_bf16_f32 v3, v4, v5
	v_cvt_pk_bf16_f32 v4, v6, v7
	v_cvt_pk_bf16_f32 v5, v8, v9
	v_cvt_pk_bf16_f32 v10, v10, v11
	v_cvt_pk_bf16_f32 v11, v12, v13
	v_cvt_pk_bf16_f32 v12, v14, v15
	v_cvt_pk_bf16_f32 v13, v16, v17
	v_cvt_pk_bf16_f32 v18, v18, v19
	v_cvt_pk_bf16_f32 v19, v20, v21
	v_cvt_pk_bf16_f32 v20, v22, v23
	v_cvt_pk_bf16_f32 v21, v24, v25
	v_cvt_pk_bf16_f32 v26, v26, v27
	v_cvt_pk_bf16_f32 v27, v28, v29
	v_cvt_pk_bf16_f32 v28, v30, v31
	v_cvt_pk_bf16_f32 v29, v32, v33
	v_cvt_pk_bf16_f32 v34, v34, v35
	v_cvt_pk_bf16_f32 v35, v36, v37
	v_cvt_pk_bf16_f32 v36, v38, v39
	v_cvt_pk_bf16_f32 v37, v40, v41
	v_cvt_pk_bf16_f32 v42, v42, v43
	v_cvt_pk_bf16_f32 v43, v44, v45
	v_cvt_pk_bf16_f32 v44, v46, v47
	v_cvt_pk_bf16_f32 v45, v48, v49
	v_cvt_pk_bf16_f32 v50, v50, v51
	v_cvt_pk_bf16_f32 v51, v52, v53
	v_cvt_pk_bf16_f32 v52, v54, v55
	v_cvt_pk_bf16_f32 v53, v56, v57
	v_cvt_pk_bf16_f32 v58, v58, v59
	v_cvt_pk_bf16_f32 v59, v60, v61
	v_cvt_pk_bf16_f32 v60, v62, v63
	v_cvt_pk_bf16_f32 v61, v64, v65
	v_cvt_pk_bf16_f32 v66, v66, v67
	v_cvt_pk_bf16_f32 v67, v68, v69
	v_mov_b32_e32 v68, 0
	v_mov_b32_e32 v69, 0
	ds_bpermute_b32 v172, v1, v170
	v_sub_f32_e32 v173, v146, v169
	v_mul_f32_e32 v173, 0x3fb8aa3b, v173
	v_exp_f32_e32 v173, v173
	s_waitcnt lgkmcnt(0)
	v_add_f32_e32 v170, v170, v172
	ds_bpermute_b32 v172, v114, v170
	ds_read2_b64 v[232:235], v165 offset0:12 offset1:16
	ds_read2_b64 v[236:239], v166 offset0:12 offset1:16
	ds_read2_b64 v[240:243], v167 offset0:12 offset1:16
	ds_read2_b64 v[244:247], v168 offset0:12 offset1:16
	s_waitcnt lgkmcnt(4)
	v_mfma_f32_16x16x32_bf16 v[70:73], v[216:219], v[2:5], 0
	v_mfma_f32_16x16x32_bf16 v[74:77], v[220:223], v[2:5], 0
	v_mfma_f32_16x16x32_bf16 v[78:81], v[224:227], v[2:5], 0
	v_mfma_f32_16x16x32_bf16 v[82:85], v[228:231], v[2:5], 0
	v_add_f32_e32 v170, v170, v172
	v_add_f32_e32 v170, v170, v173
	v_rcp_f32_e32 v147, v170
	s_nop 0
	v_fma_f32 v179, -v170, v147, 1.0
	v_fmac_f32_e32 v147, v179, v147
	ds_read2_b64 v[216:219], v165 offset0:20 offset1:24
	ds_read2_b64 v[220:223], v166 offset0:20 offset1:24
	ds_read2_b64 v[224:227], v167 offset0:20 offset1:24
	ds_read2_b64 v[228:231], v168 offset0:20 offset1:24
	s_waitcnt lgkmcnt(4)
	v_mfma_f32_16x16x32_bf16 v[70:73], v[232:235], v[10:13], v[70:73]
	v_mfma_f32_16x16x32_bf16 v[74:77], v[236:239], v[10:13], v[74:77]
	v_mfma_f32_16x16x32_bf16 v[78:81], v[240:243], v[10:13], v[78:81]
	v_mfma_f32_16x16x32_bf16 v[82:85], v[244:247], v[10:13], v[82:85]
	ds_read2_b64 v[232:235], v165 offset0:28 offset1:32
	ds_read2_b64 v[236:239], v166 offset0:28 offset1:32
	ds_read2_b64 v[240:243], v167 offset0:28 offset1:32
	ds_read2_b64 v[244:247], v168 offset0:28 offset1:32
	s_waitcnt lgkmcnt(4)
	v_mfma_f32_16x16x32_bf16 v[70:73], v[216:219], v[18:21], v[70:73]
	v_mfma_f32_16x16x32_bf16 v[74:77], v[220:223], v[18:21], v[74:77]
	v_mfma_f32_16x16x32_bf16 v[78:81], v[224:227], v[18:21], v[78:81]
	v_mfma_f32_16x16x32_bf16 v[82:85], v[228:231], v[18:21], v[82:85]
	ds_read2_b64 v[216:219], v165 offset0:36 offset1:40
	ds_read2_b64 v[220:223], v166 offset0:36 offset1:40
	ds_read2_b64 v[224:227], v167 offset0:36 offset1:40
	ds_read2_b64 v[228:231], v168 offset0:36 offset1:40
	s_waitcnt lgkmcnt(4)
; __device__ __forceinline__ unsigned cvt_pk_bf16_asm(float lo, float hi) { unsigned r; asm volatile("v_cvt_pk_bf16_f32 %0, %1, %2" : "=v"(r) : "v"(lo), "v"(hi)); return r; }
; __device__ __forceinline__ f32x4 mfma16(bf16x8 a, bf16x8 b, f32x4 c) { return __builtin_amdgcn_mfma_f32_16x16x32_bf16(a, b, c, 0, 0, 0); }
; __device__ void att_phase(int wv, const Params& p, unsigned char* lds) {
;     ...
;             for (int cb = 0; cb < 24; ++cb) { f32x4 a = {0, 0, 0, 0};
; #pragma unroll
;                 for (int kk = 0; kk < 2; ++kk) { const bf16x8 kf = *(const bf16x8*)(KL + (16 * cb + lr) * KP + 32 * kk + 8 * lq); a = mfma16(kf, qf[kk], a); }
;     ...
;             for (int ks = 0; ks < 12; ++ks) {
;                 union { bf16x8 v; unsigned u[4]; } pf;
;                 pf.u[0] = cvt_pk_bf16_asm(sc[2 * ks][0], sc[2 * ks][1]); pf.u[1] = cvt_pk_bf16_asm(sc[2 * ks][2], sc[2 * ks][3]);
;                 pf.u[2] = cvt_pk_bf16_asm(sc[2 * ks + 1][0], sc[2 * ks + 1][1]); pf.u[3] = cvt_pk_bf16_asm(sc[2 * ks + 1][2], sc[2 * ks + 1][3]);
; #pragma unroll
;                 for (int db = 0; db < 4; ++db) {
;                     union { bf16x8 v; u32x2 h2[2]; } vf;
;                     const bf16_t* vp = VTL + (16 * db + lr) * VP + 32 * ks + 4 * lq;
;                     vf.h2[0] = *(const u32x2*)vp; vf.h2[1] = *(const u32x2*)(vp + 16);
;                     oa[db] = mfma16(vf.v, pf.v, oa[db]); } }
; #pragma unroll
;             for (int db = 0; db < 4; ++db) { const f32x4 o = oa[db] * inv; u32x2 wv; wv.x = cvt_pk_bf16_asm(o[0], o[1]); wv.y = cvt_pk_bf16_asm(o[2], o[3]);
;                 *(u32x2*)(qkv + tokq * 1536 + 64 * h + 16 * db + 4 * lq) = wv; }
	v_mfma_f32_16x16x32_bf16 v[70:73], v[232:235], v[26:29], v[70:73]
	v_mfma_f32_16x16x32_bf16 v[74:77], v[236:239], v[26:29], v[74:77]
	v_mfma_f32_16x16x32_bf16 v[78:81], v[240:243], v[26:29], v[78:81]
	v_mfma_f32_16x16x32_bf16 v[82:85], v[244:247], v[26:29], v[82:85]
	ds_read2_b64 v[232:235], v165 offset0:44 offset1:48
	ds_read2_b64 v[236:239], v166 offset0:44 offset1:48
	ds_read2_b64 v[240:243], v167 offset0:44 offset1:48
	ds_read2_b64 v[244:247], v168 offset0:44 offset1:48
	s_waitcnt lgkmcnt(4)
	v_mfma_f32_16x16x32_bf16 v[70:73], v[216:219], v[34:37], v[70:73]
	v_mfma_f32_16x16x32_bf16 v[74:77], v[220:223], v[34:37], v[74:77]
	v_mfma_f32_16x16x32_bf16 v[78:81], v[224:227], v[34:37], v[78:81]
	v_mfma_f32_16x16x32_bf16 v[82:85], v[228:231], v[34:37], v[82:85]
	ds_read2_b64 v[216:219], v165 offset0:52 offset1:56
	ds_read2_b64 v[220:223], v166 offset0:52 offset1:56
	ds_read2_b64 v[224:227], v167 offset0:52 offset1:56
	ds_read2_b64 v[228:231], v168 offset0:52 offset1:56
	s_waitcnt lgkmcnt(4)
	v_mfma_f32_16x16x32_bf16 v[70:73], v[232:235], v[42:45], v[70:73]
	v_mfma_f32_16x16x32_bf16 v[74:77], v[236:239], v[42:45], v[74:77]
	v_mfma_f32_16x16x32_bf16 v[78:81], v[240:243], v[42:45], v[78:81]
	v_mfma_f32_16x16x32_bf16 v[82:85], v[244:247], v[42:45], v[82:85]
	ds_read2_b64 v[232:235], v165 offset0:60 offset1:64
	ds_read2_b64 v[236:239], v166 offset0:60 offset1:64
	ds_read2_b64 v[240:243], v167 offset0:60 offset1:64
	ds_read2_b64 v[244:247], v168 offset0:60 offset1:64
	s_waitcnt lgkmcnt(4)
	v_mfma_f32_16x16x32_bf16 v[70:73], v[216:219], v[50:53], v[70:73]
	v_mfma_f32_16x16x32_bf16 v[74:77], v[220:223], v[50:53], v[74:77]
	v_mfma_f32_16x16x32_bf16 v[78:81], v[224:227], v[50:53], v[78:81]
	v_mfma_f32_16x16x32_bf16 v[82:85], v[228:231], v[50:53], v[82:85]
	ds_read2_b64 v[216:219], v165 offset0:68 offset1:68
	ds_read2_b64 v[220:223], v166 offset0:68 offset1:68
	ds_read2_b64 v[224:227], v167 offset0:68 offset1:68
	ds_read2_b64 v[228:231], v168 offset0:68 offset1:68
	s_waitcnt lgkmcnt(4)
	v_mfma_f32_16x16x32_bf16 v[70:73], v[232:235], v[58:61], v[70:73]
	v_mfma_f32_16x16x32_bf16 v[74:77], v[236:239], v[58:61], v[74:77]
	v_mfma_f32_16x16x32_bf16 v[78:81], v[240:243], v[58:61], v[78:81]
	v_mfma_f32_16x16x32_bf16 v[82:85], v[244:247], v[58:61], v[82:85]
	s_waitcnt lgkmcnt(0)
	v_mfma_f32_16x16x32_bf16 v[70:73], v[216:219], v[66:69], v[70:73]
	v_mfma_f32_16x16x32_bf16 v[74:77], v[220:223], v[66:69], v[74:77]
	v_mfma_f32_16x16x32_bf16 v[78:81], v[224:227], v[66:69], v[78:81]
	v_mfma_f32_16x16x32_bf16 v[82:85], v[228:231], v[66:69], v[82:85]
	s_nop 7
	s_nop 1
	v_mul_f32_e32 v70, v70, v147
	v_mul_f32_e32 v71, v71, v147
	v_mul_f32_e32 v72, v72, v147
	v_mul_f32_e32 v73, v73, v147
	v_mul_f32_e32 v74, v74, v147
	v_mul_f32_e32 v75, v75, v147
	v_mul_f32_e32 v76, v76, v147
	v_mul_f32_e32 v77, v77, v147
	v_mul_f32_e32 v78, v78, v147
	v_mul_f32_e32 v79, v79, v147
	v_mul_f32_e32 v80, v80, v147
	v_mul_f32_e32 v81, v81, v147
	v_mul_f32_e32 v82, v82, v147
	v_mul_f32_e32 v83, v83, v147
	v_mul_f32_e32 v84, v84, v147
	v_mul_f32_e32 v85, v85, v147
	v_cvt_pk_bf16_f32 v70, v70, v71
	v_cvt_pk_bf16_f32 v71, v72, v73
	v_cvt_pk_bf16_f32 v74, v74, v75
	v_cvt_pk_bf16_f32 v75, v76, v77
	v_cvt_pk_bf16_f32 v78, v78, v79
	v_cvt_pk_bf16_f32 v79, v80, v81
	v_cvt_pk_bf16_f32 v82, v82, v83
	v_cvt_pk_bf16_f32 v83, v84, v85
	global_store_dwordx2 v[248:249], v[70:71], off offset:-64
	global_store_dwordx2 v[248:249], v[74:75], off offset:-32
	global_store_dwordx2 v[248:249], v[78:79], off
	global_store_dwordx2 v[248:249], v[82:83], off offset:32
	v_lshl_add_u64 v[248:249], v[248:249], 0, s[48:49]
	v_sub_f32_e32 v86, v94, v176
	v_sub_f32_e32 v87, v95, v176
	v_sub_f32_e32 v88, v96, v176
	v_sub_f32_e32 v89, v97, v176
	v_cmp_ge_i32_e32 vcc, 0, v108
	s_nop 1
	v_cndmask_b32_e32 v212, v252, v86, vcc
	v_cmp_ge_i32_e32 vcc, 0, v110
	s_nop 1
	v_cndmask_b32_e32 v213, v252, v87, vcc
	v_cmp_ge_i32_e32 vcc, 0, v111
	s_nop 1
	v_cndmask_b32_e32 v214, v252, v88, vcc
	v_cmp_ge_i32_e32 vcc, 0, v177
	s_nop 1
	v_cndmask_b32_e32 v215, v252, v89, vcc
	ds_read_b128 v[148:151], v164 offset:4608
	ds_read_b128 v[152:155], v164 offset:4672
	ds_read_b128 v[156:159], v164 offset:6912
	ds_read_b128 v[160:163], v164 offset:6976
	v_add_f32_e32 v90, v86, v174
	v_add_f32_e32 v91, v87, v174
	v_add_f32_e32 v92, v88, v174
	v_add_f32_e32 v93, v89, v174
	s_waitcnt lgkmcnt(2)
	v_mfma_f32_16x16x32_bf16 v[2:5], v[148:151], v[196:199], v[212:215]
	v_mfma_f32_16x16x32_bf16 v[2:5], v[152:155], v[200:203], v[2:5]
	ds_read_b128 v[148:151], v164 offset:9216
	ds_read_b128 v[152:155], v164 offset:9280
	v_add_f32_e32 v86, v90, v174
	v_add_f32_e32 v87, v91, v174
	v_add_f32_e32 v88, v92, v174
	v_add_f32_e32 v89, v93, v174
	s_waitcnt lgkmcnt(2)
	v_mfma_f32_16x16x32_bf16 v[6:9], v[156:159], v[196:199], v[90:93]
	v_mfma_f32_16x16x32_bf16 v[6:9], v[160:163], v[200:203], v[6:9]
	ds_read_b128 v[156:159], v164 offset:11520
	ds_read_b128 v[160:163], v164 offset:11584
	v_add_f32_e32 v90, v86, v174
	v_add_f32_e32 v91, v87, v174
	v_add_f32_e32 v92, v88, v174
	v_add_f32_e32 v93, v89, v174
	s_waitcnt lgkmcnt(2)
	v_mfma_f32_16x16x32_bf16 v[10:13], v[148:151], v[196:199], v[86:89]
	v_mfma_f32_16x16x32_bf16 v[10:13], v[152:155], v[200:203], v[10:13]
	ds_read_b128 v[148:151], v164 offset:13824
	ds_read_b128 v[152:155], v164 offset:13888
	v_add_f32_e32 v86, v90, v174
	v_add_f32_e32 v87, v91, v174
	v_add_f32_e32 v88, v92, v174
	v_add_f32_e32 v89, v93, v174
	s_waitcnt lgkmcnt(2)
	v_mfma_f32_16x16x32_bf16 v[14:17], v[156:159], v[196:199], v[90:93]
	v_mfma_f32_16x16x32_bf16 v[14:17], v[160:163], v[200:203], v[14:17]
	ds_read_b128 v[156:159], v164 offset:16128
	ds_read_b128 v[160:163], v164 offset:16192
	v_add_f32_e32 v90, v86, v174
	v_add_f32_e32 v91, v87, v174
	v_add_f32_e32 v92, v88, v174
	v_add_f32_e32 v93, v89, v174
	s_waitcnt lgkmcnt(2)
; __device__ __forceinline__ f32x4 mfma16(bf16x8 a, bf16x8 b, f32x4 c) { return __builtin_amdgcn_mfma_f32_16x16x32_bf16(a, b, c, 0, 0, 0); }
; __device__ void att_phase(int wv, const Params& p, unsigned char* lds) {
;     ...
;             for (int cb = 0; cb < 24; ++cb) { f32x4 a = {0, 0, 0, 0};
; #pragma unroll
;                 for (int kk = 0; kk < 2; ++kk) { const bf16x8 kf = *(const bf16x8*)(KL + (16 * cb + lr) * KP + 32 * kk + 8 * lq); a = mfma16(kf, qf[kk], a); }
;                 sc[cb] = a; }
;             float mx = sink;
; #pragma unroll
;             for (int cb = 0; cb < 24; ++cb) { const int kb = B - 1 + (cb >> 3); const bool bval = (kb >= sb && kb < se);
; #pragma unroll
;                 for (int j = 0; j < 4; ++j) { const int krel = 16 * cb + 4 * lq + j - 128;
;                     int dist = qrow - krel; dist = dist < 0 ? -dist : dist;
;                     const float v = (bval && dist <= 128) ? sc[cb][j] * 0.125f - slope * (float)dist : -1e30f;
;                     sc[cb][j] = v; mx = fmaxf(mx, v); } }
;             mx = fmaxf(mx, __shfl_xor(mx, 16)); mx = fmaxf(mx, __shfl_xor(mx, 32));
	v_mfma_f32_16x16x32_bf16 v[18:21], v[148:151], v[196:199], v[86:89]
	v_mfma_f32_16x16x32_bf16 v[18:21], v[152:155], v[200:203], v[18:21]
	ds_read_b128 v[148:151], v164 offset:18432
	ds_read_b128 v[152:155], v164 offset:18496
	v_add_f32_e32 v86, v90, v174
	v_add_f32_e32 v87, v91, v174
	v_add_f32_e32 v88, v92, v174
	v_add_f32_e32 v89, v93, v174
	s_waitcnt lgkmcnt(2)
	v_mfma_f32_16x16x32_bf16 v[22:25], v[156:159], v[196:199], v[90:93]
	v_mfma_f32_16x16x32_bf16 v[22:25], v[160:163], v[200:203], v[22:25]
	ds_read_b128 v[156:159], v164 offset:20736
	ds_read_b128 v[160:163], v164 offset:20800
	v_add_f32_e32 v90, v86, v174
	v_add_f32_e32 v91, v87, v174
	v_add_f32_e32 v92, v88, v174
	v_add_f32_e32 v93, v89, v174
	s_waitcnt lgkmcnt(2)
	v_mfma_f32_16x16x32_bf16 v[26:29], v[148:151], v[196:199], v[86:89]
	v_mfma_f32_16x16x32_bf16 v[26:29], v[152:155], v[200:203], v[26:29]
	ds_read_b128 v[148:151], v164 offset:23040
	ds_read_b128 v[152:155], v164 offset:23104
	s_waitcnt lgkmcnt(2)
	v_mfma_f32_16x16x32_bf16 v[30:33], v[156:159], v[196:199], v[90:93]
	v_mfma_f32_16x16x32_bf16 v[30:33], v[160:163], v[200:203], v[30:33]
	ds_read_b128 v[156:159], v164 offset:25344
	ds_read_b128 v[160:163], v164 offset:25408
	v_sub_f32_e64 v86, -v94, v174
	v_sub_f32_e64 v87, -v95, v174
	v_sub_f32_e64 v88, -v96, v174
	v_sub_f32_e64 v89, -v97, v174
	s_waitcnt lgkmcnt(2)
	v_mfma_f32_16x16x32_bf16 v[34:37], v[148:151], v[196:199], v[98:101]
	v_mfma_f32_16x16x32_bf16 v[34:37], v[152:155], v[200:203], v[34:37]
	ds_read_b128 v[148:151], v164 offset:27648
	ds_read_b128 v[152:155], v164 offset:27712
	v_sub_f32_e32 v90, v86, v174
	v_sub_f32_e32 v91, v87, v174
	v_sub_f32_e32 v92, v88, v174
	v_sub_f32_e32 v93, v89, v174
	s_waitcnt lgkmcnt(2)
	v_mfma_f32_16x16x32_bf16 v[38:41], v[156:159], v[196:199], v[86:89]
	v_mfma_f32_16x16x32_bf16 v[38:41], v[160:163], v[200:203], v[38:41]
	ds_read_b128 v[156:159], v164 offset:29952
	ds_read_b128 v[160:163], v164 offset:30016
	v_sub_f32_e32 v86, v90, v174
	v_sub_f32_e32 v87, v91, v174
	v_sub_f32_e32 v88, v92, v174
	v_sub_f32_e32 v89, v93, v174
	s_waitcnt lgkmcnt(2)
	v_mfma_f32_16x16x32_bf16 v[42:45], v[148:151], v[196:199], v[90:93]
	v_mfma_f32_16x16x32_bf16 v[42:45], v[152:155], v[200:203], v[42:45]
	ds_read_b128 v[148:151], v164 offset:32256
	ds_read_b128 v[152:155], v164 offset:32320
	v_sub_f32_e32 v90, v86, v174
	v_sub_f32_e32 v91, v87, v174
	v_sub_f32_e32 v92, v88, v174
	v_sub_f32_e32 v93, v89, v174
	s_waitcnt lgkmcnt(2)
	v_mfma_f32_16x16x32_bf16 v[46:49], v[156:159], v[196:199], v[86:89]
	v_mfma_f32_16x16x32_bf16 v[46:49], v[160:163], v[200:203], v[46:49]
	ds_read_b128 v[156:159], v164 offset:34560
	ds_read_b128 v[160:163], v164 offset:34624
	v_sub_f32_e32 v86, v90, v174
	v_sub_f32_e32 v87, v91, v174
	v_sub_f32_e32 v88, v92, v174
	v_sub_f32_e32 v89, v93, v174
	s_waitcnt lgkmcnt(2)
	v_mfma_f32_16x16x32_bf16 v[50:53], v[148:151], v[196:199], v[90:93]
	v_mfma_f32_16x16x32_bf16 v[50:53], v[152:155], v[200:203], v[50:53]
	ds_read_b128 v[148:151], v164 offset:36864
	ds_read_b128 v[152:155], v164 offset:36928
	v_sub_f32_e32 v90, v86, v174
	v_sub_f32_e32 v91, v87, v174
	v_sub_f32_e32 v92, v88, v174
	v_sub_f32_e32 v93, v89, v174
	s_waitcnt lgkmcnt(2)
	v_mfma_f32_16x16x32_bf16 v[54:57], v[156:159], v[196:199], v[86:89]
	v_mfma_f32_16x16x32_bf16 v[54:57], v[160:163], v[200:203], v[54:57]
	ds_read_b128 v[156:159], v164 offset:39168
	ds_read_b128 v[160:163], v164 offset:39232
	v_sub_f32_e32 v86, v90, v174
	v_sub_f32_e32 v87, v91, v174
	v_sub_f32_e32 v88, v92, v174
	v_sub_f32_e32 v89, v93, v174
	s_waitcnt lgkmcnt(2)
	v_mfma_f32_16x16x32_bf16 v[58:61], v[148:151], v[196:199], v[90:93]
	v_mfma_f32_16x16x32_bf16 v[58:61], v[152:155], v[200:203], v[58:61]
	ds_read_b128 v[148:151], v164 offset:41472
	ds_read_b128 v[152:155], v164 offset:41536
	v_sub_f32_e32 v90, v86, v174
	v_sub_f32_e32 v91, v87, v174
	v_sub_f32_e32 v92, v88, v174
	v_sub_f32_e32 v93, v89, v174
	v_cmp_le_i32_e32 vcc, 0, v108
	s_nop 1
	v_cndmask_b32_e32 v212, v252, v90, vcc
	v_cmp_le_i32_e32 vcc, 0, v110
	s_nop 1
	v_cndmask_b32_e32 v213, v252, v91, vcc
	v_cmp_le_i32_e32 vcc, 0, v111
	s_nop 1
	v_cndmask_b32_e32 v214, v252, v92, vcc
	v_cmp_le_i32_e32 vcc, 0, v177
	s_nop 1
	v_cndmask_b32_e32 v215, v252, v93, vcc
	s_waitcnt lgkmcnt(2)
	v_mfma_f32_16x16x32_bf16 v[62:65], v[156:159], v[196:199], v[86:89]
	v_mfma_f32_16x16x32_bf16 v[62:65], v[160:163], v[200:203], v[62:65]
	s_waitcnt lgkmcnt(0)
	v_mfma_f32_16x16x32_bf16 v[66:69], v[148:151], v[196:199], v[212:215]
	v_mfma_f32_16x16x32_bf16 v[66:69], v[152:155], v[200:203], v[66:69]
	ds_read2_b64 v[216:219], v165 offset0:8 offset1:12
	ds_read2_b64 v[220:223], v166 offset0:8 offset1:12
	ds_read2_b64 v[224:227], v167 offset0:8 offset1:12
	ds_read2_b64 v[228:231], v168 offset0:8 offset1:12
	v_max3_f32 v169, v2, v3, v4
	v_max3_f32 v172, v5, v6, v7
	v_max3_f32 v169, v8, v9, v169
	v_max3_f32 v172, v10, v11, v172
	v_max3_f32 v169, v12, v13, v169
	v_max3_f32 v172, v14, v15, v172
	v_max3_f32 v169, v16, v17, v169
	v_max3_f32 v172, v18, v19, v172
	v_max3_f32 v169, v20, v21, v169
	v_max3_f32 v172, v22, v23, v172
	v_max3_f32 v169, v24, v25, v169
	v_max3_f32 v172, v26, v27, v172
	v_max3_f32 v169, v28, v29, v169
	v_max3_f32 v172, v30, v31, v172
	v_max3_f32 v169, v32, v33, v169
	v_max3_f32 v172, v34, v35, v172
	v_max3_f32 v169, v36, v37, v169
	v_max3_f32 v172, v38, v39, v172
	v_max3_f32 v169, v40, v41, v169
	v_max3_f32 v172, v42, v43, v172
	v_max3_f32 v169, v44, v45, v169
	v_max3_f32 v172, v46, v47, v172
	v_max3_f32 v169, v48, v49, v169
	v_max3_f32 v172, v50, v51, v172
	v_max3_f32 v169, v52, v53, v169
	v_max3_f32 v172, v54, v55, v172
	v_max3_f32 v169, v56, v57, v169
	v_max3_f32 v172, v58, v59, v172
	v_max3_f32 v169, v60, v61, v169
	v_max3_f32 v172, v62, v63, v172
	v_max3_f32 v169, v64, v65, v169
	v_max3_f32 v172, v66, v67, v172
	v_max3_f32 v169, v68, v69, v169
	v_max_f32_e32 v169, v169, v172
	v_mul_f32_e32 v169, 0x3e000000, v169
	v_max_f32_e32 v169, v169, v146
	ds_bpermute_b32 v172, v1, v169
	s_waitcnt lgkmcnt(0)
; __device__ void att_phase(int wv, const Params& p, unsigned char* lds) {
;     ...
;             mx = fmaxf(mx, __shfl_xor(mx, 16)); mx = fmaxf(mx, __shfl_xor(mx, 32));
;             float sum = 0.f;
; #pragma unroll
;             for (int cb = 0; cb < 24; ++cb)
; #pragma unroll
;                 for (int j = 0; j < 4; ++j) { const float e = __expf(sc[cb][j] - mx); sc[cb][j] = e; sum += e; }
	v_max_f32_e32 v169, v169, v172
	ds_bpermute_b32 v172, v114, v169
	s_waitcnt lgkmcnt(0)
	v_max_f32_e32 v169, v169, v172
	v_mul_f32_e32 v175, 0xbfb8aa3b, v169
	v_mov_b32_e32 v170, 0
	v_mov_b32_e32 v171, 0
	v_fma_f32 v2, v2, s46, v175
	v_fma_f32 v3, v3, s46, v175
	v_fma_f32 v4, v4, s46, v175
	v_fma_f32 v5, v5, s46, v175
	v_exp_f32_e32 v2, v2
	v_exp_f32_e32 v3, v3
	v_exp_f32_e32 v4, v4
	v_exp_f32_e32 v5, v5
	v_fma_f32 v6, v6, s46, v175
	v_fma_f32 v7, v7, s46, v175
	v_fma_f32 v8, v8, s46, v175
	v_fma_f32 v9, v9, s46, v175
	v_exp_f32_e32 v6, v6
	v_exp_f32_e32 v7, v7
	v_exp_f32_e32 v8, v8
	v_exp_f32_e32 v9, v9
	v_add_f32_e32 v171, v171, v2
	v_add_f32_e32 v170, v170, v3
	v_add_f32_e32 v171, v171, v4
	v_add_f32_e32 v170, v170, v5
	v_fma_f32 v10, v10, s46, v175
	v_fma_f32 v11, v11, s46, v175
	v_fma_f32 v12, v12, s46, v175
	v_fma_f32 v13, v13, s46, v175
	v_exp_f32_e32 v10, v10
	v_exp_f32_e32 v11, v11
	v_exp_f32_e32 v12, v12
	v_exp_f32_e32 v13, v13
	v_add_f32_e32 v171, v171, v6
	v_add_f32_e32 v170, v170, v7
	v_add_f32_e32 v171, v171, v8
	v_add_f32_e32 v170, v170, v9
	v_fma_f32 v14, v14, s46, v175
	v_fma_f32 v15, v15, s46, v175
	v_fma_f32 v16, v16, s46, v175
	v_fma_f32 v17, v17, s46, v175
	v_exp_f32_e32 v14, v14
	v_exp_f32_e32 v15, v15
	v_exp_f32_e32 v16, v16
	v_exp_f32_e32 v17, v17
	v_add_f32_e32 v171, v171, v10
	v_add_f32_e32 v170, v170, v11
	v_add_f32_e32 v171, v171, v12
	v_add_f32_e32 v170, v170, v13
	v_fma_f32 v18, v18, s46, v175
	v_fma_f32 v19, v19, s46, v175
	v_fma_f32 v20, v20, s46, v175
	v_fma_f32 v21, v21, s46, v175
	v_exp_f32_e32 v18, v18
	v_exp_f32_e32 v19, v19
	v_exp_f32_e32 v20, v20
	v_exp_f32_e32 v21, v21
	v_add_f32_e32 v171, v171, v14
	v_add_f32_e32 v170, v170, v15
	v_add_f32_e32 v171, v171, v16
	v_add_f32_e32 v170, v170, v17
	v_fma_f32 v22, v22, s46, v175
	v_fma_f32 v23, v23, s46, v175
	v_fma_f32 v24, v24, s46, v175
	v_fma_f32 v25, v25, s46, v175
	v_exp_f32_e32 v22, v22
	v_exp_f32_e32 v23, v23
	v_exp_f32_e32 v24, v24
	v_exp_f32_e32 v25, v25
	v_add_f32_e32 v171, v171, v18
	v_add_f32_e32 v170, v170, v19
	v_add_f32_e32 v171, v171, v20
	v_add_f32_e32 v170, v170, v21
	v_fma_f32 v26, v26, s46, v175
	v_fma_f32 v27, v27, s46, v175
	v_fma_f32 v28, v28, s46, v175
	v_fma_f32 v29, v29, s46, v175
	v_exp_f32_e32 v26, v26
	v_exp_f32_e32 v27, v27
	v_exp_f32_e32 v28, v28
	v_exp_f32_e32 v29, v29
	v_add_f32_e32 v171, v171, v22
	v_add_f32_e32 v170, v170, v23
	v_add_f32_e32 v171, v171, v24
	v_add_f32_e32 v170, v170, v25
	v_fma_f32 v30, v30, s46, v175
	v_fma_f32 v31, v31, s46, v175
	v_fma_f32 v32, v32, s46, v175
	v_fma_f32 v33, v33, s46, v175
	v_exp_f32_e32 v30, v30
	v_exp_f32_e32 v31, v31
	v_exp_f32_e32 v32, v32
	v_exp_f32_e32 v33, v33
	v_add_f32_e32 v171, v171, v26
	v_add_f32_e32 v170, v170, v27
	v_add_f32_e32 v171, v171, v28
	v_add_f32_e32 v170, v170, v29
	v_fma_f32 v34, v34, s46, v175
	v_fma_f32 v35, v35, s46, v175
	v_fma_f32 v36, v36, s46, v175
	v_fma_f32 v37, v37, s46, v175
	v_exp_f32_e32 v34, v34
	v_exp_f32_e32 v35, v35
	v_exp_f32_e32 v36, v36
	v_exp_f32_e32 v37, v37
	v_add_f32_e32 v171, v171, v30
	v_add_f32_e32 v170, v170, v31
	v_add_f32_e32 v171, v171, v32
	v_add_f32_e32 v170, v170, v33
	v_fma_f32 v38, v38, s46, v175
	v_fma_f32 v39, v39, s46, v175
	v_fma_f32 v40, v40, s46, v175
	v_fma_f32 v41, v41, s46, v175
	v_exp_f32_e32 v38, v38
	v_exp_f32_e32 v39, v39
	v_exp_f32_e32 v40, v40
	v_exp_f32_e32 v41, v41
	v_add_f32_e32 v171, v171, v34
	v_add_f32_e32 v170, v170, v35
	v_add_f32_e32 v171, v171, v36
	v_add_f32_e32 v170, v170, v37
	v_fma_f32 v42, v42, s46, v175
	v_fma_f32 v43, v43, s46, v175
	v_fma_f32 v44, v44, s46, v175
	v_fma_f32 v45, v45, s46, v175
	v_exp_f32_e32 v42, v42
	v_exp_f32_e32 v43, v43
	v_exp_f32_e32 v44, v44
	v_exp_f32_e32 v45, v45
	v_add_f32_e32 v171, v171, v38
	v_add_f32_e32 v170, v170, v39
	v_add_f32_e32 v171, v171, v40
	v_add_f32_e32 v170, v170, v41
	v_fma_f32 v46, v46, s46, v175
	v_fma_f32 v47, v47, s46, v175
	v_fma_f32 v48, v48, s46, v175
	v_fma_f32 v49, v49, s46, v175
	v_exp_f32_e32 v46, v46
	v_exp_f32_e32 v47, v47
	v_exp_f32_e32 v48, v48
	v_exp_f32_e32 v49, v49
	v_add_f32_e32 v171, v171, v42
	v_add_f32_e32 v170, v170, v43
	v_add_f32_e32 v171, v171, v44
	v_add_f32_e32 v170, v170, v45
	v_fma_f32 v50, v50, s46, v175
	v_fma_f32 v51, v51, s46, v175
	v_fma_f32 v52, v52, s46, v175
	v_fma_f32 v53, v53, s46, v175
	v_exp_f32_e32 v50, v50
	v_exp_f32_e32 v51, v51
	v_exp_f32_e32 v52, v52
	v_exp_f32_e32 v53, v53
	v_add_f32_e32 v171, v171, v46
	v_add_f32_e32 v170, v170, v47
	v_add_f32_e32 v171, v171, v48
	v_add_f32_e32 v170, v170, v49
	v_fma_f32 v54, v54, s46, v175
	v_fma_f32 v55, v55, s46, v175
	v_fma_f32 v56, v56, s46, v175
	v_fma_f32 v57, v57, s46, v175
	v_exp_f32_e32 v54, v54
	v_exp_f32_e32 v55, v55
	v_exp_f32_e32 v56, v56
	v_exp_f32_e32 v57, v57
	v_add_f32_e32 v171, v171, v50
	v_add_f32_e32 v170, v170, v51
	v_add_f32_e32 v171, v171, v52
	v_add_f32_e32 v170, v170, v53
	v_fma_f32 v58, v58, s46, v175
	v_fma_f32 v59, v59, s46, v175
	v_fma_f32 v60, v60, s46, v175
	v_fma_f32 v61, v61, s46, v175
	v_exp_f32_e32 v58, v58
	v_exp_f32_e32 v59, v59
	v_exp_f32_e32 v60, v60
	v_exp_f32_e32 v61, v61
	v_add_f32_e32 v171, v171, v54
	v_add_f32_e32 v170, v170, v55
	v_add_f32_e32 v171, v171, v56
	v_add_f32_e32 v170, v170, v57
	v_fma_f32 v62, v62, s46, v175
	v_fma_f32 v63, v63, s46, v175
	v_fma_f32 v64, v64, s46, v175
	v_fma_f32 v65, v65, s46, v175
	v_exp_f32_e32 v62, v62
	v_exp_f32_e32 v63, v63
	v_exp_f32_e32 v64, v64
	v_exp_f32_e32 v65, v65
	v_add_f32_e32 v171, v171, v58
	v_add_f32_e32 v170, v170, v59
	v_add_f32_e32 v171, v171, v60
	v_add_f32_e32 v170, v170, v61
	v_fma_f32 v66, v66, s46, v175
	v_fma_f32 v67, v67, s46, v175
	v_fma_f32 v68, v68, s46, v175
; __device__ __forceinline__ unsigned cvt_pk_bf16_asm(float lo, float hi) { unsigned r; asm volatile("v_cvt_pk_bf16_f32 %0, %1, %2" : "=v"(r) : "v"(lo), "v"(hi)); return r; }
; __device__ __forceinline__ f32x4 mfma16(bf16x8 a, bf16x8 b, f32x4 c) { return __builtin_amdgcn_mfma_f32_16x16x32_bf16(a, b, c, 0, 0, 0); }
; __device__ void att_phase(int wv, const Params& p, unsigned char* lds) {
;     ...
;             float sum = 0.f;
; #pragma unroll
;             for (int cb = 0; cb < 24; ++cb)
; #pragma unroll
;                 for (int j = 0; j < 4; ++j) { const float e = __expf(sc[cb][j] - mx); sc[cb][j] = e; sum += e; }
;             sum += __shfl_xor(sum, 16); sum += __shfl_xor(sum, 32);
;             sum += __expf(sink - mx);
;             const float inv = 1.0f / sum;
;             f32x4 oa[4];
; #pragma unroll
;             for (int db = 0; db < 4; ++db) oa[db] = (f32x4){0, 0, 0, 0};
; #pragma unroll
;             for (int ks = 0; ks < 12; ++ks) {
;                 union { bf16x8 v; unsigned u[4]; } pf;
;                 pf.u[0] = cvt_pk_bf16_asm(sc[2 * ks][0], sc[2 * ks][1]); pf.u[1] = cvt_pk_bf16_asm(sc[2 * ks][2], sc[2 * ks][3]);
;                 pf.u[2] = cvt_pk_bf16_asm(sc[2 * ks + 1][0], sc[2 * ks + 1][1]); pf.u[3] = cvt_pk_bf16_asm(sc[2 * ks + 1][2], sc[2 * ks + 1][3]);
; #pragma unroll
;                 for (int db = 0; db < 4; ++db) {
;                     union { bf16x8 v; u32x2 h2[2]; } vf;
;                     const bf16_t* vp = VTL + (16 * db + lr) * VP + 32 * ks + 4 * lq;
;                     vf.h2[0] = *(const u32x2*)vp; vf.h2[1] = *(const u32x2*)(vp + 16);
;                     oa[db] = mfma16(vf.v, pf.v, oa[db]); } }
	v_fma_f32 v69, v69, s46, v175
	v_exp_f32_e32 v66, v66
	v_exp_f32_e32 v67, v67
	v_exp_f32_e32 v68, v68
	v_exp_f32_e32 v69, v69
	v_add_f32_e32 v171, v171, v62
	v_add_f32_e32 v170, v170, v63
	v_add_f32_e32 v171, v171, v64
	v_add_f32_e32 v170, v170, v65
	v_add_f32_e32 v171, v171, v66
	v_add_f32_e32 v170, v170, v67
	v_add_f32_e32 v171, v171, v68
	v_add_f32_e32 v170, v170, v69
	v_add_f32_e32 v170, v170, v171
	v_cvt_pk_bf16_f32 v2, v2, v3
	v_cvt_pk_bf16_f32 v3, v4, v5
	v_cvt_pk_bf16_f32 v4, v6, v7
	v_cvt_pk_bf16_f32 v5, v8, v9
	v_cvt_pk_bf16_f32 v10, v10, v11
	v_cvt_pk_bf16_f32 v11, v12, v13
	v_cvt_pk_bf16_f32 v12, v14, v15
	v_cvt_pk_bf16_f32 v13, v16, v17
	v_cvt_pk_bf16_f32 v18, v18, v19
	v_cvt_pk_bf16_f32 v19, v20, v21
	v_cvt_pk_bf16_f32 v20, v22, v23
	v_cvt_pk_bf16_f32 v21, v24, v25
	v_cvt_pk_bf16_f32 v26, v26, v27
	v_cvt_pk_bf16_f32 v27, v28, v29
	v_cvt_pk_bf16_f32 v28, v30, v31
	v_cvt_pk_bf16_f32 v29, v32, v33
	v_cvt_pk_bf16_f32 v34, v34, v35
	v_cvt_pk_bf16_f32 v35, v36, v37
	v_cvt_pk_bf16_f32 v36, v38, v39
	v_cvt_pk_bf16_f32 v37, v40, v41
	v_cvt_pk_bf16_f32 v42, v42, v43
	v_cvt_pk_bf16_f32 v43, v44, v45
	v_cvt_pk_bf16_f32 v44, v46, v47
	v_cvt_pk_bf16_f32 v45, v48, v49
	v_cvt_pk_bf16_f32 v50, v50, v51
	v_cvt_pk_bf16_f32 v51, v52, v53
	v_cvt_pk_bf16_f32 v52, v54, v55
	v_cvt_pk_bf16_f32 v53, v56, v57
	v_cvt_pk_bf16_f32 v58, v58, v59
	v_cvt_pk_bf16_f32 v59, v60, v61
	v_cvt_pk_bf16_f32 v60, v62, v63
	v_cvt_pk_bf16_f32 v61, v64, v65
	v_cvt_pk_bf16_f32 v66, v66, v67
	v_cvt_pk_bf16_f32 v67, v68, v69
	v_mov_b32_e32 v68, 0
	v_mov_b32_e32 v69, 0
	ds_bpermute_b32 v172, v1, v170
	v_sub_f32_e32 v173, v146, v169
	v_mul_f32_e32 v173, 0x3fb8aa3b, v173
	v_exp_f32_e32 v173, v173
	s_waitcnt lgkmcnt(0)
	v_add_f32_e32 v170, v170, v172
	ds_bpermute_b32 v172, v114, v170
	ds_read2_b64 v[232:235], v165 offset0:16 offset1:20
	ds_read2_b64 v[236:239], v166 offset0:16 offset1:20
	ds_read2_b64 v[240:243], v167 offset0:16 offset1:20
	ds_read2_b64 v[244:247], v168 offset0:16 offset1:20
	s_waitcnt lgkmcnt(4)
	v_mfma_f32_16x16x32_bf16 v[70:73], v[216:219], v[2:5], 0
	v_mfma_f32_16x16x32_bf16 v[74:77], v[220:223], v[2:5], 0
	v_mfma_f32_16x16x32_bf16 v[78:81], v[224:227], v[2:5], 0
	v_mfma_f32_16x16x32_bf16 v[82:85], v[228:231], v[2:5], 0
	v_add_f32_e32 v170, v170, v172
	v_add_f32_e32 v170, v170, v173
	v_rcp_f32_e32 v147, v170
	s_nop 0
	v_fma_f32 v179, -v170, v147, 1.0
	v_fmac_f32_e32 v147, v179, v147
	ds_read2_b64 v[216:219], v165 offset0:24 offset1:28
	ds_read2_b64 v[220:223], v166 offset0:24 offset1:28
	ds_read2_b64 v[224:227], v167 offset0:24 offset1:28
	ds_read2_b64 v[228:231], v168 offset0:24 offset1:28
	s_waitcnt lgkmcnt(4)
	v_mfma_f32_16x16x32_bf16 v[70:73], v[232:235], v[10:13], v[70:73]
	v_mfma_f32_16x16x32_bf16 v[74:77], v[236:239], v[10:13], v[74:77]
	v_mfma_f32_16x16x32_bf16 v[78:81], v[240:243], v[10:13], v[78:81]
	v_mfma_f32_16x16x32_bf16 v[82:85], v[244:247], v[10:13], v[82:85]
	ds_read2_b64 v[232:235], v165 offset0:32 offset1:36
	ds_read2_b64 v[236:239], v166 offset0:32 offset1:36
	ds_read2_b64 v[240:243], v167 offset0:32 offset1:36
	ds_read2_b64 v[244:247], v168 offset0:32 offset1:36
	s_waitcnt lgkmcnt(4)
	v_mfma_f32_16x16x32_bf16 v[70:73], v[216:219], v[18:21], v[70:73]
	v_mfma_f32_16x16x32_bf16 v[74:77], v[220:223], v[18:21], v[74:77]
	v_mfma_f32_16x16x32_bf16 v[78:81], v[224:227], v[18:21], v[78:81]
	v_mfma_f32_16x16x32_bf16 v[82:85], v[228:231], v[18:21], v[82:85]
	ds_read2_b64 v[216:219], v165 offset0:40 offset1:44
	ds_read2_b64 v[220:223], v166 offset0:40 offset1:44
	ds_read2_b64 v[224:227], v167 offset0:40 offset1:44
	ds_read2_b64 v[228:231], v168 offset0:40 offset1:44
	s_waitcnt lgkmcnt(4)
	v_mfma_f32_16x16x32_bf16 v[70:73], v[232:235], v[26:29], v[70:73]
	v_mfma_f32_16x16x32_bf16 v[74:77], v[236:239], v[26:29], v[74:77]
	v_mfma_f32_16x16x32_bf16 v[78:81], v[240:243], v[26:29], v[78:81]
	v_mfma_f32_16x16x32_bf16 v[82:85], v[244:247], v[26:29], v[82:85]
	ds_read2_b64 v[232:235], v165 offset0:48 offset1:52
	ds_read2_b64 v[236:239], v166 offset0:48 offset1:52
	ds_read2_b64 v[240:243], v167 offset0:48 offset1:52
	ds_read2_b64 v[244:247], v168 offset0:48 offset1:52
	s_waitcnt lgkmcnt(4)
	v_mfma_f32_16x16x32_bf16 v[70:73], v[216:219], v[34:37], v[70:73]
	v_mfma_f32_16x16x32_bf16 v[74:77], v[220:223], v[34:37], v[74:77]
	v_mfma_f32_16x16x32_bf16 v[78:81], v[224:227], v[34:37], v[78:81]
	v_mfma_f32_16x16x32_bf16 v[82:85], v[228:231], v[34:37], v[82:85]
	ds_read2_b64 v[216:219], v165 offset0:56 offset1:60
	ds_read2_b64 v[220:223], v166 offset0:56 offset1:60
	ds_read2_b64 v[224:227], v167 offset0:56 offset1:60
	ds_read2_b64 v[228:231], v168 offset0:56 offset1:60
	s_waitcnt lgkmcnt(4)
	v_mfma_f32_16x16x32_bf16 v[70:73], v[232:235], v[42:45], v[70:73]
	v_mfma_f32_16x16x32_bf16 v[74:77], v[236:239], v[42:45], v[74:77]
	v_mfma_f32_16x16x32_bf16 v[78:81], v[240:243], v[42:45], v[78:81]
	v_mfma_f32_16x16x32_bf16 v[82:85], v[244:247], v[42:45], v[82:85]
	ds_read2_b64 v[232:235], v165 offset0:64 offset1:68
	ds_read2_b64 v[236:239], v166 offset0:64 offset1:68
	ds_read2_b64 v[240:243], v167 offset0:64 offset1:68
	ds_read2_b64 v[244:247], v168 offset0:64 offset1:68
	s_waitcnt lgkmcnt(4)
	v_mfma_f32_16x16x32_bf16 v[70:73], v[216:219], v[50:53], v[70:73]
	v_mfma_f32_16x16x32_bf16 v[74:77], v[220:223], v[50:53], v[74:77]
	v_mfma_f32_16x16x32_bf16 v[78:81], v[224:227], v[50:53], v[78:81]
	v_mfma_f32_16x16x32_bf16 v[82:85], v[228:231], v[50:53], v[82:85]
	ds_read2_b64 v[216:219], v165 offset0:72 offset1:72
	ds_read2_b64 v[220:223], v166 offset0:72 offset1:72
	ds_read2_b64 v[224:227], v167 offset0:72 offset1:72
	ds_read2_b64 v[228:231], v168 offset0:72 offset1:72
	s_waitcnt lgkmcnt(4)
; __device__ void att_phase(int wv, const Params& p, unsigned char* lds) {
;     ...
;         for (int rb = 0; rb < 4; ++rb) {
;             const int qrow = 64 * (w & 1) + 16 * rb + lr;
;             const size_t tokq = (size_t)B * 128 + qrow;
;             bf16x8 qf[2];
; #pragma unroll
;             for (int kk = 0; kk < 2; ++kk) qf[kk] = *(const bf16x8*)(qkv + tokq * 1536 + 64 * h + 32 * kk + 8 * lq);
;             f32x4 sc[24];
; #pragma unroll
;             for (int cb = 0; cb < 24; ++cb) { f32x4 a = {0, 0, 0, 0};
; #pragma unroll
;                 for (int kk = 0; kk < 2; ++kk) { const bf16x8 kf = *(const bf16x8*)(KL + (16 * cb + lr) * KP + 32 * kk + 8 * lq); a = mfma16(kf, qf[kk], a); }
;                 sc[cb] = a; }
;             float mx = sink;
; #pragma unroll
;             for (int cb = 0; cb < 24; ++cb) { const int kb = B - 1 + (cb >> 3); const bool bval = (kb >= sb && kb < se);
; #pragma unroll
;                 for (int j = 0; j < 4; ++j) { const int krel = 16 * cb + 4 * lq + j - 128;
;                     int dist = qrow - krel; dist = dist < 0 ? -dist : dist;
;                     const float v = (bval && dist <= 128) ? sc[cb][j] * 0.125f - slope * (float)dist : -1e30f;
;                     sc[cb][j] = v; mx = fmaxf(mx, v); } }
;     ...
;             for (int ks = 0; ks < 12; ++ks) {
;                 union { bf16x8 v; unsigned u[4]; } pf;
;                 pf.u[0] = cvt_pk_bf16_asm(sc[2 * ks][0], sc[2 * ks][1]); pf.u[1] = cvt_pk_bf16_asm(sc[2 * ks][2], sc[2 * ks][3]);
;                 pf.u[2] = cvt_pk_bf16_asm(sc[2 * ks + 1][0], sc[2 * ks + 1][1]); pf.u[3] = cvt_pk_bf16_asm(sc[2 * ks + 1][2], sc[2 * ks + 1][3]);
; #pragma unroll
;                 for (int db = 0; db < 4; ++db) {
;                     union { bf16x8 v; u32x2 h2[2]; } vf;
;                     const bf16_t* vp = VTL + (16 * db + lr) * VP + 32 * ks + 4 * lq;
;                     vf.h2[0] = *(const u32x2*)vp; vf.h2[1] = *(const u32x2*)(vp + 16);
;                     oa[db] = mfma16(vf.v, pf.v, oa[db]); } }
; #pragma unroll
;             for (int db = 0; db < 4; ++db) { const f32x4 o = oa[db] * inv; u32x2 wv; wv.x = cvt_pk_bf16_asm(o[0], o[1]); wv.y = cvt_pk_bf16_asm(o[2], o[3]);
;                 *(u32x2*)(qkv + tokq * 1536 + 64 * h + 16 * db + 4 * lq) = wv; }
	v_mfma_f32_16x16x32_bf16 v[70:73], v[232:235], v[58:61], v[70:73]
	v_mfma_f32_16x16x32_bf16 v[74:77], v[236:239], v[58:61], v[74:77]
	v_mfma_f32_16x16x32_bf16 v[78:81], v[240:243], v[58:61], v[78:81]
	v_mfma_f32_16x16x32_bf16 v[82:85], v[244:247], v[58:61], v[82:85]
	s_waitcnt lgkmcnt(0)
	v_mfma_f32_16x16x32_bf16 v[70:73], v[216:219], v[66:69], v[70:73]
	v_mfma_f32_16x16x32_bf16 v[74:77], v[220:223], v[66:69], v[74:77]
	v_mfma_f32_16x16x32_bf16 v[78:81], v[224:227], v[66:69], v[78:81]
	v_mfma_f32_16x16x32_bf16 v[82:85], v[228:231], v[66:69], v[82:85]
	s_nop 7
	s_nop 1
	v_mul_f32_e32 v70, v70, v147
	v_mul_f32_e32 v71, v71, v147
	v_mul_f32_e32 v72, v72, v147
	v_mul_f32_e32 v73, v73, v147
	v_mul_f32_e32 v74, v74, v147
	v_mul_f32_e32 v75, v75, v147
	v_mul_f32_e32 v76, v76, v147
	v_mul_f32_e32 v77, v77, v147
	v_mul_f32_e32 v78, v78, v147
	v_mul_f32_e32 v79, v79, v147
	v_mul_f32_e32 v80, v80, v147
	v_mul_f32_e32 v81, v81, v147
	v_mul_f32_e32 v82, v82, v147
	v_mul_f32_e32 v83, v83, v147
	v_mul_f32_e32 v84, v84, v147
	v_mul_f32_e32 v85, v85, v147
	v_cvt_pk_bf16_f32 v70, v70, v71
	v_cvt_pk_bf16_f32 v71, v72, v73
	v_cvt_pk_bf16_f32 v74, v74, v75
	v_cvt_pk_bf16_f32 v75, v76, v77
	v_cvt_pk_bf16_f32 v78, v78, v79
	v_cvt_pk_bf16_f32 v79, v80, v81
	v_cvt_pk_bf16_f32 v82, v82, v83
	v_cvt_pk_bf16_f32 v83, v84, v85
	global_store_dwordx2 v[248:249], v[70:71], off offset:-64
	global_store_dwordx2 v[248:249], v[74:75], off offset:-32
	global_store_dwordx2 v[248:249], v[78:79], off
	global_store_dwordx2 v[248:249], v[82:83], off offset:32
	v_lshl_add_u64 v[248:249], v[248:249], 0, s[48:49]
	v_sub_f32_e32 v86, v94, v176
	v_sub_f32_e32 v87, v95, v176
	v_sub_f32_e32 v88, v96, v176
	v_sub_f32_e32 v89, v97, v176
	v_cmp_ge_i32_e32 vcc, 0, v108
	s_nop 1
	v_cndmask_b32_e32 v212, v252, v86, vcc
	v_cmp_ge_i32_e32 vcc, 0, v110
	s_nop 1
	v_cndmask_b32_e32 v213, v252, v87, vcc
	v_cmp_ge_i32_e32 vcc, 0, v111
	s_nop 1
	v_cndmask_b32_e32 v214, v252, v88, vcc
	v_cmp_ge_i32_e32 vcc, 0, v177
	s_nop 1
	v_cndmask_b32_e32 v215, v252, v89, vcc
	ds_read_b128 v[148:151], v164 offset:6912
	ds_read_b128 v[152:155], v164 offset:6976
	ds_read_b128 v[156:159], v164 offset:9216
	ds_read_b128 v[160:163], v164 offset:9280
	v_add_f32_e32 v90, v86, v174
	v_add_f32_e32 v91, v87, v174
	v_add_f32_e32 v92, v88, v174
	v_add_f32_e32 v93, v89, v174
	s_waitcnt lgkmcnt(2)
	v_mfma_f32_16x16x32_bf16 v[2:5], v[148:151], v[204:207], v[212:215]
	v_mfma_f32_16x16x32_bf16 v[2:5], v[152:155], v[208:211], v[2:5]
	ds_read_b128 v[148:151], v164 offset:11520
	ds_read_b128 v[152:155], v164 offset:11584
	v_add_f32_e32 v86, v90, v174
	v_add_f32_e32 v87, v91, v174
	v_add_f32_e32 v88, v92, v174
	v_add_f32_e32 v89, v93, v174
	s_waitcnt lgkmcnt(2)
	v_mfma_f32_16x16x32_bf16 v[6:9], v[156:159], v[204:207], v[90:93]
	v_mfma_f32_16x16x32_bf16 v[6:9], v[160:163], v[208:211], v[6:9]
	ds_read_b128 v[156:159], v164 offset:13824
	ds_read_b128 v[160:163], v164 offset:13888
	v_add_f32_e32 v90, v86, v174
	v_add_f32_e32 v91, v87, v174
	v_add_f32_e32 v92, v88, v174
	v_add_f32_e32 v93, v89, v174
	s_waitcnt lgkmcnt(2)
	v_mfma_f32_16x16x32_bf16 v[10:13], v[148:151], v[204:207], v[86:89]
	v_mfma_f32_16x16x32_bf16 v[10:13], v[152:155], v[208:211], v[10:13]
	ds_read_b128 v[148:151], v164 offset:16128
	ds_read_b128 v[152:155], v164 offset:16192
	v_add_f32_e32 v86, v90, v174
	v_add_f32_e32 v87, v91, v174
	v_add_f32_e32 v88, v92, v174
	v_add_f32_e32 v89, v93, v174
	s_waitcnt lgkmcnt(2)
	v_mfma_f32_16x16x32_bf16 v[14:17], v[156:159], v[204:207], v[90:93]
	v_mfma_f32_16x16x32_bf16 v[14:17], v[160:163], v[208:211], v[14:17]
	ds_read_b128 v[156:159], v164 offset:18432
	ds_read_b128 v[160:163], v164 offset:18496
	v_add_f32_e32 v90, v86, v174
	v_add_f32_e32 v91, v87, v174
	v_add_f32_e32 v92, v88, v174
	v_add_f32_e32 v93, v89, v174
	s_waitcnt lgkmcnt(2)
	v_mfma_f32_16x16x32_bf16 v[18:21], v[148:151], v[204:207], v[86:89]
	v_mfma_f32_16x16x32_bf16 v[18:21], v[152:155], v[208:211], v[18:21]
	ds_read_b128 v[148:151], v164 offset:20736
	ds_read_b128 v[152:155], v164 offset:20800
	v_add_f32_e32 v86, v90, v174
	v_add_f32_e32 v87, v91, v174
	v_add_f32_e32 v88, v92, v174
	v_add_f32_e32 v89, v93, v174
	s_waitcnt lgkmcnt(2)
	v_mfma_f32_16x16x32_bf16 v[22:25], v[156:159], v[204:207], v[90:93]
	v_mfma_f32_16x16x32_bf16 v[22:25], v[160:163], v[208:211], v[22:25]
	ds_read_b128 v[156:159], v164 offset:23040
	ds_read_b128 v[160:163], v164 offset:23104
	v_add_f32_e32 v90, v86, v174
	v_add_f32_e32 v91, v87, v174
	v_add_f32_e32 v92, v88, v174
	v_add_f32_e32 v93, v89, v174
	s_waitcnt lgkmcnt(2)
	v_mfma_f32_16x16x32_bf16 v[26:29], v[148:151], v[204:207], v[86:89]
	v_mfma_f32_16x16x32_bf16 v[26:29], v[152:155], v[208:211], v[26:29]
	ds_read_b128 v[148:151], v164 offset:25344
	ds_read_b128 v[152:155], v164 offset:25408
	s_waitcnt lgkmcnt(2)
	v_mfma_f32_16x16x32_bf16 v[30:33], v[156:159], v[204:207], v[90:93]
	v_mfma_f32_16x16x32_bf16 v[30:33], v[160:163], v[208:211], v[30:33]
	ds_read_b128 v[156:159], v164 offset:27648
	ds_read_b128 v[160:163], v164 offset:27712
	v_sub_f32_e64 v86, -v94, v174
	v_sub_f32_e64 v87, -v95, v174
	v_sub_f32_e64 v88, -v96, v174
	v_sub_f32_e64 v89, -v97, v174
	s_waitcnt lgkmcnt(2)
	v_mfma_f32_16x16x32_bf16 v[34:37], v[148:151], v[204:207], v[98:101]
	v_mfma_f32_16x16x32_bf16 v[34:37], v[152:155], v[208:211], v[34:37]
	ds_read_b128 v[148:151], v164 offset:29952
	ds_read_b128 v[152:155], v164 offset:30016
	v_sub_f32_e32 v90, v86, v174
	v_sub_f32_e32 v91, v87, v174
	v_sub_f32_e32 v92, v88, v174
	v_sub_f32_e32 v93, v89, v174
	s_waitcnt lgkmcnt(2)
; __device__ __forceinline__ f32x4 mfma16(bf16x8 a, bf16x8 b, f32x4 c) { return __builtin_amdgcn_mfma_f32_16x16x32_bf16(a, b, c, 0, 0, 0); }
; __device__ void att_phase(int wv, const Params& p, unsigned char* lds) {
;     ...
;             for (int cb = 0; cb < 24; ++cb) { f32x4 a = {0, 0, 0, 0};
; #pragma unroll
;                 for (int kk = 0; kk < 2; ++kk) { const bf16x8 kf = *(const bf16x8*)(KL + (16 * cb + lr) * KP + 32 * kk + 8 * lq); a = mfma16(kf, qf[kk], a); }
;                 sc[cb] = a; }
;             float mx = sink;
; #pragma unroll
;             for (int cb = 0; cb < 24; ++cb) { const int kb = B - 1 + (cb >> 3); const bool bval = (kb >= sb && kb < se);
; #pragma unroll
;                 for (int j = 0; j < 4; ++j) { const int krel = 16 * cb + 4 * lq + j - 128;
;                     int dist = qrow - krel; dist = dist < 0 ? -dist : dist;
;                     const float v = (bval && dist <= 128) ? sc[cb][j] * 0.125f - slope * (float)dist : -1e30f;
;                     sc[cb][j] = v; mx = fmaxf(mx, v); } }
;             mx = fmaxf(mx, __shfl_xor(mx, 16)); mx = fmaxf(mx, __shfl_xor(mx, 32));
	v_mfma_f32_16x16x32_bf16 v[38:41], v[156:159], v[204:207], v[86:89]
	v_mfma_f32_16x16x32_bf16 v[38:41], v[160:163], v[208:211], v[38:41]
	ds_read_b128 v[156:159], v164 offset:32256
	ds_read_b128 v[160:163], v164 offset:32320
	v_sub_f32_e32 v86, v90, v174
	v_sub_f32_e32 v87, v91, v174
	v_sub_f32_e32 v88, v92, v174
	v_sub_f32_e32 v89, v93, v174
	s_waitcnt lgkmcnt(2)
	v_mfma_f32_16x16x32_bf16 v[42:45], v[148:151], v[204:207], v[90:93]
	v_mfma_f32_16x16x32_bf16 v[42:45], v[152:155], v[208:211], v[42:45]
	ds_read_b128 v[148:151], v164 offset:34560
	ds_read_b128 v[152:155], v164 offset:34624
	v_sub_f32_e32 v90, v86, v174
	v_sub_f32_e32 v91, v87, v174
	v_sub_f32_e32 v92, v88, v174
	v_sub_f32_e32 v93, v89, v174
	s_waitcnt lgkmcnt(2)
	v_mfma_f32_16x16x32_bf16 v[46:49], v[156:159], v[204:207], v[86:89]
	v_mfma_f32_16x16x32_bf16 v[46:49], v[160:163], v[208:211], v[46:49]
	ds_read_b128 v[156:159], v164 offset:36864
	ds_read_b128 v[160:163], v164 offset:36928
	v_sub_f32_e32 v86, v90, v174
	v_sub_f32_e32 v87, v91, v174
	v_sub_f32_e32 v88, v92, v174
	v_sub_f32_e32 v89, v93, v174
	s_waitcnt lgkmcnt(2)
	v_mfma_f32_16x16x32_bf16 v[50:53], v[148:151], v[204:207], v[90:93]
	v_mfma_f32_16x16x32_bf16 v[50:53], v[152:155], v[208:211], v[50:53]
	ds_read_b128 v[148:151], v164 offset:39168
	ds_read_b128 v[152:155], v164 offset:39232
	v_sub_f32_e32 v90, v86, v174
	v_sub_f32_e32 v91, v87, v174
	v_sub_f32_e32 v92, v88, v174
	v_sub_f32_e32 v93, v89, v174
	s_waitcnt lgkmcnt(2)
	v_mfma_f32_16x16x32_bf16 v[54:57], v[156:159], v[204:207], v[86:89]
	v_mfma_f32_16x16x32_bf16 v[54:57], v[160:163], v[208:211], v[54:57]
	ds_read_b128 v[156:159], v164 offset:41472
	ds_read_b128 v[160:163], v164 offset:41536
	v_sub_f32_e32 v86, v90, v174
	v_sub_f32_e32 v87, v91, v174
	v_sub_f32_e32 v88, v92, v174
	v_sub_f32_e32 v89, v93, v174
	s_waitcnt lgkmcnt(2)
	v_mfma_f32_16x16x32_bf16 v[58:61], v[148:151], v[204:207], v[90:93]
	v_mfma_f32_16x16x32_bf16 v[58:61], v[152:155], v[208:211], v[58:61]
	ds_read_b128 v[148:151], v164 offset:43776
	ds_read_b128 v[152:155], v164 offset:43840
	v_sub_f32_e32 v90, v86, v174
	v_sub_f32_e32 v91, v87, v174
	v_sub_f32_e32 v92, v88, v174
	v_sub_f32_e32 v93, v89, v174
	v_cmp_le_i32_e32 vcc, 0, v108
	s_nop 1
	v_cndmask_b32_e32 v212, v252, v90, vcc
	v_cmp_le_i32_e32 vcc, 0, v110
	s_nop 1
	v_cndmask_b32_e32 v213, v252, v91, vcc
	v_cmp_le_i32_e32 vcc, 0, v111
	s_nop 1
	v_cndmask_b32_e32 v214, v252, v92, vcc
	v_cmp_le_i32_e32 vcc, 0, v177
	s_nop 1
	v_cndmask_b32_e32 v215, v252, v93, vcc
	s_waitcnt lgkmcnt(2)
	v_mfma_f32_16x16x32_bf16 v[62:65], v[156:159], v[204:207], v[86:89]
	v_mfma_f32_16x16x32_bf16 v[62:65], v[160:163], v[208:211], v[62:65]
	s_waitcnt lgkmcnt(0)
	v_mfma_f32_16x16x32_bf16 v[66:69], v[148:151], v[204:207], v[212:215]
	v_mfma_f32_16x16x32_bf16 v[66:69], v[152:155], v[208:211], v[66:69]
	ds_read2_b64 v[216:219], v165 offset0:12 offset1:16
	ds_read2_b64 v[220:223], v166 offset0:12 offset1:16
	ds_read2_b64 v[224:227], v167 offset0:12 offset1:16
	ds_read2_b64 v[228:231], v168 offset0:12 offset1:16
	v_max3_f32 v169, v2, v3, v4
	v_max3_f32 v172, v5, v6, v7
	v_max3_f32 v169, v8, v9, v169
	v_max3_f32 v172, v10, v11, v172
	v_max3_f32 v169, v12, v13, v169
	v_max3_f32 v172, v14, v15, v172
	v_max3_f32 v169, v16, v17, v169
	v_max3_f32 v172, v18, v19, v172
	v_max3_f32 v169, v20, v21, v169
	v_max3_f32 v172, v22, v23, v172
	v_max3_f32 v169, v24, v25, v169
	v_max3_f32 v172, v26, v27, v172
	v_max3_f32 v169, v28, v29, v169
	v_max3_f32 v172, v30, v31, v172
	v_max3_f32 v169, v32, v33, v169
	v_max3_f32 v172, v34, v35, v172
	v_max3_f32 v169, v36, v37, v169
	v_max3_f32 v172, v38, v39, v172
	v_max3_f32 v169, v40, v41, v169
	v_max3_f32 v172, v42, v43, v172
	v_max3_f32 v169, v44, v45, v169
	v_max3_f32 v172, v46, v47, v172
	v_max3_f32 v169, v48, v49, v169
	v_max3_f32 v172, v50, v51, v172
	v_max3_f32 v169, v52, v53, v169
	v_max3_f32 v172, v54, v55, v172
	v_max3_f32 v169, v56, v57, v169
	v_max3_f32 v172, v58, v59, v172
	v_max3_f32 v169, v60, v61, v169
	v_max3_f32 v172, v62, v63, v172
	v_max3_f32 v169, v64, v65, v169
	v_max3_f32 v172, v66, v67, v172
	v_max3_f32 v169, v68, v69, v169
	v_max_f32_e32 v169, v169, v172
	v_mul_f32_e32 v169, 0x3e000000, v169
	v_max_f32_e32 v169, v169, v146
	ds_bpermute_b32 v172, v1, v169
	s_waitcnt lgkmcnt(0)
	v_max_f32_e32 v169, v169, v172
	ds_bpermute_b32 v172, v114, v169
	s_waitcnt lgkmcnt(0)
; __device__ void att_phase(int wv, const Params& p, unsigned char* lds) {
;     ...
;             mx = fmaxf(mx, __shfl_xor(mx, 16)); mx = fmaxf(mx, __shfl_xor(mx, 32));
;             float sum = 0.f;
; #pragma unroll
;             for (int cb = 0; cb < 24; ++cb)
; #pragma unroll
;                 for (int j = 0; j < 4; ++j) { const float e = __expf(sc[cb][j] - mx); sc[cb][j] = e; sum += e; }
	v_max_f32_e32 v169, v169, v172
	v_mul_f32_e32 v175, 0xbfb8aa3b, v169
	v_mov_b32_e32 v170, 0
	v_mov_b32_e32 v171, 0
	v_fma_f32 v2, v2, s46, v175
	v_fma_f32 v3, v3, s46, v175
	v_fma_f32 v4, v4, s46, v175
	v_fma_f32 v5, v5, s46, v175
	v_exp_f32_e32 v2, v2
	v_exp_f32_e32 v3, v3
	v_exp_f32_e32 v4, v4
	v_exp_f32_e32 v5, v5
	v_fma_f32 v6, v6, s46, v175
	v_fma_f32 v7, v7, s46, v175
	v_fma_f32 v8, v8, s46, v175
	v_fma_f32 v9, v9, s46, v175
	v_exp_f32_e32 v6, v6
	v_exp_f32_e32 v7, v7
	v_exp_f32_e32 v8, v8
	v_exp_f32_e32 v9, v9
	v_add_f32_e32 v171, v171, v2
	v_add_f32_e32 v170, v170, v3
	v_add_f32_e32 v171, v171, v4
	v_add_f32_e32 v170, v170, v5
	v_fma_f32 v10, v10, s46, v175
	v_fma_f32 v11, v11, s46, v175
	v_fma_f32 v12, v12, s46, v175
	v_fma_f32 v13, v13, s46, v175
	v_exp_f32_e32 v10, v10
	v_exp_f32_e32 v11, v11
	v_exp_f32_e32 v12, v12
	v_exp_f32_e32 v13, v13
	v_add_f32_e32 v171, v171, v6
	v_add_f32_e32 v170, v170, v7
	v_add_f32_e32 v171, v171, v8
	v_add_f32_e32 v170, v170, v9
	v_fma_f32 v14, v14, s46, v175
	v_fma_f32 v15, v15, s46, v175
	v_fma_f32 v16, v16, s46, v175
	v_fma_f32 v17, v17, s46, v175
	v_exp_f32_e32 v14, v14
	v_exp_f32_e32 v15, v15
	v_exp_f32_e32 v16, v16
	v_exp_f32_e32 v17, v17
	v_add_f32_e32 v171, v171, v10
	v_add_f32_e32 v170, v170, v11
	v_add_f32_e32 v171, v171, v12
	v_add_f32_e32 v170, v170, v13
	v_fma_f32 v18, v18, s46, v175
	v_fma_f32 v19, v19, s46, v175
	v_fma_f32 v20, v20, s46, v175
	v_fma_f32 v21, v21, s46, v175
	v_exp_f32_e32 v18, v18
	v_exp_f32_e32 v19, v19
	v_exp_f32_e32 v20, v20
	v_exp_f32_e32 v21, v21
	v_add_f32_e32 v171, v171, v14
	v_add_f32_e32 v170, v170, v15
	v_add_f32_e32 v171, v171, v16
	v_add_f32_e32 v170, v170, v17
	v_fma_f32 v22, v22, s46, v175
	v_fma_f32 v23, v23, s46, v175
	v_fma_f32 v24, v24, s46, v175
	v_fma_f32 v25, v25, s46, v175
	v_exp_f32_e32 v22, v22
	v_exp_f32_e32 v23, v23
	v_exp_f32_e32 v24, v24
	v_exp_f32_e32 v25, v25
	v_add_f32_e32 v171, v171, v18
	v_add_f32_e32 v170, v170, v19
	v_add_f32_e32 v171, v171, v20
	v_add_f32_e32 v170, v170, v21
	v_fma_f32 v26, v26, s46, v175
	v_fma_f32 v27, v27, s46, v175
	v_fma_f32 v28, v28, s46, v175
	v_fma_f32 v29, v29, s46, v175
	v_exp_f32_e32 v26, v26
	v_exp_f32_e32 v27, v27
	v_exp_f32_e32 v28, v28
	v_exp_f32_e32 v29, v29
	v_add_f32_e32 v171, v171, v22
	v_add_f32_e32 v170, v170, v23
	v_add_f32_e32 v171, v171, v24
	v_add_f32_e32 v170, v170, v25
	v_fma_f32 v30, v30, s46, v175
	v_fma_f32 v31, v31, s46, v175
	v_fma_f32 v32, v32, s46, v175
	v_fma_f32 v33, v33, s46, v175
	v_exp_f32_e32 v30, v30
	v_exp_f32_e32 v31, v31
	v_exp_f32_e32 v32, v32
	v_exp_f32_e32 v33, v33
	v_add_f32_e32 v171, v171, v26
	v_add_f32_e32 v170, v170, v27
	v_add_f32_e32 v171, v171, v28
	v_add_f32_e32 v170, v170, v29
	v_fma_f32 v34, v34, s46, v175
	v_fma_f32 v35, v35, s46, v175
	v_fma_f32 v36, v36, s46, v175
	v_fma_f32 v37, v37, s46, v175
	v_exp_f32_e32 v34, v34
	v_exp_f32_e32 v35, v35
	v_exp_f32_e32 v36, v36
	v_exp_f32_e32 v37, v37
	v_add_f32_e32 v171, v171, v30
	v_add_f32_e32 v170, v170, v31
	v_add_f32_e32 v171, v171, v32
	v_add_f32_e32 v170, v170, v33
	v_fma_f32 v38, v38, s46, v175
	v_fma_f32 v39, v39, s46, v175
	v_fma_f32 v40, v40, s46, v175
	v_fma_f32 v41, v41, s46, v175
	v_exp_f32_e32 v38, v38
	v_exp_f32_e32 v39, v39
	v_exp_f32_e32 v40, v40
	v_exp_f32_e32 v41, v41
	v_add_f32_e32 v171, v171, v34
	v_add_f32_e32 v170, v170, v35
	v_add_f32_e32 v171, v171, v36
	v_add_f32_e32 v170, v170, v37
	v_fma_f32 v42, v42, s46, v175
	v_fma_f32 v43, v43, s46, v175
	v_fma_f32 v44, v44, s46, v175
	v_fma_f32 v45, v45, s46, v175
	v_exp_f32_e32 v42, v42
	v_exp_f32_e32 v43, v43
	v_exp_f32_e32 v44, v44
	v_exp_f32_e32 v45, v45
	v_add_f32_e32 v171, v171, v38
	v_add_f32_e32 v170, v170, v39
	v_add_f32_e32 v171, v171, v40
	v_add_f32_e32 v170, v170, v41
	v_fma_f32 v46, v46, s46, v175
	v_fma_f32 v47, v47, s46, v175
	v_fma_f32 v48, v48, s46, v175
	v_fma_f32 v49, v49, s46, v175
	v_exp_f32_e32 v46, v46
	v_exp_f32_e32 v47, v47
	v_exp_f32_e32 v48, v48
	v_exp_f32_e32 v49, v49
	v_add_f32_e32 v171, v171, v42
	v_add_f32_e32 v170, v170, v43
	v_add_f32_e32 v171, v171, v44
	v_add_f32_e32 v170, v170, v45
	v_fma_f32 v50, v50, s46, v175
	v_fma_f32 v51, v51, s46, v175
	v_fma_f32 v52, v52, s46, v175
	v_fma_f32 v53, v53, s46, v175
	v_exp_f32_e32 v50, v50
	v_exp_f32_e32 v51, v51
	v_exp_f32_e32 v52, v52
	v_exp_f32_e32 v53, v53
	v_add_f32_e32 v171, v171, v46
	v_add_f32_e32 v170, v170, v47
	v_add_f32_e32 v171, v171, v48
	v_add_f32_e32 v170, v170, v49
	v_fma_f32 v54, v54, s46, v175
	v_fma_f32 v55, v55, s46, v175
	v_fma_f32 v56, v56, s46, v175
	v_fma_f32 v57, v57, s46, v175
	v_exp_f32_e32 v54, v54
	v_exp_f32_e32 v55, v55
	v_exp_f32_e32 v56, v56
	v_exp_f32_e32 v57, v57
	v_add_f32_e32 v171, v171, v50
	v_add_f32_e32 v170, v170, v51
	v_add_f32_e32 v171, v171, v52
	v_add_f32_e32 v170, v170, v53
	v_fma_f32 v58, v58, s46, v175
	v_fma_f32 v59, v59, s46, v175
	v_fma_f32 v60, v60, s46, v175
	v_fma_f32 v61, v61, s46, v175
	v_exp_f32_e32 v58, v58
	v_exp_f32_e32 v59, v59
	v_exp_f32_e32 v60, v60
	v_exp_f32_e32 v61, v61
	v_add_f32_e32 v171, v171, v54
	v_add_f32_e32 v170, v170, v55
	v_add_f32_e32 v171, v171, v56
	v_add_f32_e32 v170, v170, v57
	v_fma_f32 v62, v62, s46, v175
	v_fma_f32 v63, v63, s46, v175
	v_fma_f32 v64, v64, s46, v175
	v_fma_f32 v65, v65, s46, v175
	v_exp_f32_e32 v62, v62
	v_exp_f32_e32 v63, v63
	v_exp_f32_e32 v64, v64
	v_exp_f32_e32 v65, v65
	v_add_f32_e32 v171, v171, v58
	v_add_f32_e32 v170, v170, v59
	v_add_f32_e32 v171, v171, v60
	v_add_f32_e32 v170, v170, v61
	v_fma_f32 v66, v66, s46, v175
	v_fma_f32 v67, v67, s46, v175
	v_fma_f32 v68, v68, s46, v175
	v_fma_f32 v69, v69, s46, v175
	v_exp_f32_e32 v66, v66
	v_exp_f32_e32 v67, v67
; __device__ __forceinline__ unsigned cvt_pk_bf16_asm(float lo, float hi) { unsigned r; asm volatile("v_cvt_pk_bf16_f32 %0, %1, %2" : "=v"(r) : "v"(lo), "v"(hi)); return r; }
; __device__ __forceinline__ f32x4 mfma16(bf16x8 a, bf16x8 b, f32x4 c) { return __builtin_amdgcn_mfma_f32_16x16x32_bf16(a, b, c, 0, 0, 0); }
; __device__ void att_phase(int wv, const Params& p, unsigned char* lds) {
;     ...
;             for (int cb = 0; cb < 24; ++cb)
; #pragma unroll
;                 for (int j = 0; j < 4; ++j) { const float e = __expf(sc[cb][j] - mx); sc[cb][j] = e; sum += e; }
;             sum += __shfl_xor(sum, 16); sum += __shfl_xor(sum, 32);
;             sum += __expf(sink - mx);
;             const float inv = 1.0f / sum;
;             f32x4 oa[4];
; #pragma unroll
;             for (int db = 0; db < 4; ++db) oa[db] = (f32x4){0, 0, 0, 0};
; #pragma unroll
;             for (int ks = 0; ks < 12; ++ks) {
;                 union { bf16x8 v; unsigned u[4]; } pf;
;                 pf.u[0] = cvt_pk_bf16_asm(sc[2 * ks][0], sc[2 * ks][1]); pf.u[1] = cvt_pk_bf16_asm(sc[2 * ks][2], sc[2 * ks][3]);
;                 pf.u[2] = cvt_pk_bf16_asm(sc[2 * ks + 1][0], sc[2 * ks + 1][1]); pf.u[3] = cvt_pk_bf16_asm(sc[2 * ks + 1][2], sc[2 * ks + 1][3]);
; #pragma unroll
;                 for (int db = 0; db < 4; ++db) {
;                     union { bf16x8 v; u32x2 h2[2]; } vf;
;                     const bf16_t* vp = VTL + (16 * db + lr) * VP + 32 * ks + 4 * lq;
;                     vf.h2[0] = *(const u32x2*)vp; vf.h2[1] = *(const u32x2*)(vp + 16);
;                     oa[db] = mfma16(vf.v, pf.v, oa[db]); } }
	v_exp_f32_e32 v68, v68
	v_exp_f32_e32 v69, v69
	v_add_f32_e32 v171, v171, v62
	v_add_f32_e32 v170, v170, v63
	v_add_f32_e32 v171, v171, v64
	v_add_f32_e32 v170, v170, v65
	v_add_f32_e32 v171, v171, v66
	v_add_f32_e32 v170, v170, v67
	v_add_f32_e32 v171, v171, v68
	v_add_f32_e32 v170, v170, v69
	v_add_f32_e32 v170, v170, v171
	v_cvt_pk_bf16_f32 v2, v2, v3
	v_cvt_pk_bf16_f32 v3, v4, v5
	v_cvt_pk_bf16_f32 v4, v6, v7
	v_cvt_pk_bf16_f32 v5, v8, v9
	v_cvt_pk_bf16_f32 v10, v10, v11
	v_cvt_pk_bf16_f32 v11, v12, v13
	v_cvt_pk_bf16_f32 v12, v14, v15
	v_cvt_pk_bf16_f32 v13, v16, v17
	v_cvt_pk_bf16_f32 v18, v18, v19
	v_cvt_pk_bf16_f32 v19, v20, v21
	v_cvt_pk_bf16_f32 v20, v22, v23
	v_cvt_pk_bf16_f32 v21, v24, v25
	v_cvt_pk_bf16_f32 v26, v26, v27
	v_cvt_pk_bf16_f32 v27, v28, v29
	v_cvt_pk_bf16_f32 v28, v30, v31
	v_cvt_pk_bf16_f32 v29, v32, v33
	v_cvt_pk_bf16_f32 v34, v34, v35
	v_cvt_pk_bf16_f32 v35, v36, v37
	v_cvt_pk_bf16_f32 v36, v38, v39
	v_cvt_pk_bf16_f32 v37, v40, v41
	v_cvt_pk_bf16_f32 v42, v42, v43
	v_cvt_pk_bf16_f32 v43, v44, v45
	v_cvt_pk_bf16_f32 v44, v46, v47
	v_cvt_pk_bf16_f32 v45, v48, v49
	v_cvt_pk_bf16_f32 v50, v50, v51
	v_cvt_pk_bf16_f32 v51, v52, v53
	v_cvt_pk_bf16_f32 v52, v54, v55
	v_cvt_pk_bf16_f32 v53, v56, v57
	v_cvt_pk_bf16_f32 v58, v58, v59
	v_cvt_pk_bf16_f32 v59, v60, v61
	v_cvt_pk_bf16_f32 v60, v62, v63
	v_cvt_pk_bf16_f32 v61, v64, v65
	v_cvt_pk_bf16_f32 v66, v66, v67
	v_cvt_pk_bf16_f32 v67, v68, v69
	v_mov_b32_e32 v68, 0
	v_mov_b32_e32 v69, 0
	ds_bpermute_b32 v172, v1, v170
	v_sub_f32_e32 v173, v146, v169
	v_mul_f32_e32 v173, 0x3fb8aa3b, v173
	v_exp_f32_e32 v173, v173
	s_waitcnt lgkmcnt(0)
	v_add_f32_e32 v170, v170, v172
	ds_bpermute_b32 v172, v114, v170
	ds_read2_b64 v[232:235], v165 offset0:20 offset1:24
	ds_read2_b64 v[236:239], v166 offset0:20 offset1:24
	ds_read2_b64 v[240:243], v167 offset0:20 offset1:24
	ds_read2_b64 v[244:247], v168 offset0:20 offset1:24
	s_waitcnt lgkmcnt(4)
	v_mfma_f32_16x16x32_bf16 v[70:73], v[216:219], v[2:5], 0
	v_mfma_f32_16x16x32_bf16 v[74:77], v[220:223], v[2:5], 0
	v_mfma_f32_16x16x32_bf16 v[78:81], v[224:227], v[2:5], 0
	v_mfma_f32_16x16x32_bf16 v[82:85], v[228:231], v[2:5], 0
	v_add_f32_e32 v170, v170, v172
	v_add_f32_e32 v170, v170, v173
	v_rcp_f32_e32 v147, v170
	s_nop 0
	v_fma_f32 v179, -v170, v147, 1.0
	v_fmac_f32_e32 v147, v179, v147
	ds_read2_b64 v[216:219], v165 offset0:28 offset1:32
	ds_read2_b64 v[220:223], v166 offset0:28 offset1:32
	ds_read2_b64 v[224:227], v167 offset0:28 offset1:32
	ds_read2_b64 v[228:231], v168 offset0:28 offset1:32
	s_waitcnt lgkmcnt(4)
	v_mfma_f32_16x16x32_bf16 v[70:73], v[232:235], v[10:13], v[70:73]
	v_mfma_f32_16x16x32_bf16 v[74:77], v[236:239], v[10:13], v[74:77]
	v_mfma_f32_16x16x32_bf16 v[78:81], v[240:243], v[10:13], v[78:81]
	v_mfma_f32_16x16x32_bf16 v[82:85], v[244:247], v[10:13], v[82:85]
	ds_read2_b64 v[232:235], v165 offset0:36 offset1:40
	ds_read2_b64 v[236:239], v166 offset0:36 offset1:40
	ds_read2_b64 v[240:243], v167 offset0:36 offset1:40
	ds_read2_b64 v[244:247], v168 offset0:36 offset1:40
	s_waitcnt lgkmcnt(4)
	v_mfma_f32_16x16x32_bf16 v[70:73], v[216:219], v[18:21], v[70:73]
	v_mfma_f32_16x16x32_bf16 v[74:77], v[220:223], v[18:21], v[74:77]
	v_mfma_f32_16x16x32_bf16 v[78:81], v[224:227], v[18:21], v[78:81]
	v_mfma_f32_16x16x32_bf16 v[82:85], v[228:231], v[18:21], v[82:85]
	ds_read2_b64 v[216:219], v165 offset0:44 offset1:48
	ds_read2_b64 v[220:223], v166 offset0:44 offset1:48
	ds_read2_b64 v[224:227], v167 offset0:44 offset1:48
	ds_read2_b64 v[228:231], v168 offset0:44 offset1:48
	s_waitcnt lgkmcnt(4)
	v_mfma_f32_16x16x32_bf16 v[70:73], v[232:235], v[26:29], v[70:73]
	v_mfma_f32_16x16x32_bf16 v[74:77], v[236:239], v[26:29], v[74:77]
	v_mfma_f32_16x16x32_bf16 v[78:81], v[240:243], v[26:29], v[78:81]
	v_mfma_f32_16x16x32_bf16 v[82:85], v[244:247], v[26:29], v[82:85]
	ds_read2_b64 v[232:235], v165 offset0:52 offset1:56
	ds_read2_b64 v[236:239], v166 offset0:52 offset1:56
	ds_read2_b64 v[240:243], v167 offset0:52 offset1:56
	ds_read2_b64 v[244:247], v168 offset0:52 offset1:56
	s_waitcnt lgkmcnt(4)
	v_mfma_f32_16x16x32_bf16 v[70:73], v[216:219], v[34:37], v[70:73]
	v_mfma_f32_16x16x32_bf16 v[74:77], v[220:223], v[34:37], v[74:77]
	v_mfma_f32_16x16x32_bf16 v[78:81], v[224:227], v[34:37], v[78:81]
	v_mfma_f32_16x16x32_bf16 v[82:85], v[228:231], v[34:37], v[82:85]
	ds_read2_b64 v[216:219], v165 offset0:60 offset1:64
	ds_read2_b64 v[220:223], v166 offset0:60 offset1:64
	ds_read2_b64 v[224:227], v167 offset0:60 offset1:64
	ds_read2_b64 v[228:231], v168 offset0:60 offset1:64
	s_waitcnt lgkmcnt(4)
	v_mfma_f32_16x16x32_bf16 v[70:73], v[232:235], v[42:45], v[70:73]
	v_mfma_f32_16x16x32_bf16 v[74:77], v[236:239], v[42:45], v[74:77]
	v_mfma_f32_16x16x32_bf16 v[78:81], v[240:243], v[42:45], v[78:81]
	v_mfma_f32_16x16x32_bf16 v[82:85], v[244:247], v[42:45], v[82:85]
	ds_read2_b64 v[232:235], v165 offset0:68 offset1:72
	ds_read2_b64 v[236:239], v166 offset0:68 offset1:72
	ds_read2_b64 v[240:243], v167 offset0:68 offset1:72
	ds_read2_b64 v[244:247], v168 offset0:68 offset1:72
	s_waitcnt lgkmcnt(4)
	v_mfma_f32_16x16x32_bf16 v[70:73], v[216:219], v[50:53], v[70:73]
	v_mfma_f32_16x16x32_bf16 v[74:77], v[220:223], v[50:53], v[74:77]
	v_mfma_f32_16x16x32_bf16 v[78:81], v[224:227], v[50:53], v[78:81]
	v_mfma_f32_16x16x32_bf16 v[82:85], v[228:231], v[50:53], v[82:85]
	ds_read2_b64 v[216:219], v165 offset0:76 offset1:76
	ds_read2_b64 v[220:223], v166 offset0:76 offset1:76
	ds_read2_b64 v[224:227], v167 offset0:76 offset1:76
	ds_read2_b64 v[228:231], v168 offset0:76 offset1:76
	s_waitcnt lgkmcnt(4)
; __device__ __forceinline__ unsigned cvt_pk_bf16_asm(float lo, float hi) { unsigned r; asm volatile("v_cvt_pk_bf16_f32 %0, %1, %2" : "=v"(r) : "v"(lo), "v"(hi)); return r; }
; __device__ __forceinline__ f32x4 mfma16(bf16x8 a, bf16x8 b, f32x4 c) { return __builtin_amdgcn_mfma_f32_16x16x32_bf16(a, b, c, 0, 0, 0); }
; __device__ void att_phase(int wv, const Params& p, unsigned char* lds) {
;     ...
;         const int gq = w >> 1, h = 4 * kh + gq;
;         const float slope = exp2f(-0.5f * (float)(h + 1)), sink = p.b_sinks[h];
;         for (int rb = 0; rb < 4; ++rb) {
;             const int qrow = 64 * (w & 1) + 16 * rb + lr;
;             const size_t tokq = (size_t)B * 128 + qrow;
;             bf16x8 qf[2];
; #pragma unroll
;             for (int kk = 0; kk < 2; ++kk) qf[kk] = *(const bf16x8*)(qkv + tokq * 1536 + 64 * h + 32 * kk + 8 * lq);
;             f32x4 sc[24];
; #pragma unroll
;             for (int cb = 0; cb < 24; ++cb) { f32x4 a = {0, 0, 0, 0};
; #pragma unroll
;                 for (int kk = 0; kk < 2; ++kk) { const bf16x8 kf = *(const bf16x8*)(KL + (16 * cb + lr) * KP + 32 * kk + 8 * lq); a = mfma16(kf, qf[kk], a); }
;                 sc[cb] = a; }
;             float mx = sink;
; #pragma unroll
;             for (int cb = 0; cb < 24; ++cb) { const int kb = B - 1 + (cb >> 3); const bool bval = (kb >= sb && kb < se);
; #pragma unroll
;                 for (int j = 0; j < 4; ++j) { const int krel = 16 * cb + 4 * lq + j - 128;
;                     int dist = qrow - krel; dist = dist < 0 ? -dist : dist;
;                     const float v = (bval && dist <= 128) ? sc[cb][j] * 0.125f - slope * (float)dist : -1e30f;
;                     sc[cb][j] = v; mx = fmaxf(mx, v); } }
;     ...
;                 for (int db = 0; db < 4; ++db) {
;                     union { bf16x8 v; u32x2 h2[2]; } vf;
;                     const bf16_t* vp = VTL + (16 * db + lr) * VP + 32 * ks + 4 * lq;
;                     vf.h2[0] = *(const u32x2*)vp; vf.h2[1] = *(const u32x2*)(vp + 16);
;                     oa[db] = mfma16(vf.v, pf.v, oa[db]); } }
; #pragma unroll
;             for (int db = 0; db < 4; ++db) { const f32x4 o = oa[db] * inv; u32x2 wv; wv.x = cvt_pk_bf16_asm(o[0], o[1]); wv.y = cvt_pk_bf16_asm(o[2], o[3]);
;                 *(u32x2*)(qkv + tokq * 1536 + 64 * h + 16 * db + 4 * lq) = wv; }
	v_mfma_f32_16x16x32_bf16 v[70:73], v[232:235], v[58:61], v[70:73]
	v_mfma_f32_16x16x32_bf16 v[74:77], v[236:239], v[58:61], v[74:77]
	v_mfma_f32_16x16x32_bf16 v[78:81], v[240:243], v[58:61], v[78:81]
	v_mfma_f32_16x16x32_bf16 v[82:85], v[244:247], v[58:61], v[82:85]
	s_waitcnt lgkmcnt(0)
	v_mfma_f32_16x16x32_bf16 v[70:73], v[216:219], v[66:69], v[70:73]
	v_mfma_f32_16x16x32_bf16 v[74:77], v[220:223], v[66:69], v[74:77]
	v_mfma_f32_16x16x32_bf16 v[78:81], v[224:227], v[66:69], v[78:81]
	v_mfma_f32_16x16x32_bf16 v[82:85], v[228:231], v[66:69], v[82:85]
	s_nop 7
	s_nop 1
	v_mul_f32_e32 v70, v70, v147
	v_mul_f32_e32 v71, v71, v147
	v_mul_f32_e32 v72, v72, v147
	v_mul_f32_e32 v73, v73, v147
	v_mul_f32_e32 v74, v74, v147
	v_mul_f32_e32 v75, v75, v147
	v_mul_f32_e32 v76, v76, v147
	v_mul_f32_e32 v77, v77, v147
	v_mul_f32_e32 v78, v78, v147
	v_mul_f32_e32 v79, v79, v147
	v_mul_f32_e32 v80, v80, v147
	v_mul_f32_e32 v81, v81, v147
	v_mul_f32_e32 v82, v82, v147
	v_mul_f32_e32 v83, v83, v147
	v_mul_f32_e32 v84, v84, v147
	v_mul_f32_e32 v85, v85, v147
	v_cvt_pk_bf16_f32 v70, v70, v71
	v_cvt_pk_bf16_f32 v71, v72, v73
	v_cvt_pk_bf16_f32 v74, v74, v75
	v_cvt_pk_bf16_f32 v75, v76, v77
	v_cvt_pk_bf16_f32 v78, v78, v79
	v_cvt_pk_bf16_f32 v79, v80, v81
	v_cvt_pk_bf16_f32 v82, v82, v83
	v_cvt_pk_bf16_f32 v83, v84, v85
	global_store_dwordx2 v[248:249], v[70:71], off offset:-64
	global_store_dwordx2 v[248:249], v[74:75], off offset:-32
	global_store_dwordx2 v[248:249], v[78:79], off
	global_store_dwordx2 v[248:249], v[82:83], off offset:32
	s_branch .Latt_done
.Latt_general:
	s_mov_b32 s46, 0x3e38aa3b
	s_and_b32 s47, s33, 1
	s_mul_i32 s22, s47, 0x2400
	v_add_u32_e32 v164, s22, v141
	s_lshl_b32 s22, s47, 7
	s_add_i32 s22, s22, 0xd800
	v_add_u32_e32 v165, s22, v142
	v_add_u32_e32 v166, s22, v143
	v_add_u32_e32 v167, s22, v144
	v_add_u32_e32 v168, s22, v145
	s_lshl_b32 s47, s47, 2
	v_and_b32_e32 v172, 15, v250
	v_lshrrev_b32_e32 v173, 4, v250
	v_lshlrev_b32_e32 v173, 2, v173
	v_sub_u32_e32 v108, v172, v173
	v_subrev_u32_e32 v110, 1, v108
	v_subrev_u32_e32 v111, 2, v108
	v_subrev_u32_e32 v177, 3, v108
	v_mul_f32_e32 v147, 0xc1000000, v109
	v_mul_f32_e32 v174, 0x43000000, v109
	v_mul_f32_e32 v176, 0x44800000, v109
	v_cvt_f32_i32_e32 v179, v108
	v_mul_f32_e32 v94, v147, v179
	v_mul_f32_e64 v98, v147, |v179|
	v_cvt_f32_i32_e32 v179, v110
	v_mul_f32_e32 v95, v147, v179
	v_mul_f32_e64 v99, v147, |v179|
	v_cvt_f32_i32_e32 v179, v111
	v_mul_f32_e32 v96, v147, v179
	v_mul_f32_e64 v100, v147, |v179|
	v_cvt_f32_i32_e32 v179, v177
	v_mul_f32_e32 v97, v147, v179
	v_mul_f32_e64 v101, v147, |v179|
	v_lshl_add_u64 v[248:249], v[112:113], 0, s[0:1]
	v_sub_f32_e32 v86, v94, v176
	v_sub_f32_e32 v87, v95, v176
	v_sub_f32_e32 v88, v96, v176
	v_sub_f32_e32 v89, v97, v176
	v_cmp_ge_i32_e32 vcc, 0, v108
	s_nop 1
	v_cndmask_b32_e32 v212, v252, v86, vcc
	v_cmp_ge_i32_e32 vcc, 0, v110
	s_nop 1
	v_cndmask_b32_e32 v213, v252, v87, vcc
	v_cmp_ge_i32_e32 vcc, 0, v111
	s_nop 1
	v_cndmask_b32_e32 v214, v252, v88, vcc
	v_cmp_ge_i32_e32 vcc, 0, v177
	s_nop 1
	v_cndmask_b32_e32 v215, v252, v89, vcc
	ds_read_b128 v[148:151], v164 offset:0
	ds_read_b128 v[152:155], v164 offset:64
	ds_read_b128 v[156:159], v164 offset:2304
	ds_read_b128 v[160:163], v164 offset:2368
	v_add_f32_e32 v90, v86, v174
	v_add_f32_e32 v91, v87, v174
	v_add_f32_e32 v92, v88, v174
	v_add_f32_e32 v93, v89, v174
	s_cmp_lt_i32 s47, 16
	s_cselect_b64 vcc, -1, s[10:11]
	s_cmp_lt_i32 s47, 8
	s_cselect_b64 vcc, s[6:7], vcc
	v_cndmask_b32_e32 v232, v252, v212, vcc
	v_cndmask_b32_e32 v233, v252, v213, vcc
	v_cndmask_b32_e32 v234, v252, v214, vcc
	v_cndmask_b32_e32 v235, v252, v215, vcc
	s_waitcnt lgkmcnt(2)
	v_mfma_f32_16x16x32_bf16 v[2:5], v[148:151], v[180:183], v[232:235]
	v_mfma_f32_16x16x32_bf16 v[2:5], v[152:155], v[184:187], v[2:5]
	ds_read_b128 v[148:151], v164 offset:4608
	ds_read_b128 v[152:155], v164 offset:4672
	v_add_f32_e32 v86, v90, v174
	v_add_f32_e32 v87, v91, v174
	v_add_f32_e32 v88, v92, v174
	v_add_f32_e32 v89, v93, v174
	s_cmp_lt_i32 s47, 15
	s_cselect_b64 vcc, -1, s[10:11]
	s_cmp_lt_i32 s47, 7
	s_cselect_b64 vcc, s[6:7], vcc
	v_cndmask_b32_e32 v236, v252, v90, vcc
	v_cndmask_b32_e32 v237, v252, v91, vcc
	v_cndmask_b32_e32 v238, v252, v92, vcc
	v_cndmask_b32_e32 v239, v252, v93, vcc
	s_waitcnt lgkmcnt(2)
	v_mfma_f32_16x16x32_bf16 v[6:9], v[156:159], v[180:183], v[236:239]
	v_mfma_f32_16x16x32_bf16 v[6:9], v[160:163], v[184:187], v[6:9]
	ds_read_b128 v[156:159], v164 offset:6912
	ds_read_b128 v[160:163], v164 offset:6976
	v_add_f32_e32 v90, v86, v174
	v_add_f32_e32 v91, v87, v174
	v_add_f32_e32 v92, v88, v174
	v_add_f32_e32 v93, v89, v174
	s_cmp_lt_i32 s47, 14
	s_cselect_b64 vcc, -1, s[10:11]
	s_cmp_lt_i32 s47, 6
	s_cselect_b64 vcc, s[6:7], vcc
	v_cndmask_b32_e32 v232, v252, v86, vcc
	v_cndmask_b32_e32 v233, v252, v87, vcc
	v_cndmask_b32_e32 v234, v252, v88, vcc
	v_cndmask_b32_e32 v235, v252, v89, vcc
	s_waitcnt lgkmcnt(2)
	v_mfma_f32_16x16x32_bf16 v[10:13], v[148:151], v[180:183], v[232:235]
	v_mfma_f32_16x16x32_bf16 v[10:13], v[152:155], v[184:187], v[10:13]
	ds_read_b128 v[148:151], v164 offset:9216
	ds_read_b128 v[152:155], v164 offset:9280
	v_add_f32_e32 v86, v90, v174
	v_add_f32_e32 v87, v91, v174
	v_add_f32_e32 v88, v92, v174
	v_add_f32_e32 v89, v93, v174
	s_cmp_lt_i32 s47, 13
	s_cselect_b64 vcc, -1, s[10:11]
	s_cmp_lt_i32 s47, 5
	s_cselect_b64 vcc, s[6:7], vcc
	v_cndmask_b32_e32 v236, v252, v90, vcc
	v_cndmask_b32_e32 v237, v252, v91, vcc
	v_cndmask_b32_e32 v238, v252, v92, vcc
	v_cndmask_b32_e32 v239, v252, v93, vcc
	s_waitcnt lgkmcnt(2)
; __device__ __forceinline__ f32x4 mfma16(bf16x8 a, bf16x8 b, f32x4 c) { return __builtin_amdgcn_mfma_f32_16x16x32_bf16(a, b, c, 0, 0, 0); }
; __device__ void att_phase(int wv, const Params& p, unsigned char* lds) {
;     ...
; #pragma unroll
;             for (int cb = 0; cb < 24; ++cb) { f32x4 a = {0, 0, 0, 0};
; #pragma unroll
;                 for (int kk = 0; kk < 2; ++kk) { const bf16x8 kf = *(const bf16x8*)(KL + (16 * cb + lr) * KP + 32 * kk + 8 * lq); a = mfma16(kf, qf[kk], a); }
;                 sc[cb] = a; }
;             float mx = sink;
; #pragma unroll
;             for (int cb = 0; cb < 24; ++cb) { const int kb = B - 1 + (cb >> 3); const bool bval = (kb >= sb && kb < se);
; #pragma unroll
;                 for (int j = 0; j < 4; ++j) { const int krel = 16 * cb + 4 * lq + j - 128;
;                     int dist = qrow - krel; dist = dist < 0 ? -dist : dist;
;                     const float v = (bval && dist <= 128) ? sc[cb][j] * 0.125f - slope * (float)dist : -1e30f;
;                     sc[cb][j] = v; mx = fmaxf(mx, v); } }
	v_mfma_f32_16x16x32_bf16 v[14:17], v[156:159], v[180:183], v[236:239]
	v_mfma_f32_16x16x32_bf16 v[14:17], v[160:163], v[184:187], v[14:17]
	ds_read_b128 v[156:159], v164 offset:11520
	ds_read_b128 v[160:163], v164 offset:11584
	v_add_f32_e32 v90, v86, v174
	v_add_f32_e32 v91, v87, v174
	v_add_f32_e32 v92, v88, v174
	v_add_f32_e32 v93, v89, v174
	s_cmp_lt_i32 s47, 12
	s_cselect_b64 vcc, -1, s[10:11]
	s_cmp_lt_i32 s47, 4
	s_cselect_b64 vcc, s[6:7], vcc
	v_cndmask_b32_e32 v232, v252, v86, vcc
	v_cndmask_b32_e32 v233, v252, v87, vcc
	v_cndmask_b32_e32 v234, v252, v88, vcc
	v_cndmask_b32_e32 v235, v252, v89, vcc
	s_waitcnt lgkmcnt(2)
	v_mfma_f32_16x16x32_bf16 v[18:21], v[148:151], v[180:183], v[232:235]
	v_mfma_f32_16x16x32_bf16 v[18:21], v[152:155], v[184:187], v[18:21]
	ds_read_b128 v[148:151], v164 offset:13824
	ds_read_b128 v[152:155], v164 offset:13888
	v_add_f32_e32 v86, v90, v174
	v_add_f32_e32 v87, v91, v174
	v_add_f32_e32 v88, v92, v174
	v_add_f32_e32 v89, v93, v174
	s_cmp_lt_i32 s47, 11
	s_cselect_b64 vcc, -1, s[10:11]
	s_cmp_lt_i32 s47, 3
	s_cselect_b64 vcc, s[6:7], vcc
	v_cndmask_b32_e32 v236, v252, v90, vcc
	v_cndmask_b32_e32 v237, v252, v91, vcc
	v_cndmask_b32_e32 v238, v252, v92, vcc
	v_cndmask_b32_e32 v239, v252, v93, vcc
	s_waitcnt lgkmcnt(2)
	v_mfma_f32_16x16x32_bf16 v[22:25], v[156:159], v[180:183], v[236:239]
	v_mfma_f32_16x16x32_bf16 v[22:25], v[160:163], v[184:187], v[22:25]
	ds_read_b128 v[156:159], v164 offset:16128
	ds_read_b128 v[160:163], v164 offset:16192
	v_add_f32_e32 v90, v86, v174
	v_add_f32_e32 v91, v87, v174
	v_add_f32_e32 v92, v88, v174
	v_add_f32_e32 v93, v89, v174
	s_cmp_lt_i32 s47, 10
	s_cselect_b64 vcc, -1, s[10:11]
	s_cmp_lt_i32 s47, 2
	s_cselect_b64 vcc, s[6:7], vcc
	v_cndmask_b32_e32 v232, v252, v86, vcc
	v_cndmask_b32_e32 v233, v252, v87, vcc
	v_cndmask_b32_e32 v234, v252, v88, vcc
	v_cndmask_b32_e32 v235, v252, v89, vcc
	s_waitcnt lgkmcnt(2)
	v_mfma_f32_16x16x32_bf16 v[26:29], v[148:151], v[180:183], v[232:235]
	v_mfma_f32_16x16x32_bf16 v[26:29], v[152:155], v[184:187], v[26:29]
	ds_read_b128 v[148:151], v164 offset:18432
	ds_read_b128 v[152:155], v164 offset:18496
	s_cmp_lt_i32 s47, 9
	s_cselect_b64 vcc, -1, s[10:11]
	s_cmp_lt_i32 s47, 1
	s_cselect_b64 vcc, s[6:7], vcc
	v_cndmask_b32_e32 v236, v252, v90, vcc
	v_cndmask_b32_e32 v237, v252, v91, vcc
	v_cndmask_b32_e32 v238, v252, v92, vcc
	v_cndmask_b32_e32 v239, v252, v93, vcc
	s_waitcnt lgkmcnt(2)
	v_mfma_f32_16x16x32_bf16 v[30:33], v[156:159], v[180:183], v[236:239]
	v_mfma_f32_16x16x32_bf16 v[30:33], v[160:163], v[184:187], v[30:33]
	ds_read_b128 v[156:159], v164 offset:20736
	ds_read_b128 v[160:163], v164 offset:20800
	v_sub_f32_e64 v86, -v94, v174
	v_sub_f32_e64 v87, -v95, v174
	v_sub_f32_e64 v88, -v96, v174
	v_sub_f32_e64 v89, -v97, v174
	s_waitcnt lgkmcnt(2)
	v_mfma_f32_16x16x32_bf16 v[34:37], v[148:151], v[180:183], v[98:101]
	v_mfma_f32_16x16x32_bf16 v[34:37], v[152:155], v[184:187], v[34:37]
	ds_read_b128 v[148:151], v164 offset:23040
	ds_read_b128 v[152:155], v164 offset:23104
	v_sub_f32_e32 v90, v86, v174
	v_sub_f32_e32 v91, v87, v174
	v_sub_f32_e32 v92, v88, v174
	v_sub_f32_e32 v93, v89, v174
	s_waitcnt lgkmcnt(2)
	v_mfma_f32_16x16x32_bf16 v[38:41], v[156:159], v[180:183], v[86:89]
	v_mfma_f32_16x16x32_bf16 v[38:41], v[160:163], v[184:187], v[38:41]
	ds_read_b128 v[156:159], v164 offset:25344
	ds_read_b128 v[160:163], v164 offset:25408
	v_sub_f32_e32 v86, v90, v174
	v_sub_f32_e32 v87, v91, v174
	v_sub_f32_e32 v88, v92, v174
	v_sub_f32_e32 v89, v93, v174
	s_waitcnt lgkmcnt(2)
	v_mfma_f32_16x16x32_bf16 v[42:45], v[148:151], v[180:183], v[90:93]
	v_mfma_f32_16x16x32_bf16 v[42:45], v[152:155], v[184:187], v[42:45]
	ds_read_b128 v[148:151], v164 offset:27648
	ds_read_b128 v[152:155], v164 offset:27712
	v_sub_f32_e32 v90, v86, v174
	v_sub_f32_e32 v91, v87, v174
	v_sub_f32_e32 v92, v88, v174
	v_sub_f32_e32 v93, v89, v174
	s_waitcnt lgkmcnt(2)
	v_mfma_f32_16x16x32_bf16 v[46:49], v[156:159], v[180:183], v[86:89]
	v_mfma_f32_16x16x32_bf16 v[46:49], v[160:163], v[184:187], v[46:49]
	ds_read_b128 v[156:159], v164 offset:29952
	ds_read_b128 v[160:163], v164 offset:30016
	v_sub_f32_e32 v86, v90, v174
	v_sub_f32_e32 v87, v91, v174
	v_sub_f32_e32 v88, v92, v174
	v_sub_f32_e32 v89, v93, v174
	s_cmp_lt_i32 s47, 4
	s_cselect_b64 vcc, -1, s[10:11]
	s_cmp_lt_i32 s47, -4
	s_cselect_b64 vcc, s[6:7], vcc
	v_cndmask_b32_e32 v232, v252, v90, vcc
	v_cndmask_b32_e32 v233, v252, v91, vcc
	v_cndmask_b32_e32 v234, v252, v92, vcc
	v_cndmask_b32_e32 v235, v252, v93, vcc
	s_waitcnt lgkmcnt(2)
	v_mfma_f32_16x16x32_bf16 v[50:53], v[148:151], v[180:183], v[232:235]
	v_mfma_f32_16x16x32_bf16 v[50:53], v[152:155], v[184:187], v[50:53]
	ds_read_b128 v[148:151], v164 offset:32256
	ds_read_b128 v[152:155], v164 offset:32320
	v_sub_f32_e32 v90, v86, v174
	v_sub_f32_e32 v91, v87, v174
	v_sub_f32_e32 v92, v88, v174
	v_sub_f32_e32 v93, v89, v174
	s_cmp_lt_i32 s47, 3
	s_cselect_b64 vcc, -1, s[10:11]
	s_cmp_lt_i32 s47, -5
	s_cselect_b64 vcc, s[6:7], vcc
	v_cndmask_b32_e32 v236, v252, v86, vcc
	v_cndmask_b32_e32 v237, v252, v87, vcc
	v_cndmask_b32_e32 v238, v252, v88, vcc
	v_cndmask_b32_e32 v239, v252, v89, vcc
	s_waitcnt lgkmcnt(2)
	v_mfma_f32_16x16x32_bf16 v[54:57], v[156:159], v[180:183], v[236:239]
	v_mfma_f32_16x16x32_bf16 v[54:57], v[160:163], v[184:187], v[54:57]
	ds_read_b128 v[156:159], v164 offset:34560
	ds_read_b128 v[160:163], v164 offset:34624
	v_sub_f32_e32 v86, v90, v174
	v_sub_f32_e32 v87, v91, v174
	v_sub_f32_e32 v88, v92, v174
	v_sub_f32_e32 v89, v93, v174
	s_cmp_lt_i32 s47, 2
	s_cselect_b64 vcc, -1, s[10:11]
	s_cmp_lt_i32 s47, -6
	s_cselect_b64 vcc, s[6:7], vcc
	v_cndmask_b32_e32 v232, v252, v90, vcc
	v_cndmask_b32_e32 v233, v252, v91, vcc
	v_cndmask_b32_e32 v234, v252, v92, vcc
	v_cndmask_b32_e32 v235, v252, v93, vcc
	s_waitcnt lgkmcnt(2)
; __device__ void att_phase(int wv, const Params& p, unsigned char* lds) {
;     ...
;             float mx = sink;
; #pragma unroll
;             for (int cb = 0; cb < 24; ++cb) { const int kb = B - 1 + (cb >> 3); const bool bval = (kb >= sb && kb < se);
; #pragma unroll
;                 for (int j = 0; j < 4; ++j) { const int krel = 16 * cb + 4 * lq + j - 128;
;                     int dist = qrow - krel; dist = dist < 0 ? -dist : dist;
;                     const float v = (bval && dist <= 128) ? sc[cb][j] * 0.125f - slope * (float)dist : -1e30f;
;                     sc[cb][j] = v; mx = fmaxf(mx, v); } }
;             mx = fmaxf(mx, __shfl_xor(mx, 16)); mx = fmaxf(mx, __shfl_xor(mx, 32));
;             float sum = 0.f;
; #pragma unroll
;             for (int cb = 0; cb < 24; ++cb)
; #pragma unroll
;                 for (int j = 0; j < 4; ++j) { const float e = __expf(sc[cb][j] - mx); sc[cb][j] = e; sum += e; }
	v_mfma_f32_16x16x32_bf16 v[58:61], v[148:151], v[180:183], v[232:235]
	v_mfma_f32_16x16x32_bf16 v[58:61], v[152:155], v[184:187], v[58:61]
	ds_read_b128 v[148:151], v164 offset:36864
	ds_read_b128 v[152:155], v164 offset:36928
	v_sub_f32_e32 v90, v86, v174
	v_sub_f32_e32 v91, v87, v174
	v_sub_f32_e32 v92, v88, v174
	v_sub_f32_e32 v93, v89, v174
	v_cmp_le_i32_e32 vcc, 0, v108
	s_nop 1
	v_cndmask_b32_e32 v212, v252, v90, vcc
	v_cmp_le_i32_e32 vcc, 0, v110
	s_nop 1
	v_cndmask_b32_e32 v213, v252, v91, vcc
	v_cmp_le_i32_e32 vcc, 0, v111
	s_nop 1
	v_cndmask_b32_e32 v214, v252, v92, vcc
	v_cmp_le_i32_e32 vcc, 0, v177
	s_nop 1
	v_cndmask_b32_e32 v215, v252, v93, vcc
	s_cmp_lt_i32 s47, 1
	s_cselect_b64 vcc, -1, s[10:11]
	s_cmp_lt_i32 s47, -7
	s_cselect_b64 vcc, s[6:7], vcc
	v_cndmask_b32_e32 v236, v252, v86, vcc
	v_cndmask_b32_e32 v237, v252, v87, vcc
	v_cndmask_b32_e32 v238, v252, v88, vcc
	v_cndmask_b32_e32 v239, v252, v89, vcc
	s_waitcnt lgkmcnt(2)
	v_mfma_f32_16x16x32_bf16 v[62:65], v[156:159], v[180:183], v[236:239]
	v_mfma_f32_16x16x32_bf16 v[62:65], v[160:163], v[184:187], v[62:65]
	s_cmp_lt_i32 s47, 0
	s_cselect_b64 vcc, -1, s[10:11]
	s_cmp_lt_i32 s47, -8
	s_cselect_b64 vcc, s[6:7], vcc
	v_cndmask_b32_e32 v232, v252, v212, vcc
	v_cndmask_b32_e32 v233, v252, v213, vcc
	v_cndmask_b32_e32 v234, v252, v214, vcc
	v_cndmask_b32_e32 v235, v252, v215, vcc
	s_waitcnt lgkmcnt(0)
	v_mfma_f32_16x16x32_bf16 v[66:69], v[148:151], v[180:183], v[232:235]
	v_mfma_f32_16x16x32_bf16 v[66:69], v[152:155], v[184:187], v[66:69]
	ds_read2_b64 v[216:219], v165 offset0:0 offset1:4
	ds_read2_b64 v[220:223], v166 offset0:0 offset1:4
	ds_read2_b64 v[224:227], v167 offset0:0 offset1:4
	ds_read2_b64 v[228:231], v168 offset0:0 offset1:4
	v_max3_f32 v169, v2, v3, v4
	v_max3_f32 v172, v5, v6, v7
	v_max3_f32 v169, v8, v9, v169
	v_max3_f32 v172, v10, v11, v172
	v_max3_f32 v169, v12, v13, v169
	v_max3_f32 v172, v14, v15, v172
	v_max3_f32 v169, v16, v17, v169
	v_max3_f32 v172, v18, v19, v172
	v_max3_f32 v169, v20, v21, v169
	v_max3_f32 v172, v22, v23, v172
	v_max3_f32 v169, v24, v25, v169
	v_max3_f32 v172, v26, v27, v172
	v_max3_f32 v169, v28, v29, v169
	v_max3_f32 v172, v30, v31, v172
	v_max3_f32 v169, v32, v33, v169
	v_max3_f32 v172, v34, v35, v172
	v_max3_f32 v169, v36, v37, v169
	v_max3_f32 v172, v38, v39, v172
	v_max3_f32 v169, v40, v41, v169
	v_max3_f32 v172, v42, v43, v172
	v_max3_f32 v169, v44, v45, v169
	v_max3_f32 v172, v46, v47, v172
	v_max3_f32 v169, v48, v49, v169
	v_max3_f32 v172, v50, v51, v172
	v_max3_f32 v169, v52, v53, v169
	v_max3_f32 v172, v54, v55, v172
	v_max3_f32 v169, v56, v57, v169
	v_max3_f32 v172, v58, v59, v172
	v_max3_f32 v169, v60, v61, v169
	v_max3_f32 v172, v62, v63, v172
	v_max3_f32 v169, v64, v65, v169
	v_max3_f32 v172, v66, v67, v172
	v_max3_f32 v169, v68, v69, v169
	v_max_f32_e32 v169, v169, v172
	v_mul_f32_e32 v169, 0x3e000000, v169
	s_waitcnt vmcnt(0)
	v_max_f32_e32 v169, v169, v146
	ds_bpermute_b32 v172, v1, v169
	s_waitcnt lgkmcnt(0)
	v_max_f32_e32 v169, v169, v172
	ds_bpermute_b32 v172, v114, v169
	s_waitcnt lgkmcnt(0)
	v_max_f32_e32 v169, v169, v172
	v_mul_f32_e32 v175, 0xbfb8aa3b, v169
	v_mov_b32_e32 v170, 0
	v_mov_b32_e32 v171, 0
	v_fma_f32 v2, v2, s46, v175
	v_fma_f32 v3, v3, s46, v175
	v_fma_f32 v4, v4, s46, v175
	v_fma_f32 v5, v5, s46, v175
	v_exp_f32_e32 v2, v2
	v_exp_f32_e32 v3, v3
	v_exp_f32_e32 v4, v4
	v_exp_f32_e32 v5, v5
	v_fma_f32 v6, v6, s46, v175
	v_fma_f32 v7, v7, s46, v175
	v_fma_f32 v8, v8, s46, v175
	v_fma_f32 v9, v9, s46, v175
	v_exp_f32_e32 v6, v6
	v_exp_f32_e32 v7, v7
	v_exp_f32_e32 v8, v8
	v_exp_f32_e32 v9, v9
	v_add_f32_e32 v171, v171, v2
	v_add_f32_e32 v170, v170, v3
	v_add_f32_e32 v171, v171, v4
	v_add_f32_e32 v170, v170, v5
	v_fma_f32 v10, v10, s46, v175
	v_fma_f32 v11, v11, s46, v175
	v_fma_f32 v12, v12, s46, v175
	v_fma_f32 v13, v13, s46, v175
	v_exp_f32_e32 v10, v10
	v_exp_f32_e32 v11, v11
	v_exp_f32_e32 v12, v12
	v_exp_f32_e32 v13, v13
	v_add_f32_e32 v171, v171, v6
	v_add_f32_e32 v170, v170, v7
	v_add_f32_e32 v171, v171, v8
	v_add_f32_e32 v170, v170, v9
	v_fma_f32 v14, v14, s46, v175
	v_fma_f32 v15, v15, s46, v175
	v_fma_f32 v16, v16, s46, v175
	v_fma_f32 v17, v17, s46, v175
	v_exp_f32_e32 v14, v14
	v_exp_f32_e32 v15, v15
	v_exp_f32_e32 v16, v16
	v_exp_f32_e32 v17, v17
	v_add_f32_e32 v171, v171, v10
	v_add_f32_e32 v170, v170, v11
	v_add_f32_e32 v171, v171, v12
	v_add_f32_e32 v170, v170, v13
	v_fma_f32 v18, v18, s46, v175
	v_fma_f32 v19, v19, s46, v175
	v_fma_f32 v20, v20, s46, v175
	v_fma_f32 v21, v21, s46, v175
	v_exp_f32_e32 v18, v18
	v_exp_f32_e32 v19, v19
	v_exp_f32_e32 v20, v20
	v_exp_f32_e32 v21, v21
	v_add_f32_e32 v171, v171, v14
	v_add_f32_e32 v170, v170, v15
	v_add_f32_e32 v171, v171, v16
	v_add_f32_e32 v170, v170, v17
	v_fma_f32 v22, v22, s46, v175
	v_fma_f32 v23, v23, s46, v175
	v_fma_f32 v24, v24, s46, v175
	v_fma_f32 v25, v25, s46, v175
	v_exp_f32_e32 v22, v22
	v_exp_f32_e32 v23, v23
	v_exp_f32_e32 v24, v24
	v_exp_f32_e32 v25, v25
	v_add_f32_e32 v171, v171, v18
	v_add_f32_e32 v170, v170, v19
	v_add_f32_e32 v171, v171, v20
	v_add_f32_e32 v170, v170, v21
	v_fma_f32 v26, v26, s46, v175
	v_fma_f32 v27, v27, s46, v175
	v_fma_f32 v28, v28, s46, v175
	v_fma_f32 v29, v29, s46, v175
	v_exp_f32_e32 v26, v26
	v_exp_f32_e32 v27, v27
	v_exp_f32_e32 v28, v28
	v_exp_f32_e32 v29, v29
	v_add_f32_e32 v171, v171, v22
	v_add_f32_e32 v170, v170, v23
	v_add_f32_e32 v171, v171, v24
	v_add_f32_e32 v170, v170, v25
	v_fma_f32 v30, v30, s46, v175
	v_fma_f32 v31, v31, s46, v175
	v_fma_f32 v32, v32, s46, v175
	v_fma_f32 v33, v33, s46, v175
	v_exp_f32_e32 v30, v30
	v_exp_f32_e32 v31, v31
	v_exp_f32_e32 v32, v32
; __device__ __forceinline__ unsigned cvt_pk_bf16_asm(float lo, float hi) { unsigned r; asm volatile("v_cvt_pk_bf16_f32 %0, %1, %2" : "=v"(r) : "v"(lo), "v"(hi)); return r; }
; __device__ __forceinline__ f32x4 mfma16(bf16x8 a, bf16x8 b, f32x4 c) { return __builtin_amdgcn_mfma_f32_16x16x32_bf16(a, b, c, 0, 0, 0); }
; __device__ void att_phase(int wv, const Params& p, unsigned char* lds) {
;     ...
;             float sum = 0.f;
; #pragma unroll
;             for (int cb = 0; cb < 24; ++cb)
; #pragma unroll
;                 for (int j = 0; j < 4; ++j) { const float e = __expf(sc[cb][j] - mx); sc[cb][j] = e; sum += e; }
;             sum += __shfl_xor(sum, 16); sum += __shfl_xor(sum, 32);
;             sum += __expf(sink - mx);
;             const float inv = 1.0f / sum;
;             f32x4 oa[4];
; #pragma unroll
;             for (int db = 0; db < 4; ++db) oa[db] = (f32x4){0, 0, 0, 0};
; #pragma unroll
;             for (int ks = 0; ks < 12; ++ks) {
;                 union { bf16x8 v; unsigned u[4]; } pf;
;                 pf.u[0] = cvt_pk_bf16_asm(sc[2 * ks][0], sc[2 * ks][1]); pf.u[1] = cvt_pk_bf16_asm(sc[2 * ks][2], sc[2 * ks][3]);
;                 pf.u[2] = cvt_pk_bf16_asm(sc[2 * ks + 1][0], sc[2 * ks + 1][1]); pf.u[3] = cvt_pk_bf16_asm(sc[2 * ks + 1][2], sc[2 * ks + 1][3]);
; #pragma unroll
;                 for (int db = 0; db < 4; ++db) {
;                     union { bf16x8 v; u32x2 h2[2]; } vf;
;                     const bf16_t* vp = VTL + (16 * db + lr) * VP + 32 * ks + 4 * lq;
;                     vf.h2[0] = *(const u32x2*)vp; vf.h2[1] = *(const u32x2*)(vp + 16);
;                     oa[db] = mfma16(vf.v, pf.v, oa[db]); } }
	v_exp_f32_e32 v33, v33
	v_add_f32_e32 v171, v171, v26
	v_add_f32_e32 v170, v170, v27
	v_add_f32_e32 v171, v171, v28
	v_add_f32_e32 v170, v170, v29
	v_fma_f32 v34, v34, s46, v175
	v_fma_f32 v35, v35, s46, v175
	v_fma_f32 v36, v36, s46, v175
	v_fma_f32 v37, v37, s46, v175
	v_exp_f32_e32 v34, v34
	v_exp_f32_e32 v35, v35
	v_exp_f32_e32 v36, v36
	v_exp_f32_e32 v37, v37
	v_add_f32_e32 v171, v171, v30
	v_add_f32_e32 v170, v170, v31
	v_add_f32_e32 v171, v171, v32
	v_add_f32_e32 v170, v170, v33
	v_fma_f32 v38, v38, s46, v175
	v_fma_f32 v39, v39, s46, v175
	v_fma_f32 v40, v40, s46, v175
	v_fma_f32 v41, v41, s46, v175
	v_exp_f32_e32 v38, v38
	v_exp_f32_e32 v39, v39
	v_exp_f32_e32 v40, v40
	v_exp_f32_e32 v41, v41
	v_add_f32_e32 v171, v171, v34
	v_add_f32_e32 v170, v170, v35
	v_add_f32_e32 v171, v171, v36
	v_add_f32_e32 v170, v170, v37
	v_fma_f32 v42, v42, s46, v175
	v_fma_f32 v43, v43, s46, v175
	v_fma_f32 v44, v44, s46, v175
	v_fma_f32 v45, v45, s46, v175
	v_exp_f32_e32 v42, v42
	v_exp_f32_e32 v43, v43
	v_exp_f32_e32 v44, v44
	v_exp_f32_e32 v45, v45
	v_add_f32_e32 v171, v171, v38
	v_add_f32_e32 v170, v170, v39
	v_add_f32_e32 v171, v171, v40
	v_add_f32_e32 v170, v170, v41
	v_fma_f32 v46, v46, s46, v175
	v_fma_f32 v47, v47, s46, v175
	v_fma_f32 v48, v48, s46, v175
	v_fma_f32 v49, v49, s46, v175
	v_exp_f32_e32 v46, v46
	v_exp_f32_e32 v47, v47
	v_exp_f32_e32 v48, v48
	v_exp_f32_e32 v49, v49
	v_add_f32_e32 v171, v171, v42
	v_add_f32_e32 v170, v170, v43
	v_add_f32_e32 v171, v171, v44
	v_add_f32_e32 v170, v170, v45
	v_fma_f32 v50, v50, s46, v175
	v_fma_f32 v51, v51, s46, v175
	v_fma_f32 v52, v52, s46, v175
	v_fma_f32 v53, v53, s46, v175
	v_exp_f32_e32 v50, v50
	v_exp_f32_e32 v51, v51
	v_exp_f32_e32 v52, v52
	v_exp_f32_e32 v53, v53
	v_add_f32_e32 v171, v171, v46
	v_add_f32_e32 v170, v170, v47
	v_add_f32_e32 v171, v171, v48
	v_add_f32_e32 v170, v170, v49
	v_fma_f32 v54, v54, s46, v175
	v_fma_f32 v55, v55, s46, v175
	v_fma_f32 v56, v56, s46, v175
	v_fma_f32 v57, v57, s46, v175
	v_exp_f32_e32 v54, v54
	v_exp_f32_e32 v55, v55
	v_exp_f32_e32 v56, v56
	v_exp_f32_e32 v57, v57
	v_add_f32_e32 v171, v171, v50
	v_add_f32_e32 v170, v170, v51
	v_add_f32_e32 v171, v171, v52
	v_add_f32_e32 v170, v170, v53
	v_fma_f32 v58, v58, s46, v175
	v_fma_f32 v59, v59, s46, v175
	v_fma_f32 v60, v60, s46, v175
	v_fma_f32 v61, v61, s46, v175
	v_exp_f32_e32 v58, v58
	v_exp_f32_e32 v59, v59
	v_exp_f32_e32 v60, v60
	v_exp_f32_e32 v61, v61
	v_add_f32_e32 v171, v171, v54
	v_add_f32_e32 v170, v170, v55
	v_add_f32_e32 v171, v171, v56
	v_add_f32_e32 v170, v170, v57
	v_fma_f32 v62, v62, s46, v175
	v_fma_f32 v63, v63, s46, v175
	v_fma_f32 v64, v64, s46, v175
	v_fma_f32 v65, v65, s46, v175
	v_exp_f32_e32 v62, v62
	v_exp_f32_e32 v63, v63
	v_exp_f32_e32 v64, v64
	v_exp_f32_e32 v65, v65
	v_add_f32_e32 v171, v171, v58
	v_add_f32_e32 v170, v170, v59
	v_add_f32_e32 v171, v171, v60
	v_add_f32_e32 v170, v170, v61
	v_fma_f32 v66, v66, s46, v175
	v_fma_f32 v67, v67, s46, v175
	v_fma_f32 v68, v68, s46, v175
	v_fma_f32 v69, v69, s46, v175
	v_exp_f32_e32 v66, v66
	v_exp_f32_e32 v67, v67
	v_exp_f32_e32 v68, v68
	v_exp_f32_e32 v69, v69
	v_add_f32_e32 v171, v171, v62
	v_add_f32_e32 v170, v170, v63
	v_add_f32_e32 v171, v171, v64
	v_add_f32_e32 v170, v170, v65
	v_add_f32_e32 v171, v171, v66
	v_add_f32_e32 v170, v170, v67
	v_add_f32_e32 v171, v171, v68
	v_add_f32_e32 v170, v170, v69
	v_add_f32_e32 v170, v170, v171
	v_cvt_pk_bf16_f32 v2, v2, v3
	v_cvt_pk_bf16_f32 v3, v4, v5
	v_cvt_pk_bf16_f32 v4, v6, v7
	v_cvt_pk_bf16_f32 v5, v8, v9
	v_cvt_pk_bf16_f32 v10, v10, v11
	v_cvt_pk_bf16_f32 v11, v12, v13
	v_cvt_pk_bf16_f32 v12, v14, v15
	v_cvt_pk_bf16_f32 v13, v16, v17
	v_cvt_pk_bf16_f32 v18, v18, v19
	v_cvt_pk_bf16_f32 v19, v20, v21
	v_cvt_pk_bf16_f32 v20, v22, v23
	v_cvt_pk_bf16_f32 v21, v24, v25
	v_cvt_pk_bf16_f32 v26, v26, v27
	v_cvt_pk_bf16_f32 v27, v28, v29
	v_cvt_pk_bf16_f32 v28, v30, v31
	v_cvt_pk_bf16_f32 v29, v32, v33
	v_cvt_pk_bf16_f32 v34, v34, v35
	v_cvt_pk_bf16_f32 v35, v36, v37
	v_cvt_pk_bf16_f32 v36, v38, v39
	v_cvt_pk_bf16_f32 v37, v40, v41
	v_cvt_pk_bf16_f32 v42, v42, v43
	v_cvt_pk_bf16_f32 v43, v44, v45
	v_cvt_pk_bf16_f32 v44, v46, v47
	v_cvt_pk_bf16_f32 v45, v48, v49
	v_cvt_pk_bf16_f32 v50, v50, v51
	v_cvt_pk_bf16_f32 v51, v52, v53
	v_cvt_pk_bf16_f32 v52, v54, v55
	v_cvt_pk_bf16_f32 v53, v56, v57
	v_cvt_pk_bf16_f32 v58, v58, v59
	v_cvt_pk_bf16_f32 v59, v60, v61
	v_cvt_pk_bf16_f32 v60, v62, v63
	v_cvt_pk_bf16_f32 v61, v64, v65
	v_cvt_pk_bf16_f32 v66, v66, v67
	v_cvt_pk_bf16_f32 v67, v68, v69
	v_mov_b32_e32 v68, 0
	v_mov_b32_e32 v69, 0
	ds_bpermute_b32 v172, v1, v170
	v_sub_f32_e32 v173, v146, v169
	v_mul_f32_e32 v173, 0x3fb8aa3b, v173
	v_exp_f32_e32 v173, v173
	s_waitcnt lgkmcnt(0)
	v_add_f32_e32 v170, v170, v172
	ds_bpermute_b32 v172, v114, v170
	ds_read2_b64 v[232:235], v165 offset0:8 offset1:12
	ds_read2_b64 v[236:239], v166 offset0:8 offset1:12
	ds_read2_b64 v[240:243], v167 offset0:8 offset1:12
	ds_read2_b64 v[244:247], v168 offset0:8 offset1:12
	s_waitcnt lgkmcnt(4)
	v_mfma_f32_16x16x32_bf16 v[70:73], v[216:219], v[2:5], 0
	v_mfma_f32_16x16x32_bf16 v[74:77], v[220:223], v[2:5], 0
	v_mfma_f32_16x16x32_bf16 v[78:81], v[224:227], v[2:5], 0
	v_mfma_f32_16x16x32_bf16 v[82:85], v[228:231], v[2:5], 0
	v_add_f32_e32 v170, v170, v172
	v_add_f32_e32 v170, v170, v173
	v_rcp_f32_e32 v147, v170
	s_nop 0
	v_fma_f32 v179, -v170, v147, 1.0
	v_fmac_f32_e32 v147, v179, v147
	ds_read2_b64 v[216:219], v165 offset0:16 offset1:20
	ds_read2_b64 v[220:223], v166 offset0:16 offset1:20
	ds_read2_b64 v[224:227], v167 offset0:16 offset1:20
	ds_read2_b64 v[228:231], v168 offset0:16 offset1:20
	s_waitcnt lgkmcnt(4)
; __device__ __forceinline__ unsigned cvt_pk_bf16_asm(float lo, float hi) { unsigned r; asm volatile("v_cvt_pk_bf16_f32 %0, %1, %2" : "=v"(r) : "v"(lo), "v"(hi)); return r; }
; __device__ __forceinline__ f32x4 mfma16(bf16x8 a, bf16x8 b, f32x4 c) { return __builtin_amdgcn_mfma_f32_16x16x32_bf16(a, b, c, 0, 0, 0); }
; __device__ void att_phase(int wv, const Params& p, unsigned char* lds) {
;     ...
;         for (int rb = 0; rb < 4; ++rb) {
;             const int qrow = 64 * (w & 1) + 16 * rb + lr;
;             const size_t tokq = (size_t)B * 128 + qrow;
;             bf16x8 qf[2];
; #pragma unroll
;             for (int kk = 0; kk < 2; ++kk) qf[kk] = *(const bf16x8*)(qkv + tokq * 1536 + 64 * h + 32 * kk + 8 * lq);
;             f32x4 sc[24];
; #pragma unroll
;             for (int cb = 0; cb < 24; ++cb) { f32x4 a = {0, 0, 0, 0};
; #pragma unroll
;                 for (int kk = 0; kk < 2; ++kk) { const bf16x8 kf = *(const bf16x8*)(KL + (16 * cb + lr) * KP + 32 * kk + 8 * lq); a = mfma16(kf, qf[kk], a); }
;                 sc[cb] = a; }
;             float mx = sink;
; #pragma unroll
;             for (int cb = 0; cb < 24; ++cb) { const int kb = B - 1 + (cb >> 3); const bool bval = (kb >= sb && kb < se);
; #pragma unroll
;                 for (int j = 0; j < 4; ++j) { const int krel = 16 * cb + 4 * lq + j - 128;
;                     int dist = qrow - krel; dist = dist < 0 ? -dist : dist;
;                     const float v = (bval && dist <= 128) ? sc[cb][j] * 0.125f - slope * (float)dist : -1e30f;
;                     sc[cb][j] = v; mx = fmaxf(mx, v); } }
;     ...
;                 for (int db = 0; db < 4; ++db) {
;                     union { bf16x8 v; u32x2 h2[2]; } vf;
;                     const bf16_t* vp = VTL + (16 * db + lr) * VP + 32 * ks + 4 * lq;
;                     vf.h2[0] = *(const u32x2*)vp; vf.h2[1] = *(const u32x2*)(vp + 16);
;                     oa[db] = mfma16(vf.v, pf.v, oa[db]); } }
; #pragma unroll
;             for (int db = 0; db < 4; ++db) { const f32x4 o = oa[db] * inv; u32x2 wv; wv.x = cvt_pk_bf16_asm(o[0], o[1]); wv.y = cvt_pk_bf16_asm(o[2], o[3]);
;                 *(u32x2*)(qkv + tokq * 1536 + 64 * h + 16 * db + 4 * lq) = wv; }
	v_mfma_f32_16x16x32_bf16 v[70:73], v[232:235], v[10:13], v[70:73]
	v_mfma_f32_16x16x32_bf16 v[74:77], v[236:239], v[10:13], v[74:77]
	v_mfma_f32_16x16x32_bf16 v[78:81], v[240:243], v[10:13], v[78:81]
	v_mfma_f32_16x16x32_bf16 v[82:85], v[244:247], v[10:13], v[82:85]
	ds_read2_b64 v[232:235], v165 offset0:24 offset1:28
	ds_read2_b64 v[236:239], v166 offset0:24 offset1:28
	ds_read2_b64 v[240:243], v167 offset0:24 offset1:28
	ds_read2_b64 v[244:247], v168 offset0:24 offset1:28
	s_waitcnt lgkmcnt(4)
	v_mfma_f32_16x16x32_bf16 v[70:73], v[216:219], v[18:21], v[70:73]
	v_mfma_f32_16x16x32_bf16 v[74:77], v[220:223], v[18:21], v[74:77]
	v_mfma_f32_16x16x32_bf16 v[78:81], v[224:227], v[18:21], v[78:81]
	v_mfma_f32_16x16x32_bf16 v[82:85], v[228:231], v[18:21], v[82:85]
	ds_read2_b64 v[216:219], v165 offset0:32 offset1:36
	ds_read2_b64 v[220:223], v166 offset0:32 offset1:36
	ds_read2_b64 v[224:227], v167 offset0:32 offset1:36
	ds_read2_b64 v[228:231], v168 offset0:32 offset1:36
	s_waitcnt lgkmcnt(4)
	v_mfma_f32_16x16x32_bf16 v[70:73], v[232:235], v[26:29], v[70:73]
	v_mfma_f32_16x16x32_bf16 v[74:77], v[236:239], v[26:29], v[74:77]
	v_mfma_f32_16x16x32_bf16 v[78:81], v[240:243], v[26:29], v[78:81]
	v_mfma_f32_16x16x32_bf16 v[82:85], v[244:247], v[26:29], v[82:85]
	ds_read2_b64 v[232:235], v165 offset0:40 offset1:44
	ds_read2_b64 v[236:239], v166 offset0:40 offset1:44
	ds_read2_b64 v[240:243], v167 offset0:40 offset1:44
	ds_read2_b64 v[244:247], v168 offset0:40 offset1:44
	s_waitcnt lgkmcnt(4)
	v_mfma_f32_16x16x32_bf16 v[70:73], v[216:219], v[34:37], v[70:73]
	v_mfma_f32_16x16x32_bf16 v[74:77], v[220:223], v[34:37], v[74:77]
	v_mfma_f32_16x16x32_bf16 v[78:81], v[224:227], v[34:37], v[78:81]
	v_mfma_f32_16x16x32_bf16 v[82:85], v[228:231], v[34:37], v[82:85]
	ds_read2_b64 v[216:219], v165 offset0:48 offset1:52
	ds_read2_b64 v[220:223], v166 offset0:48 offset1:52
	ds_read2_b64 v[224:227], v167 offset0:48 offset1:52
	ds_read2_b64 v[228:231], v168 offset0:48 offset1:52
	s_waitcnt lgkmcnt(4)
	v_mfma_f32_16x16x32_bf16 v[70:73], v[232:235], v[42:45], v[70:73]
	v_mfma_f32_16x16x32_bf16 v[74:77], v[236:239], v[42:45], v[74:77]
	v_mfma_f32_16x16x32_bf16 v[78:81], v[240:243], v[42:45], v[78:81]
	v_mfma_f32_16x16x32_bf16 v[82:85], v[244:247], v[42:45], v[82:85]
	ds_read2_b64 v[232:235], v165 offset0:56 offset1:60
	ds_read2_b64 v[236:239], v166 offset0:56 offset1:60
	ds_read2_b64 v[240:243], v167 offset0:56 offset1:60
	ds_read2_b64 v[244:247], v168 offset0:56 offset1:60
	s_waitcnt lgkmcnt(4)
	v_mfma_f32_16x16x32_bf16 v[70:73], v[216:219], v[50:53], v[70:73]
	v_mfma_f32_16x16x32_bf16 v[74:77], v[220:223], v[50:53], v[74:77]
	v_mfma_f32_16x16x32_bf16 v[78:81], v[224:227], v[50:53], v[78:81]
	v_mfma_f32_16x16x32_bf16 v[82:85], v[228:231], v[50:53], v[82:85]
	ds_read2_b64 v[216:219], v165 offset0:64 offset1:64
	ds_read2_b64 v[220:223], v166 offset0:64 offset1:64
	ds_read2_b64 v[224:227], v167 offset0:64 offset1:64
	ds_read2_b64 v[228:231], v168 offset0:64 offset1:64
	s_waitcnt lgkmcnt(4)
	v_mfma_f32_16x16x32_bf16 v[70:73], v[232:235], v[58:61], v[70:73]
	v_mfma_f32_16x16x32_bf16 v[74:77], v[236:239], v[58:61], v[74:77]
	v_mfma_f32_16x16x32_bf16 v[78:81], v[240:243], v[58:61], v[78:81]
	v_mfma_f32_16x16x32_bf16 v[82:85], v[244:247], v[58:61], v[82:85]
	s_waitcnt lgkmcnt(0)
	v_mfma_f32_16x16x32_bf16 v[70:73], v[216:219], v[66:69], v[70:73]
	v_mfma_f32_16x16x32_bf16 v[74:77], v[220:223], v[66:69], v[74:77]
	v_mfma_f32_16x16x32_bf16 v[78:81], v[224:227], v[66:69], v[78:81]
	v_mfma_f32_16x16x32_bf16 v[82:85], v[228:231], v[66:69], v[82:85]
	s_nop 7
	s_nop 1
	v_mul_f32_e32 v70, v70, v147
	v_mul_f32_e32 v71, v71, v147
	v_mul_f32_e32 v72, v72, v147
	v_mul_f32_e32 v73, v73, v147
	v_mul_f32_e32 v74, v74, v147
	v_mul_f32_e32 v75, v75, v147
	v_mul_f32_e32 v76, v76, v147
	v_mul_f32_e32 v77, v77, v147
	v_mul_f32_e32 v78, v78, v147
	v_mul_f32_e32 v79, v79, v147
	v_mul_f32_e32 v80, v80, v147
	v_mul_f32_e32 v81, v81, v147
	v_mul_f32_e32 v82, v82, v147
	v_mul_f32_e32 v83, v83, v147
	v_mul_f32_e32 v84, v84, v147
	v_mul_f32_e32 v85, v85, v147
	v_cvt_pk_bf16_f32 v70, v70, v71
	v_cvt_pk_bf16_f32 v71, v72, v73
	v_cvt_pk_bf16_f32 v74, v74, v75
	v_cvt_pk_bf16_f32 v75, v76, v77
	v_cvt_pk_bf16_f32 v78, v78, v79
	v_cvt_pk_bf16_f32 v79, v80, v81
	v_cvt_pk_bf16_f32 v82, v82, v83
	v_cvt_pk_bf16_f32 v83, v84, v85
	global_store_dwordx2 v[248:249], v[70:71], off offset:-64
	global_store_dwordx2 v[248:249], v[74:75], off offset:-32
	global_store_dwordx2 v[248:249], v[78:79], off
	global_store_dwordx2 v[248:249], v[82:83], off offset:32
	v_lshl_add_u64 v[248:249], v[248:249], 0, s[48:49]
	v_sub_f32_e32 v86, v94, v176
	v_sub_f32_e32 v87, v95, v176
	v_sub_f32_e32 v88, v96, v176
	v_sub_f32_e32 v89, v97, v176
	v_cmp_ge_i32_e32 vcc, 0, v108
	s_nop 1
	v_cndmask_b32_e32 v212, v252, v86, vcc
	v_cmp_ge_i32_e32 vcc, 0, v110
	s_nop 1
	v_cndmask_b32_e32 v213, v252, v87, vcc
	v_cmp_ge_i32_e32 vcc, 0, v111
	s_nop 1
	v_cndmask_b32_e32 v214, v252, v88, vcc
	v_cmp_ge_i32_e32 vcc, 0, v177
	s_nop 1
	v_cndmask_b32_e32 v215, v252, v89, vcc
	ds_read_b128 v[148:151], v164 offset:2304
	ds_read_b128 v[152:155], v164 offset:2368
	ds_read_b128 v[156:159], v164 offset:4608
	ds_read_b128 v[160:163], v164 offset:4672
	v_add_f32_e32 v90, v86, v174
	v_add_f32_e32 v91, v87, v174
	v_add_f32_e32 v92, v88, v174
	v_add_f32_e32 v93, v89, v174
	s_cmp_lt_i32 s47, 15
	s_cselect_b64 vcc, -1, s[10:11]
	s_cmp_lt_i32 s47, 7
	s_cselect_b64 vcc, s[6:7], vcc
	v_cndmask_b32_e32 v232, v252, v212, vcc
	v_cndmask_b32_e32 v233, v252, v213, vcc
	v_cndmask_b32_e32 v234, v252, v214, vcc
	v_cndmask_b32_e32 v235, v252, v215, vcc
	s_waitcnt lgkmcnt(2)
; __device__ __forceinline__ f32x4 mfma16(bf16x8 a, bf16x8 b, f32x4 c) { return __builtin_amdgcn_mfma_f32_16x16x32_bf16(a, b, c, 0, 0, 0); }
; __device__ void att_phase(int wv, const Params& p, unsigned char* lds) {
;     ...
; #pragma unroll
;             for (int cb = 0; cb < 24; ++cb) { f32x4 a = {0, 0, 0, 0};
; #pragma unroll
;                 for (int kk = 0; kk < 2; ++kk) { const bf16x8 kf = *(const bf16x8*)(KL + (16 * cb + lr) * KP + 32 * kk + 8 * lq); a = mfma16(kf, qf[kk], a); }
;                 sc[cb] = a; }
;             float mx = sink;
; #pragma unroll
;             for (int cb = 0; cb < 24; ++cb) { const int kb = B - 1 + (cb >> 3); const bool bval = (kb >= sb && kb < se);
; #pragma unroll
;                 for (int j = 0; j < 4; ++j) { const int krel = 16 * cb + 4 * lq + j - 128;
;                     int dist = qrow - krel; dist = dist < 0 ? -dist : dist;
;                     const float v = (bval && dist <= 128) ? sc[cb][j] * 0.125f - slope * (float)dist : -1e30f;
;                     sc[cb][j] = v; mx = fmaxf(mx, v); } }
	v_mfma_f32_16x16x32_bf16 v[2:5], v[148:151], v[188:191], v[232:235]
	v_mfma_f32_16x16x32_bf16 v[2:5], v[152:155], v[192:195], v[2:5]
	ds_read_b128 v[148:151], v164 offset:6912
	ds_read_b128 v[152:155], v164 offset:6976
	v_add_f32_e32 v86, v90, v174
	v_add_f32_e32 v87, v91, v174
	v_add_f32_e32 v88, v92, v174
	v_add_f32_e32 v89, v93, v174
	s_cmp_lt_i32 s47, 14
	s_cselect_b64 vcc, -1, s[10:11]
	s_cmp_lt_i32 s47, 6
	s_cselect_b64 vcc, s[6:7], vcc
	v_cndmask_b32_e32 v236, v252, v90, vcc
	v_cndmask_b32_e32 v237, v252, v91, vcc
	v_cndmask_b32_e32 v238, v252, v92, vcc
	v_cndmask_b32_e32 v239, v252, v93, vcc
	s_waitcnt lgkmcnt(2)
	v_mfma_f32_16x16x32_bf16 v[6:9], v[156:159], v[188:191], v[236:239]
	v_mfma_f32_16x16x32_bf16 v[6:9], v[160:163], v[192:195], v[6:9]
	ds_read_b128 v[156:159], v164 offset:9216
	ds_read_b128 v[160:163], v164 offset:9280
	v_add_f32_e32 v90, v86, v174
	v_add_f32_e32 v91, v87, v174
	v_add_f32_e32 v92, v88, v174
	v_add_f32_e32 v93, v89, v174
	s_cmp_lt_i32 s47, 13
	s_cselect_b64 vcc, -1, s[10:11]
	s_cmp_lt_i32 s47, 5
	s_cselect_b64 vcc, s[6:7], vcc
	v_cndmask_b32_e32 v232, v252, v86, vcc
	v_cndmask_b32_e32 v233, v252, v87, vcc
	v_cndmask_b32_e32 v234, v252, v88, vcc
	v_cndmask_b32_e32 v235, v252, v89, vcc
	s_waitcnt lgkmcnt(2)
	v_mfma_f32_16x16x32_bf16 v[10:13], v[148:151], v[188:191], v[232:235]
	v_mfma_f32_16x16x32_bf16 v[10:13], v[152:155], v[192:195], v[10:13]
	ds_read_b128 v[148:151], v164 offset:11520
	ds_read_b128 v[152:155], v164 offset:11584
	v_add_f32_e32 v86, v90, v174
	v_add_f32_e32 v87, v91, v174
	v_add_f32_e32 v88, v92, v174
	v_add_f32_e32 v89, v93, v174
	s_cmp_lt_i32 s47, 12
	s_cselect_b64 vcc, -1, s[10:11]
	s_cmp_lt_i32 s47, 4
	s_cselect_b64 vcc, s[6:7], vcc
	v_cndmask_b32_e32 v236, v252, v90, vcc
	v_cndmask_b32_e32 v237, v252, v91, vcc
	v_cndmask_b32_e32 v238, v252, v92, vcc
	v_cndmask_b32_e32 v239, v252, v93, vcc
	s_waitcnt lgkmcnt(2)
	v_mfma_f32_16x16x32_bf16 v[14:17], v[156:159], v[188:191], v[236:239]
	v_mfma_f32_16x16x32_bf16 v[14:17], v[160:163], v[192:195], v[14:17]
	ds_read_b128 v[156:159], v164 offset:13824
	ds_read_b128 v[160:163], v164 offset:13888
	v_add_f32_e32 v90, v86, v174
	v_add_f32_e32 v91, v87, v174
	v_add_f32_e32 v92, v88, v174
	v_add_f32_e32 v93, v89, v174
	s_cmp_lt_i32 s47, 11
	s_cselect_b64 vcc, -1, s[10:11]
	s_cmp_lt_i32 s47, 3
	s_cselect_b64 vcc, s[6:7], vcc
	v_cndmask_b32_e32 v232, v252, v86, vcc
	v_cndmask_b32_e32 v233, v252, v87, vcc
	v_cndmask_b32_e32 v234, v252, v88, vcc
	v_cndmask_b32_e32 v235, v252, v89, vcc
	s_waitcnt lgkmcnt(2)
	v_mfma_f32_16x16x32_bf16 v[18:21], v[148:151], v[188:191], v[232:235]
	v_mfma_f32_16x16x32_bf16 v[18:21], v[152:155], v[192:195], v[18:21]
	ds_read_b128 v[148:151], v164 offset:16128
	ds_read_b128 v[152:155], v164 offset:16192
	v_add_f32_e32 v86, v90, v174
	v_add_f32_e32 v87, v91, v174
	v_add_f32_e32 v88, v92, v174
	v_add_f32_e32 v89, v93, v174
	s_cmp_lt_i32 s47, 10
	s_cselect_b64 vcc, -1, s[10:11]
	s_cmp_lt_i32 s47, 2
	s_cselect_b64 vcc, s[6:7], vcc
	v_cndmask_b32_e32 v236, v252, v90, vcc
	v_cndmask_b32_e32 v237, v252, v91, vcc
	v_cndmask_b32_e32 v238, v252, v92, vcc
	v_cndmask_b32_e32 v239, v252, v93, vcc
	s_waitcnt lgkmcnt(2)
	v_mfma_f32_16x16x32_bf16 v[22:25], v[156:159], v[188:191], v[236:239]
	v_mfma_f32_16x16x32_bf16 v[22:25], v[160:163], v[192:195], v[22:25]
	ds_read_b128 v[156:159], v164 offset:18432
	ds_read_b128 v[160:163], v164 offset:18496
	v_add_f32_e32 v90, v86, v174
	v_add_f32_e32 v91, v87, v174
	v_add_f32_e32 v92, v88, v174
	v_add_f32_e32 v93, v89, v174
	s_cmp_lt_i32 s47, 9
	s_cselect_b64 vcc, -1, s[10:11]
	s_cmp_lt_i32 s47, 1
	s_cselect_b64 vcc, s[6:7], vcc
	v_cndmask_b32_e32 v232, v252, v86, vcc
	v_cndmask_b32_e32 v233, v252, v87, vcc
	v_cndmask_b32_e32 v234, v252, v88, vcc
	v_cndmask_b32_e32 v235, v252, v89, vcc
	s_waitcnt lgkmcnt(2)
	v_mfma_f32_16x16x32_bf16 v[26:29], v[148:151], v[188:191], v[232:235]
	v_mfma_f32_16x16x32_bf16 v[26:29], v[152:155], v[192:195], v[26:29]
	ds_read_b128 v[148:151], v164 offset:20736
	ds_read_b128 v[152:155], v164 offset:20800
	s_waitcnt lgkmcnt(2)
	v_mfma_f32_16x16x32_bf16 v[30:33], v[156:159], v[188:191], v[90:93]
	v_mfma_f32_16x16x32_bf16 v[30:33], v[160:163], v[192:195], v[30:33]
	ds_read_b128 v[156:159], v164 offset:23040
	ds_read_b128 v[160:163], v164 offset:23104
	v_sub_f32_e64 v86, -v94, v174
	v_sub_f32_e64 v87, -v95, v174
	v_sub_f32_e64 v88, -v96, v174
	v_sub_f32_e64 v89, -v97, v174
	s_waitcnt lgkmcnt(2)
	v_mfma_f32_16x16x32_bf16 v[34:37], v[148:151], v[188:191], v[98:101]
	v_mfma_f32_16x16x32_bf16 v[34:37], v[152:155], v[192:195], v[34:37]
	ds_read_b128 v[148:151], v164 offset:25344
	ds_read_b128 v[152:155], v164 offset:25408
	v_sub_f32_e32 v90, v86, v174
	v_sub_f32_e32 v91, v87, v174
	v_sub_f32_e32 v92, v88, v174
	v_sub_f32_e32 v93, v89, v174
	s_waitcnt lgkmcnt(2)
	v_mfma_f32_16x16x32_bf16 v[38:41], v[156:159], v[188:191], v[86:89]
	v_mfma_f32_16x16x32_bf16 v[38:41], v[160:163], v[192:195], v[38:41]
	ds_read_b128 v[156:159], v164 offset:27648
	ds_read_b128 v[160:163], v164 offset:27712
	v_sub_f32_e32 v86, v90, v174
	v_sub_f32_e32 v87, v91, v174
	v_sub_f32_e32 v88, v92, v174
	v_sub_f32_e32 v89, v93, v174
	s_waitcnt lgkmcnt(2)
	v_mfma_f32_16x16x32_bf16 v[42:45], v[148:151], v[188:191], v[90:93]
	v_mfma_f32_16x16x32_bf16 v[42:45], v[152:155], v[192:195], v[42:45]
	ds_read_b128 v[148:151], v164 offset:29952
	ds_read_b128 v[152:155], v164 offset:30016
	v_sub_f32_e32 v90, v86, v174
	v_sub_f32_e32 v91, v87, v174
	v_sub_f32_e32 v92, v88, v174
	v_sub_f32_e32 v93, v89, v174
	s_cmp_lt_i32 s47, 4
	s_cselect_b64 vcc, -1, s[10:11]
	s_cmp_lt_i32 s47, -4
	s_cselect_b64 vcc, s[6:7], vcc
	v_cndmask_b32_e32 v236, v252, v86, vcc
	v_cndmask_b32_e32 v237, v252, v87, vcc
	v_cndmask_b32_e32 v238, v252, v88, vcc
	v_cndmask_b32_e32 v239, v252, v89, vcc
	s_waitcnt lgkmcnt(2)
; __device__ __forceinline__ f32x4 mfma16(bf16x8 a, bf16x8 b, f32x4 c) { return __builtin_amdgcn_mfma_f32_16x16x32_bf16(a, b, c, 0, 0, 0); }
; __device__ void att_phase(int wv, const Params& p, unsigned char* lds) {
;     ...
;             for (int cb = 0; cb < 24; ++cb) { f32x4 a = {0, 0, 0, 0};
; #pragma unroll
;                 for (int kk = 0; kk < 2; ++kk) { const bf16x8 kf = *(const bf16x8*)(KL + (16 * cb + lr) * KP + 32 * kk + 8 * lq); a = mfma16(kf, qf[kk], a); }
;                 sc[cb] = a; }
;             float mx = sink;
; #pragma unroll
;             for (int cb = 0; cb < 24; ++cb) { const int kb = B - 1 + (cb >> 3); const bool bval = (kb >= sb && kb < se);
; #pragma unroll
;                 for (int j = 0; j < 4; ++j) { const int krel = 16 * cb + 4 * lq + j - 128;
;                     int dist = qrow - krel; dist = dist < 0 ? -dist : dist;
;                     const float v = (bval && dist <= 128) ? sc[cb][j] * 0.125f - slope * (float)dist : -1e30f;
;                     sc[cb][j] = v; mx = fmaxf(mx, v); } }
;             mx = fmaxf(mx, __shfl_xor(mx, 16)); mx = fmaxf(mx, __shfl_xor(mx, 32));
	v_mfma_f32_16x16x32_bf16 v[46:49], v[156:159], v[188:191], v[236:239]
	v_mfma_f32_16x16x32_bf16 v[46:49], v[160:163], v[192:195], v[46:49]
	ds_read_b128 v[156:159], v164 offset:32256
	ds_read_b128 v[160:163], v164 offset:32320
	v_sub_f32_e32 v86, v90, v174
	v_sub_f32_e32 v87, v91, v174
	v_sub_f32_e32 v88, v92, v174
	v_sub_f32_e32 v89, v93, v174
	s_cmp_lt_i32 s47, 3
	s_cselect_b64 vcc, -1, s[10:11]
	s_cmp_lt_i32 s47, -5
	s_cselect_b64 vcc, s[6:7], vcc
	v_cndmask_b32_e32 v232, v252, v90, vcc
	v_cndmask_b32_e32 v233, v252, v91, vcc
	v_cndmask_b32_e32 v234, v252, v92, vcc
	v_cndmask_b32_e32 v235, v252, v93, vcc
	s_waitcnt lgkmcnt(2)
	v_mfma_f32_16x16x32_bf16 v[50:53], v[148:151], v[188:191], v[232:235]
	v_mfma_f32_16x16x32_bf16 v[50:53], v[152:155], v[192:195], v[50:53]
	ds_read_b128 v[148:151], v164 offset:34560
	ds_read_b128 v[152:155], v164 offset:34624
	v_sub_f32_e32 v90, v86, v174
	v_sub_f32_e32 v91, v87, v174
	v_sub_f32_e32 v92, v88, v174
	v_sub_f32_e32 v93, v89, v174
	s_cmp_lt_i32 s47, 2
	s_cselect_b64 vcc, -1, s[10:11]
	s_cmp_lt_i32 s47, -6
	s_cselect_b64 vcc, s[6:7], vcc
	v_cndmask_b32_e32 v236, v252, v86, vcc
	v_cndmask_b32_e32 v237, v252, v87, vcc
	v_cndmask_b32_e32 v238, v252, v88, vcc
	v_cndmask_b32_e32 v239, v252, v89, vcc
	s_waitcnt lgkmcnt(2)
	v_mfma_f32_16x16x32_bf16 v[54:57], v[156:159], v[188:191], v[236:239]
	v_mfma_f32_16x16x32_bf16 v[54:57], v[160:163], v[192:195], v[54:57]
	ds_read_b128 v[156:159], v164 offset:36864
	ds_read_b128 v[160:163], v164 offset:36928
	v_sub_f32_e32 v86, v90, v174
	v_sub_f32_e32 v87, v91, v174
	v_sub_f32_e32 v88, v92, v174
	v_sub_f32_e32 v89, v93, v174
	s_cmp_lt_i32 s47, 1
	s_cselect_b64 vcc, -1, s[10:11]
	s_cmp_lt_i32 s47, -7
	s_cselect_b64 vcc, s[6:7], vcc
	v_cndmask_b32_e32 v232, v252, v90, vcc
	v_cndmask_b32_e32 v233, v252, v91, vcc
	v_cndmask_b32_e32 v234, v252, v92, vcc
	v_cndmask_b32_e32 v235, v252, v93, vcc
	s_waitcnt lgkmcnt(2)
	v_mfma_f32_16x16x32_bf16 v[58:61], v[148:151], v[188:191], v[232:235]
	v_mfma_f32_16x16x32_bf16 v[58:61], v[152:155], v[192:195], v[58:61]
	ds_read_b128 v[148:151], v164 offset:39168
	ds_read_b128 v[152:155], v164 offset:39232
	v_sub_f32_e32 v90, v86, v174
	v_sub_f32_e32 v91, v87, v174
	v_sub_f32_e32 v92, v88, v174
	v_sub_f32_e32 v93, v89, v174
	v_cmp_le_i32_e32 vcc, 0, v108
	s_nop 1
	v_cndmask_b32_e32 v212, v252, v90, vcc
	v_cmp_le_i32_e32 vcc, 0, v110
	s_nop 1
	v_cndmask_b32_e32 v213, v252, v91, vcc
	v_cmp_le_i32_e32 vcc, 0, v111
	s_nop 1
	v_cndmask_b32_e32 v214, v252, v92, vcc
	v_cmp_le_i32_e32 vcc, 0, v177
	s_nop 1
	v_cndmask_b32_e32 v215, v252, v93, vcc
	s_cmp_lt_i32 s47, 0
	s_cselect_b64 vcc, -1, s[10:11]
	s_cmp_lt_i32 s47, -8
	s_cselect_b64 vcc, s[6:7], vcc
	v_cndmask_b32_e32 v236, v252, v86, vcc
	v_cndmask_b32_e32 v237, v252, v87, vcc
	v_cndmask_b32_e32 v238, v252, v88, vcc
	v_cndmask_b32_e32 v239, v252, v89, vcc
	s_waitcnt lgkmcnt(2)
	v_mfma_f32_16x16x32_bf16 v[62:65], v[156:159], v[188:191], v[236:239]
	v_mfma_f32_16x16x32_bf16 v[62:65], v[160:163], v[192:195], v[62:65]
	s_cmp_lt_i32 s47, -1
	s_cselect_b64 vcc, -1, s[10:11]
	s_cmp_lt_i32 s47, -9
	s_cselect_b64 vcc, s[6:7], vcc
	v_cndmask_b32_e32 v232, v252, v212, vcc
	v_cndmask_b32_e32 v233, v252, v213, vcc
	v_cndmask_b32_e32 v234, v252, v214, vcc
	v_cndmask_b32_e32 v235, v252, v215, vcc
	s_waitcnt lgkmcnt(0)
	v_mfma_f32_16x16x32_bf16 v[66:69], v[148:151], v[188:191], v[232:235]
	v_mfma_f32_16x16x32_bf16 v[66:69], v[152:155], v[192:195], v[66:69]
	ds_read2_b64 v[216:219], v165 offset0:4 offset1:8
	ds_read2_b64 v[220:223], v166 offset0:4 offset1:8
	ds_read2_b64 v[224:227], v167 offset0:4 offset1:8
	ds_read2_b64 v[228:231], v168 offset0:4 offset1:8
	v_max3_f32 v169, v2, v3, v4
	v_max3_f32 v172, v5, v6, v7
	v_max3_f32 v169, v8, v9, v169
	v_max3_f32 v172, v10, v11, v172
	v_max3_f32 v169, v12, v13, v169
	v_max3_f32 v172, v14, v15, v172
	v_max3_f32 v169, v16, v17, v169
	v_max3_f32 v172, v18, v19, v172
	v_max3_f32 v169, v20, v21, v169
	v_max3_f32 v172, v22, v23, v172
	v_max3_f32 v169, v24, v25, v169
	v_max3_f32 v172, v26, v27, v172
	v_max3_f32 v169, v28, v29, v169
	v_max3_f32 v172, v30, v31, v172
	v_max3_f32 v169, v32, v33, v169
	v_max3_f32 v172, v34, v35, v172
	v_max3_f32 v169, v36, v37, v169
	v_max3_f32 v172, v38, v39, v172
	v_max3_f32 v169, v40, v41, v169
	v_max3_f32 v172, v42, v43, v172
	v_max3_f32 v169, v44, v45, v169
	v_max3_f32 v172, v46, v47, v172
	v_max3_f32 v169, v48, v49, v169
	v_max3_f32 v172, v50, v51, v172
	v_max3_f32 v169, v52, v53, v169
	v_max3_f32 v172, v54, v55, v172
	v_max3_f32 v169, v56, v57, v169
	v_max3_f32 v172, v58, v59, v172
	v_max3_f32 v169, v60, v61, v169
	v_max3_f32 v172, v62, v63, v172
	v_max3_f32 v169, v64, v65, v169
	v_max3_f32 v172, v66, v67, v172
	v_max3_f32 v169, v68, v69, v169
	v_max_f32_e32 v169, v169, v172
	v_mul_f32_e32 v169, 0x3e000000, v169
	v_max_f32_e32 v169, v169, v146
	ds_bpermute_b32 v172, v1, v169
	s_waitcnt lgkmcnt(0)
	v_max_f32_e32 v169, v169, v172
	ds_bpermute_b32 v172, v114, v169
	s_waitcnt lgkmcnt(0)
; __device__ void att_phase(int wv, const Params& p, unsigned char* lds) {
;     ...
;             mx = fmaxf(mx, __shfl_xor(mx, 16)); mx = fmaxf(mx, __shfl_xor(mx, 32));
;             float sum = 0.f;
; #pragma unroll
;             for (int cb = 0; cb < 24; ++cb)
; #pragma unroll
;                 for (int j = 0; j < 4; ++j) { const float e = __expf(sc[cb][j] - mx); sc[cb][j] = e; sum += e; }
	v_max_f32_e32 v169, v169, v172
	v_mul_f32_e32 v175, 0xbfb8aa3b, v169
	v_mov_b32_e32 v170, 0
	v_mov_b32_e32 v171, 0
	v_fma_f32 v2, v2, s46, v175
	v_fma_f32 v3, v3, s46, v175
	v_fma_f32 v4, v4, s46, v175
	v_fma_f32 v5, v5, s46, v175
	v_exp_f32_e32 v2, v2
	v_exp_f32_e32 v3, v3
	v_exp_f32_e32 v4, v4
	v_exp_f32_e32 v5, v5
	v_fma_f32 v6, v6, s46, v175
	v_fma_f32 v7, v7, s46, v175
	v_fma_f32 v8, v8, s46, v175
	v_fma_f32 v9, v9, s46, v175
	v_exp_f32_e32 v6, v6
	v_exp_f32_e32 v7, v7
	v_exp_f32_e32 v8, v8
	v_exp_f32_e32 v9, v9
	v_add_f32_e32 v171, v171, v2
	v_add_f32_e32 v170, v170, v3
	v_add_f32_e32 v171, v171, v4
	v_add_f32_e32 v170, v170, v5
	v_fma_f32 v10, v10, s46, v175
	v_fma_f32 v11, v11, s46, v175
	v_fma_f32 v12, v12, s46, v175
	v_fma_f32 v13, v13, s46, v175
	v_exp_f32_e32 v10, v10
	v_exp_f32_e32 v11, v11
	v_exp_f32_e32 v12, v12
	v_exp_f32_e32 v13, v13
	v_add_f32_e32 v171, v171, v6
	v_add_f32_e32 v170, v170, v7
	v_add_f32_e32 v171, v171, v8
	v_add_f32_e32 v170, v170, v9
	v_fma_f32 v14, v14, s46, v175
	v_fma_f32 v15, v15, s46, v175
	v_fma_f32 v16, v16, s46, v175
	v_fma_f32 v17, v17, s46, v175
	v_exp_f32_e32 v14, v14
	v_exp_f32_e32 v15, v15
	v_exp_f32_e32 v16, v16
	v_exp_f32_e32 v17, v17
	v_add_f32_e32 v171, v171, v10
	v_add_f32_e32 v170, v170, v11
	v_add_f32_e32 v171, v171, v12
	v_add_f32_e32 v170, v170, v13
	v_fma_f32 v18, v18, s46, v175
	v_fma_f32 v19, v19, s46, v175
	v_fma_f32 v20, v20, s46, v175
	v_fma_f32 v21, v21, s46, v175
	v_exp_f32_e32 v18, v18
	v_exp_f32_e32 v19, v19
	v_exp_f32_e32 v20, v20
	v_exp_f32_e32 v21, v21
	v_add_f32_e32 v171, v171, v14
	v_add_f32_e32 v170, v170, v15
	v_add_f32_e32 v171, v171, v16
	v_add_f32_e32 v170, v170, v17
	v_fma_f32 v22, v22, s46, v175
	v_fma_f32 v23, v23, s46, v175
	v_fma_f32 v24, v24, s46, v175
	v_fma_f32 v25, v25, s46, v175
	v_exp_f32_e32 v22, v22
	v_exp_f32_e32 v23, v23
	v_exp_f32_e32 v24, v24
	v_exp_f32_e32 v25, v25
	v_add_f32_e32 v171, v171, v18
	v_add_f32_e32 v170, v170, v19
	v_add_f32_e32 v171, v171, v20
	v_add_f32_e32 v170, v170, v21
	v_fma_f32 v26, v26, s46, v175
	v_fma_f32 v27, v27, s46, v175
	v_fma_f32 v28, v28, s46, v175
	v_fma_f32 v29, v29, s46, v175
	v_exp_f32_e32 v26, v26
	v_exp_f32_e32 v27, v27
	v_exp_f32_e32 v28, v28
	v_exp_f32_e32 v29, v29
	v_add_f32_e32 v171, v171, v22
	v_add_f32_e32 v170, v170, v23
	v_add_f32_e32 v171, v171, v24
	v_add_f32_e32 v170, v170, v25
	v_fma_f32 v30, v30, s46, v175
	v_fma_f32 v31, v31, s46, v175
	v_fma_f32 v32, v32, s46, v175
	v_fma_f32 v33, v33, s46, v175
	v_exp_f32_e32 v30, v30
	v_exp_f32_e32 v31, v31
	v_exp_f32_e32 v32, v32
	v_exp_f32_e32 v33, v33
	v_add_f32_e32 v171, v171, v26
	v_add_f32_e32 v170, v170, v27
	v_add_f32_e32 v171, v171, v28
	v_add_f32_e32 v170, v170, v29
	v_fma_f32 v34, v34, s46, v175
	v_fma_f32 v35, v35, s46, v175
	v_fma_f32 v36, v36, s46, v175
	v_fma_f32 v37, v37, s46, v175
	v_exp_f32_e32 v34, v34
	v_exp_f32_e32 v35, v35
	v_exp_f32_e32 v36, v36
	v_exp_f32_e32 v37, v37
	v_add_f32_e32 v171, v171, v30
	v_add_f32_e32 v170, v170, v31
	v_add_f32_e32 v171, v171, v32
	v_add_f32_e32 v170, v170, v33
	v_fma_f32 v38, v38, s46, v175
	v_fma_f32 v39, v39, s46, v175
	v_fma_f32 v40, v40, s46, v175
	v_fma_f32 v41, v41, s46, v175
	v_exp_f32_e32 v38, v38
	v_exp_f32_e32 v39, v39
	v_exp_f32_e32 v40, v40
	v_exp_f32_e32 v41, v41
	v_add_f32_e32 v171, v171, v34
	v_add_f32_e32 v170, v170, v35
	v_add_f32_e32 v171, v171, v36
	v_add_f32_e32 v170, v170, v37
	v_fma_f32 v42, v42, s46, v175
	v_fma_f32 v43, v43, s46, v175
	v_fma_f32 v44, v44, s46, v175
	v_fma_f32 v45, v45, s46, v175
	v_exp_f32_e32 v42, v42
	v_exp_f32_e32 v43, v43
	v_exp_f32_e32 v44, v44
	v_exp_f32_e32 v45, v45
	v_add_f32_e32 v171, v171, v38
	v_add_f32_e32 v170, v170, v39
	v_add_f32_e32 v171, v171, v40
	v_add_f32_e32 v170, v170, v41
	v_fma_f32 v46, v46, s46, v175
	v_fma_f32 v47, v47, s46, v175
	v_fma_f32 v48, v48, s46, v175
	v_fma_f32 v49, v49, s46, v175
	v_exp_f32_e32 v46, v46
	v_exp_f32_e32 v47, v47
	v_exp_f32_e32 v48, v48
	v_exp_f32_e32 v49, v49
	v_add_f32_e32 v171, v171, v42
	v_add_f32_e32 v170, v170, v43
	v_add_f32_e32 v171, v171, v44
	v_add_f32_e32 v170, v170, v45
	v_fma_f32 v50, v50, s46, v175
	v_fma_f32 v51, v51, s46, v175
	v_fma_f32 v52, v52, s46, v175
	v_fma_f32 v53, v53, s46, v175
	v_exp_f32_e32 v50, v50
	v_exp_f32_e32 v51, v51
	v_exp_f32_e32 v52, v52
	v_exp_f32_e32 v53, v53
	v_add_f32_e32 v171, v171, v46
	v_add_f32_e32 v170, v170, v47
	v_add_f32_e32 v171, v171, v48
	v_add_f32_e32 v170, v170, v49
	v_fma_f32 v54, v54, s46, v175
	v_fma_f32 v55, v55, s46, v175
	v_fma_f32 v56, v56, s46, v175
	v_fma_f32 v57, v57, s46, v175
	v_exp_f32_e32 v54, v54
	v_exp_f32_e32 v55, v55
	v_exp_f32_e32 v56, v56
	v_exp_f32_e32 v57, v57
	v_add_f32_e32 v171, v171, v50
	v_add_f32_e32 v170, v170, v51
	v_add_f32_e32 v171, v171, v52
	v_add_f32_e32 v170, v170, v53
	v_fma_f32 v58, v58, s46, v175
	v_fma_f32 v59, v59, s46, v175
	v_fma_f32 v60, v60, s46, v175
	v_fma_f32 v61, v61, s46, v175
	v_exp_f32_e32 v58, v58
	v_exp_f32_e32 v59, v59
	v_exp_f32_e32 v60, v60
	v_exp_f32_e32 v61, v61
	v_add_f32_e32 v171, v171, v54
	v_add_f32_e32 v170, v170, v55
	v_add_f32_e32 v171, v171, v56
	v_add_f32_e32 v170, v170, v57
	v_fma_f32 v62, v62, s46, v175
	v_fma_f32 v63, v63, s46, v175
	v_fma_f32 v64, v64, s46, v175
	v_fma_f32 v65, v65, s46, v175
	v_exp_f32_e32 v62, v62
	v_exp_f32_e32 v63, v63
	v_exp_f32_e32 v64, v64
	v_exp_f32_e32 v65, v65
	v_add_f32_e32 v171, v171, v58
	v_add_f32_e32 v170, v170, v59
	v_add_f32_e32 v171, v171, v60
	v_add_f32_e32 v170, v170, v61
	v_fma_f32 v66, v66, s46, v175
	v_fma_f32 v67, v67, s46, v175
	v_fma_f32 v68, v68, s46, v175
	v_fma_f32 v69, v69, s46, v175
	v_exp_f32_e32 v66, v66
	v_exp_f32_e32 v67, v67
; __device__ __forceinline__ unsigned cvt_pk_bf16_asm(float lo, float hi) { unsigned r; asm volatile("v_cvt_pk_bf16_f32 %0, %1, %2" : "=v"(r) : "v"(lo), "v"(hi)); return r; }
; __device__ __forceinline__ f32x4 mfma16(bf16x8 a, bf16x8 b, f32x4 c) { return __builtin_amdgcn_mfma_f32_16x16x32_bf16(a, b, c, 0, 0, 0); }
; __device__ void att_phase(int wv, const Params& p, unsigned char* lds) {
;     ...
;             for (int cb = 0; cb < 24; ++cb)
; #pragma unroll
;                 for (int j = 0; j < 4; ++j) { const float e = __expf(sc[cb][j] - mx); sc[cb][j] = e; sum += e; }
;             sum += __shfl_xor(sum, 16); sum += __shfl_xor(sum, 32);
;             sum += __expf(sink - mx);
;             const float inv = 1.0f / sum;
;             f32x4 oa[4];
; #pragma unroll
;             for (int db = 0; db < 4; ++db) oa[db] = (f32x4){0, 0, 0, 0};
; #pragma unroll
;             for (int ks = 0; ks < 12; ++ks) {
;                 union { bf16x8 v; unsigned u[4]; } pf;
;                 pf.u[0] = cvt_pk_bf16_asm(sc[2 * ks][0], sc[2 * ks][1]); pf.u[1] = cvt_pk_bf16_asm(sc[2 * ks][2], sc[2 * ks][3]);
;                 pf.u[2] = cvt_pk_bf16_asm(sc[2 * ks + 1][0], sc[2 * ks + 1][1]); pf.u[3] = cvt_pk_bf16_asm(sc[2 * ks + 1][2], sc[2 * ks + 1][3]);
; #pragma unroll
;                 for (int db = 0; db < 4; ++db) {
;                     union { bf16x8 v; u32x2 h2[2]; } vf;
;                     const bf16_t* vp = VTL + (16 * db + lr) * VP + 32 * ks + 4 * lq;
;                     vf.h2[0] = *(const u32x2*)vp; vf.h2[1] = *(const u32x2*)(vp + 16);
;                     oa[db] = mfma16(vf.v, pf.v, oa[db]); } }
	v_exp_f32_e32 v68, v68
	v_exp_f32_e32 v69, v69
	v_add_f32_e32 v171, v171, v62
	v_add_f32_e32 v170, v170, v63
	v_add_f32_e32 v171, v171, v64
	v_add_f32_e32 v170, v170, v65
	v_add_f32_e32 v171, v171, v66
	v_add_f32_e32 v170, v170, v67
	v_add_f32_e32 v171, v171, v68
	v_add_f32_e32 v170, v170, v69
	v_add_f32_e32 v170, v170, v171
	v_cvt_pk_bf16_f32 v2, v2, v3
	v_cvt_pk_bf16_f32 v3, v4, v5
	v_cvt_pk_bf16_f32 v4, v6, v7
	v_cvt_pk_bf16_f32 v5, v8, v9
	v_cvt_pk_bf16_f32 v10, v10, v11
	v_cvt_pk_bf16_f32 v11, v12, v13
	v_cvt_pk_bf16_f32 v12, v14, v15
	v_cvt_pk_bf16_f32 v13, v16, v17
	v_cvt_pk_bf16_f32 v18, v18, v19
	v_cvt_pk_bf16_f32 v19, v20, v21
	v_cvt_pk_bf16_f32 v20, v22, v23
	v_cvt_pk_bf16_f32 v21, v24, v25
	v_cvt_pk_bf16_f32 v26, v26, v27
	v_cvt_pk_bf16_f32 v27, v28, v29
	v_cvt_pk_bf16_f32 v28, v30, v31
	v_cvt_pk_bf16_f32 v29, v32, v33
	v_cvt_pk_bf16_f32 v34, v34, v35
	v_cvt_pk_bf16_f32 v35, v36, v37
	v_cvt_pk_bf16_f32 v36, v38, v39
	v_cvt_pk_bf16_f32 v37, v40, v41
	v_cvt_pk_bf16_f32 v42, v42, v43
	v_cvt_pk_bf16_f32 v43, v44, v45
	v_cvt_pk_bf16_f32 v44, v46, v47
	v_cvt_pk_bf16_f32 v45, v48, v49
	v_cvt_pk_bf16_f32 v50, v50, v51
	v_cvt_pk_bf16_f32 v51, v52, v53
	v_cvt_pk_bf16_f32 v52, v54, v55
	v_cvt_pk_bf16_f32 v53, v56, v57
	v_cvt_pk_bf16_f32 v58, v58, v59
	v_cvt_pk_bf16_f32 v59, v60, v61
	v_cvt_pk_bf16_f32 v60, v62, v63
	v_cvt_pk_bf16_f32 v61, v64, v65
	v_cvt_pk_bf16_f32 v66, v66, v67
	v_cvt_pk_bf16_f32 v67, v68, v69
	v_mov_b32_e32 v68, 0
	v_mov_b32_e32 v69, 0
	ds_bpermute_b32 v172, v1, v170
	v_sub_f32_e32 v173, v146, v169
	v_mul_f32_e32 v173, 0x3fb8aa3b, v173
	v_exp_f32_e32 v173, v173
	s_waitcnt lgkmcnt(0)
	v_add_f32_e32 v170, v170, v172
	ds_bpermute_b32 v172, v114, v170
	ds_read2_b64 v[232:235], v165 offset0:12 offset1:16
	ds_read2_b64 v[236:239], v166 offset0:12 offset1:16
	ds_read2_b64 v[240:243], v167 offset0:12 offset1:16
	ds_read2_b64 v[244:247], v168 offset0:12 offset1:16
	s_waitcnt lgkmcnt(4)
	v_mfma_f32_16x16x32_bf16 v[70:73], v[216:219], v[2:5], 0
	v_mfma_f32_16x16x32_bf16 v[74:77], v[220:223], v[2:5], 0
	v_mfma_f32_16x16x32_bf16 v[78:81], v[224:227], v[2:5], 0
	v_mfma_f32_16x16x32_bf16 v[82:85], v[228:231], v[2:5], 0
	v_add_f32_e32 v170, v170, v172
	v_add_f32_e32 v170, v170, v173
	v_rcp_f32_e32 v147, v170
	s_nop 0
	v_fma_f32 v179, -v170, v147, 1.0
	v_fmac_f32_e32 v147, v179, v147
	ds_read2_b64 v[216:219], v165 offset0:20 offset1:24
	ds_read2_b64 v[220:223], v166 offset0:20 offset1:24
	ds_read2_b64 v[224:227], v167 offset0:20 offset1:24
	ds_read2_b64 v[228:231], v168 offset0:20 offset1:24
	s_waitcnt lgkmcnt(4)
	v_mfma_f32_16x16x32_bf16 v[70:73], v[232:235], v[10:13], v[70:73]
	v_mfma_f32_16x16x32_bf16 v[74:77], v[236:239], v[10:13], v[74:77]
	v_mfma_f32_16x16x32_bf16 v[78:81], v[240:243], v[10:13], v[78:81]
	v_mfma_f32_16x16x32_bf16 v[82:85], v[244:247], v[10:13], v[82:85]
	ds_read2_b64 v[232:235], v165 offset0:28 offset1:32
	ds_read2_b64 v[236:239], v166 offset0:28 offset1:32
	ds_read2_b64 v[240:243], v167 offset0:28 offset1:32
	ds_read2_b64 v[244:247], v168 offset0:28 offset1:32
	s_waitcnt lgkmcnt(4)
	v_mfma_f32_16x16x32_bf16 v[70:73], v[216:219], v[18:21], v[70:73]
	v_mfma_f32_16x16x32_bf16 v[74:77], v[220:223], v[18:21], v[74:77]
	v_mfma_f32_16x16x32_bf16 v[78:81], v[224:227], v[18:21], v[78:81]
	v_mfma_f32_16x16x32_bf16 v[82:85], v[228:231], v[18:21], v[82:85]
	ds_read2_b64 v[216:219], v165 offset0:36 offset1:40
	ds_read2_b64 v[220:223], v166 offset0:36 offset1:40
	ds_read2_b64 v[224:227], v167 offset0:36 offset1:40
	ds_read2_b64 v[228:231], v168 offset0:36 offset1:40
	s_waitcnt lgkmcnt(4)
	v_mfma_f32_16x16x32_bf16 v[70:73], v[232:235], v[26:29], v[70:73]
	v_mfma_f32_16x16x32_bf16 v[74:77], v[236:239], v[26:29], v[74:77]
	v_mfma_f32_16x16x32_bf16 v[78:81], v[240:243], v[26:29], v[78:81]
	v_mfma_f32_16x16x32_bf16 v[82:85], v[244:247], v[26:29], v[82:85]
	ds_read2_b64 v[232:235], v165 offset0:44 offset1:48
	ds_read2_b64 v[236:239], v166 offset0:44 offset1:48
	ds_read2_b64 v[240:243], v167 offset0:44 offset1:48
	ds_read2_b64 v[244:247], v168 offset0:44 offset1:48
	s_waitcnt lgkmcnt(4)
	v_mfma_f32_16x16x32_bf16 v[70:73], v[216:219], v[34:37], v[70:73]
	v_mfma_f32_16x16x32_bf16 v[74:77], v[220:223], v[34:37], v[74:77]
	v_mfma_f32_16x16x32_bf16 v[78:81], v[224:227], v[34:37], v[78:81]
	v_mfma_f32_16x16x32_bf16 v[82:85], v[228:231], v[34:37], v[82:85]
	ds_read2_b64 v[216:219], v165 offset0:52 offset1:56
	ds_read2_b64 v[220:223], v166 offset0:52 offset1:56
	ds_read2_b64 v[224:227], v167 offset0:52 offset1:56
	ds_read2_b64 v[228:231], v168 offset0:52 offset1:56
	s_waitcnt lgkmcnt(4)
	v_mfma_f32_16x16x32_bf16 v[70:73], v[232:235], v[42:45], v[70:73]
	v_mfma_f32_16x16x32_bf16 v[74:77], v[236:239], v[42:45], v[74:77]
	v_mfma_f32_16x16x32_bf16 v[78:81], v[240:243], v[42:45], v[78:81]
	v_mfma_f32_16x16x32_bf16 v[82:85], v[244:247], v[42:45], v[82:85]
	ds_read2_b64 v[232:235], v165 offset0:60 offset1:64
	ds_read2_b64 v[236:239], v166 offset0:60 offset1:64
	ds_read2_b64 v[240:243], v167 offset0:60 offset1:64
	ds_read2_b64 v[244:247], v168 offset0:60 offset1:64
	s_waitcnt lgkmcnt(4)
	v_mfma_f32_16x16x32_bf16 v[70:73], v[216:219], v[50:53], v[70:73]
	v_mfma_f32_16x16x32_bf16 v[74:77], v[220:223], v[50:53], v[74:77]
	v_mfma_f32_16x16x32_bf16 v[78:81], v[224:227], v[50:53], v[78:81]
	v_mfma_f32_16x16x32_bf16 v[82:85], v[228:231], v[50:53], v[82:85]
	ds_read2_b64 v[216:219], v165 offset0:68 offset1:68
	ds_read2_b64 v[220:223], v166 offset0:68 offset1:68
	ds_read2_b64 v[224:227], v167 offset0:68 offset1:68
	ds_read2_b64 v[228:231], v168 offset0:68 offset1:68
	s_waitcnt lgkmcnt(4)
; __device__ __forceinline__ unsigned cvt_pk_bf16_asm(float lo, float hi) { unsigned r; asm volatile("v_cvt_pk_bf16_f32 %0, %1, %2" : "=v"(r) : "v"(lo), "v"(hi)); return r; }
; __device__ __forceinline__ f32x4 mfma16(bf16x8 a, bf16x8 b, f32x4 c) { return __builtin_amdgcn_mfma_f32_16x16x32_bf16(a, b, c, 0, 0, 0); }
; __device__ void att_phase(int wv, const Params& p, unsigned char* lds) {
;     ...
;         for (int rb = 0; rb < 4; ++rb) {
;             const int qrow = 64 * (w & 1) + 16 * rb + lr;
;             const size_t tokq = (size_t)B * 128 + qrow;
;             bf16x8 qf[2];
; #pragma unroll
;             for (int kk = 0; kk < 2; ++kk) qf[kk] = *(const bf16x8*)(qkv + tokq * 1536 + 64 * h + 32 * kk + 8 * lq);
;             f32x4 sc[24];
; #pragma unroll
;             for (int cb = 0; cb < 24; ++cb) { f32x4 a = {0, 0, 0, 0};
; #pragma unroll
;                 for (int kk = 0; kk < 2; ++kk) { const bf16x8 kf = *(const bf16x8*)(KL + (16 * cb + lr) * KP + 32 * kk + 8 * lq); a = mfma16(kf, qf[kk], a); }
;                 sc[cb] = a; }
;             float mx = sink;
; #pragma unroll
;             for (int cb = 0; cb < 24; ++cb) { const int kb = B - 1 + (cb >> 3); const bool bval = (kb >= sb && kb < se);
; #pragma unroll
;                 for (int j = 0; j < 4; ++j) { const int krel = 16 * cb + 4 * lq + j - 128;
;                     int dist = qrow - krel; dist = dist < 0 ? -dist : dist;
;                     const float v = (bval && dist <= 128) ? sc[cb][j] * 0.125f - slope * (float)dist : -1e30f;
;                     sc[cb][j] = v; mx = fmaxf(mx, v); } }
;     ...
;                 for (int db = 0; db < 4; ++db) {
;                     union { bf16x8 v; u32x2 h2[2]; } vf;
;                     const bf16_t* vp = VTL + (16 * db + lr) * VP + 32 * ks + 4 * lq;
;                     vf.h2[0] = *(const u32x2*)vp; vf.h2[1] = *(const u32x2*)(vp + 16);
;                     oa[db] = mfma16(vf.v, pf.v, oa[db]); } }
; #pragma unroll
;             for (int db = 0; db < 4; ++db) { const f32x4 o = oa[db] * inv; u32x2 wv; wv.x = cvt_pk_bf16_asm(o[0], o[1]); wv.y = cvt_pk_bf16_asm(o[2], o[3]);
;                 *(u32x2*)(qkv + tokq * 1536 + 64 * h + 16 * db + 4 * lq) = wv; }
	v_mfma_f32_16x16x32_bf16 v[70:73], v[232:235], v[58:61], v[70:73]
	v_mfma_f32_16x16x32_bf16 v[74:77], v[236:239], v[58:61], v[74:77]
	v_mfma_f32_16x16x32_bf16 v[78:81], v[240:243], v[58:61], v[78:81]
	v_mfma_f32_16x16x32_bf16 v[82:85], v[244:247], v[58:61], v[82:85]
	s_waitcnt lgkmcnt(0)
	v_mfma_f32_16x16x32_bf16 v[70:73], v[216:219], v[66:69], v[70:73]
	v_mfma_f32_16x16x32_bf16 v[74:77], v[220:223], v[66:69], v[74:77]
	v_mfma_f32_16x16x32_bf16 v[78:81], v[224:227], v[66:69], v[78:81]
	v_mfma_f32_16x16x32_bf16 v[82:85], v[228:231], v[66:69], v[82:85]
	s_nop 7
	s_nop 1
	v_mul_f32_e32 v70, v70, v147
	v_mul_f32_e32 v71, v71, v147
	v_mul_f32_e32 v72, v72, v147
	v_mul_f32_e32 v73, v73, v147
	v_mul_f32_e32 v74, v74, v147
	v_mul_f32_e32 v75, v75, v147
	v_mul_f32_e32 v76, v76, v147
	v_mul_f32_e32 v77, v77, v147
	v_mul_f32_e32 v78, v78, v147
	v_mul_f32_e32 v79, v79, v147
	v_mul_f32_e32 v80, v80, v147
	v_mul_f32_e32 v81, v81, v147
	v_mul_f32_e32 v82, v82, v147
	v_mul_f32_e32 v83, v83, v147
	v_mul_f32_e32 v84, v84, v147
	v_mul_f32_e32 v85, v85, v147
	v_cvt_pk_bf16_f32 v70, v70, v71
	v_cvt_pk_bf16_f32 v71, v72, v73
	v_cvt_pk_bf16_f32 v74, v74, v75
	v_cvt_pk_bf16_f32 v75, v76, v77
	v_cvt_pk_bf16_f32 v78, v78, v79
	v_cvt_pk_bf16_f32 v79, v80, v81
	v_cvt_pk_bf16_f32 v82, v82, v83
	v_cvt_pk_bf16_f32 v83, v84, v85
	global_store_dwordx2 v[248:249], v[70:71], off offset:-64
	global_store_dwordx2 v[248:249], v[74:75], off offset:-32
	global_store_dwordx2 v[248:249], v[78:79], off
	global_store_dwordx2 v[248:249], v[82:83], off offset:32
	v_lshl_add_u64 v[248:249], v[248:249], 0, s[48:49]
	v_sub_f32_e32 v86, v94, v176
	v_sub_f32_e32 v87, v95, v176
	v_sub_f32_e32 v88, v96, v176
	v_sub_f32_e32 v89, v97, v176
	v_cmp_ge_i32_e32 vcc, 0, v108
	s_nop 1
	v_cndmask_b32_e32 v212, v252, v86, vcc
	v_cmp_ge_i32_e32 vcc, 0, v110
	s_nop 1
	v_cndmask_b32_e32 v213, v252, v87, vcc
	v_cmp_ge_i32_e32 vcc, 0, v111
	s_nop 1
	v_cndmask_b32_e32 v214, v252, v88, vcc
	v_cmp_ge_i32_e32 vcc, 0, v177
	s_nop 1
	v_cndmask_b32_e32 v215, v252, v89, vcc
	ds_read_b128 v[148:151], v164 offset:4608
	ds_read_b128 v[152:155], v164 offset:4672
	ds_read_b128 v[156:159], v164 offset:6912
	ds_read_b128 v[160:163], v164 offset:6976
	v_add_f32_e32 v90, v86, v174
	v_add_f32_e32 v91, v87, v174
	v_add_f32_e32 v92, v88, v174
	v_add_f32_e32 v93, v89, v174
	s_cmp_lt_i32 s47, 14
	s_cselect_b64 vcc, -1, s[10:11]
	s_cmp_lt_i32 s47, 6
	s_cselect_b64 vcc, s[6:7], vcc
	v_cndmask_b32_e32 v232, v252, v212, vcc
	v_cndmask_b32_e32 v233, v252, v213, vcc
	v_cndmask_b32_e32 v234, v252, v214, vcc
	v_cndmask_b32_e32 v235, v252, v215, vcc
	s_waitcnt lgkmcnt(2)
	v_mfma_f32_16x16x32_bf16 v[2:5], v[148:151], v[196:199], v[232:235]
	v_mfma_f32_16x16x32_bf16 v[2:5], v[152:155], v[200:203], v[2:5]
	ds_read_b128 v[148:151], v164 offset:9216
	ds_read_b128 v[152:155], v164 offset:9280
	v_add_f32_e32 v86, v90, v174
	v_add_f32_e32 v87, v91, v174
	v_add_f32_e32 v88, v92, v174
	v_add_f32_e32 v89, v93, v174
	s_cmp_lt_i32 s47, 13
	s_cselect_b64 vcc, -1, s[10:11]
	s_cmp_lt_i32 s47, 5
	s_cselect_b64 vcc, s[6:7], vcc
	v_cndmask_b32_e32 v236, v252, v90, vcc
	v_cndmask_b32_e32 v237, v252, v91, vcc
	v_cndmask_b32_e32 v238, v252, v92, vcc
	v_cndmask_b32_e32 v239, v252, v93, vcc
	s_waitcnt lgkmcnt(2)
	v_mfma_f32_16x16x32_bf16 v[6:9], v[156:159], v[196:199], v[236:239]
	v_mfma_f32_16x16x32_bf16 v[6:9], v[160:163], v[200:203], v[6:9]
	ds_read_b128 v[156:159], v164 offset:11520
	ds_read_b128 v[160:163], v164 offset:11584
	v_add_f32_e32 v90, v86, v174
	v_add_f32_e32 v91, v87, v174
	v_add_f32_e32 v92, v88, v174
	v_add_f32_e32 v93, v89, v174
	s_cmp_lt_i32 s47, 12
	s_cselect_b64 vcc, -1, s[10:11]
	s_cmp_lt_i32 s47, 4
	s_cselect_b64 vcc, s[6:7], vcc
	v_cndmask_b32_e32 v232, v252, v86, vcc
	v_cndmask_b32_e32 v233, v252, v87, vcc
	v_cndmask_b32_e32 v234, v252, v88, vcc
	v_cndmask_b32_e32 v235, v252, v89, vcc
	s_waitcnt lgkmcnt(2)
	v_mfma_f32_16x16x32_bf16 v[10:13], v[148:151], v[196:199], v[232:235]
	v_mfma_f32_16x16x32_bf16 v[10:13], v[152:155], v[200:203], v[10:13]
	ds_read_b128 v[148:151], v164 offset:13824
	ds_read_b128 v[152:155], v164 offset:13888
	v_add_f32_e32 v86, v90, v174
	v_add_f32_e32 v87, v91, v174
	v_add_f32_e32 v88, v92, v174
	v_add_f32_e32 v89, v93, v174
	s_cmp_lt_i32 s47, 11
	s_cselect_b64 vcc, -1, s[10:11]
	s_cmp_lt_i32 s47, 3
	s_cselect_b64 vcc, s[6:7], vcc
	v_cndmask_b32_e32 v236, v252, v90, vcc
	v_cndmask_b32_e32 v237, v252, v91, vcc
	v_cndmask_b32_e32 v238, v252, v92, vcc
	v_cndmask_b32_e32 v239, v252, v93, vcc
	s_waitcnt lgkmcnt(2)
	v_mfma_f32_16x16x32_bf16 v[14:17], v[156:159], v[196:199], v[236:239]
	v_mfma_f32_16x16x32_bf16 v[14:17], v[160:163], v[200:203], v[14:17]
	ds_read_b128 v[156:159], v164 offset:16128
	ds_read_b128 v[160:163], v164 offset:16192
	v_add_f32_e32 v90, v86, v174
	v_add_f32_e32 v91, v87, v174
	v_add_f32_e32 v92, v88, v174
	v_add_f32_e32 v93, v89, v174
	s_cmp_lt_i32 s47, 10
	s_cselect_b64 vcc, -1, s[10:11]
	s_cmp_lt_i32 s47, 2
	s_cselect_b64 vcc, s[6:7], vcc
	v_cndmask_b32_e32 v232, v252, v86, vcc
	v_cndmask_b32_e32 v233, v252, v87, vcc
	v_cndmask_b32_e32 v234, v252, v88, vcc
	v_cndmask_b32_e32 v235, v252, v89, vcc
	s_waitcnt lgkmcnt(2)
	v_mfma_f32_16x16x32_bf16 v[18:21], v[148:151], v[196:199], v[232:235]
	v_mfma_f32_16x16x32_bf16 v[18:21], v[152:155], v[200:203], v[18:21]
	ds_read_b128 v[148:151], v164 offset:18432
	ds_read_b128 v[152:155], v164 offset:18496
	v_add_f32_e32 v86, v90, v174
	v_add_f32_e32 v87, v91, v174
	v_add_f32_e32 v88, v92, v174
	v_add_f32_e32 v89, v93, v174
	s_cmp_lt_i32 s47, 9
	s_cselect_b64 vcc, -1, s[10:11]
	s_cmp_lt_i32 s47, 1
	s_cselect_b64 vcc, s[6:7], vcc
	v_cndmask_b32_e32 v236, v252, v90, vcc
	v_cndmask_b32_e32 v237, v252, v91, vcc
	v_cndmask_b32_e32 v238, v252, v92, vcc
	v_cndmask_b32_e32 v239, v252, v93, vcc
	s_waitcnt lgkmcnt(2)
; __device__ __forceinline__ f32x4 mfma16(bf16x8 a, bf16x8 b, f32x4 c) { return __builtin_amdgcn_mfma_f32_16x16x32_bf16(a, b, c, 0, 0, 0); }
; __device__ void att_phase(int wv, const Params& p, unsigned char* lds) {
;     ...
; #pragma unroll
;             for (int cb = 0; cb < 24; ++cb) { f32x4 a = {0, 0, 0, 0};
; #pragma unroll
;                 for (int kk = 0; kk < 2; ++kk) { const bf16x8 kf = *(const bf16x8*)(KL + (16 * cb + lr) * KP + 32 * kk + 8 * lq); a = mfma16(kf, qf[kk], a); }
;                 sc[cb] = a; }
;             float mx = sink;
; #pragma unroll
;             for (int cb = 0; cb < 24; ++cb) { const int kb = B - 1 + (cb >> 3); const bool bval = (kb >= sb && kb < se);
; #pragma unroll
;                 for (int j = 0; j < 4; ++j) { const int krel = 16 * cb + 4 * lq + j - 128;
;                     int dist = qrow - krel; dist = dist < 0 ? -dist : dist;
;                     const float v = (bval && dist <= 128) ? sc[cb][j] * 0.125f - slope * (float)dist : -1e30f;
;                     sc[cb][j] = v; mx = fmaxf(mx, v); } }
	v_mfma_f32_16x16x32_bf16 v[22:25], v[156:159], v[196:199], v[236:239]
	v_mfma_f32_16x16x32_bf16 v[22:25], v[160:163], v[200:203], v[22:25]
	ds_read_b128 v[156:159], v164 offset:20736
	ds_read_b128 v[160:163], v164 offset:20800
	v_add_f32_e32 v90, v86, v174
	v_add_f32_e32 v91, v87, v174
	v_add_f32_e32 v92, v88, v174
	v_add_f32_e32 v93, v89, v174
	s_waitcnt lgkmcnt(2)
	v_mfma_f32_16x16x32_bf16 v[26:29], v[148:151], v[196:199], v[86:89]
	v_mfma_f32_16x16x32_bf16 v[26:29], v[152:155], v[200:203], v[26:29]
	ds_read_b128 v[148:151], v164 offset:23040
	ds_read_b128 v[152:155], v164 offset:23104
	s_waitcnt lgkmcnt(2)
	v_mfma_f32_16x16x32_bf16 v[30:33], v[156:159], v[196:199], v[90:93]
	v_mfma_f32_16x16x32_bf16 v[30:33], v[160:163], v[200:203], v[30:33]
	ds_read_b128 v[156:159], v164 offset:25344
	ds_read_b128 v[160:163], v164 offset:25408
	v_sub_f32_e64 v86, -v94, v174
	v_sub_f32_e64 v87, -v95, v174
	v_sub_f32_e64 v88, -v96, v174
	v_sub_f32_e64 v89, -v97, v174
	s_waitcnt lgkmcnt(2)
	v_mfma_f32_16x16x32_bf16 v[34:37], v[148:151], v[196:199], v[98:101]
	v_mfma_f32_16x16x32_bf16 v[34:37], v[152:155], v[200:203], v[34:37]
	ds_read_b128 v[148:151], v164 offset:27648
	ds_read_b128 v[152:155], v164 offset:27712
	v_sub_f32_e32 v90, v86, v174
	v_sub_f32_e32 v91, v87, v174
	v_sub_f32_e32 v92, v88, v174
	v_sub_f32_e32 v93, v89, v174
	s_waitcnt lgkmcnt(2)
	v_mfma_f32_16x16x32_bf16 v[38:41], v[156:159], v[196:199], v[86:89]
	v_mfma_f32_16x16x32_bf16 v[38:41], v[160:163], v[200:203], v[38:41]
	ds_read_b128 v[156:159], v164 offset:29952
	ds_read_b128 v[160:163], v164 offset:30016
	v_sub_f32_e32 v86, v90, v174
	v_sub_f32_e32 v87, v91, v174
	v_sub_f32_e32 v88, v92, v174
	v_sub_f32_e32 v89, v93, v174
	s_cmp_lt_i32 s47, 4
	s_cselect_b64 vcc, -1, s[10:11]
	s_cmp_lt_i32 s47, -4
	s_cselect_b64 vcc, s[6:7], vcc
	v_cndmask_b32_e32 v232, v252, v90, vcc
	v_cndmask_b32_e32 v233, v252, v91, vcc
	v_cndmask_b32_e32 v234, v252, v92, vcc
	v_cndmask_b32_e32 v235, v252, v93, vcc
	s_waitcnt lgkmcnt(2)
	v_mfma_f32_16x16x32_bf16 v[42:45], v[148:151], v[196:199], v[232:235]
	v_mfma_f32_16x16x32_bf16 v[42:45], v[152:155], v[200:203], v[42:45]
	ds_read_b128 v[148:151], v164 offset:32256
	ds_read_b128 v[152:155], v164 offset:32320
	v_sub_f32_e32 v90, v86, v174
	v_sub_f32_e32 v91, v87, v174
	v_sub_f32_e32 v92, v88, v174
	v_sub_f32_e32 v93, v89, v174
	s_cmp_lt_i32 s47, 3
	s_cselect_b64 vcc, -1, s[10:11]
	s_cmp_lt_i32 s47, -5
	s_cselect_b64 vcc, s[6:7], vcc
	v_cndmask_b32_e32 v236, v252, v86, vcc
	v_cndmask_b32_e32 v237, v252, v87, vcc
	v_cndmask_b32_e32 v238, v252, v88, vcc
	v_cndmask_b32_e32 v239, v252, v89, vcc
	s_waitcnt lgkmcnt(2)
	v_mfma_f32_16x16x32_bf16 v[46:49], v[156:159], v[196:199], v[236:239]
	v_mfma_f32_16x16x32_bf16 v[46:49], v[160:163], v[200:203], v[46:49]
	ds_read_b128 v[156:159], v164 offset:34560
	ds_read_b128 v[160:163], v164 offset:34624
	v_sub_f32_e32 v86, v90, v174
	v_sub_f32_e32 v87, v91, v174
	v_sub_f32_e32 v88, v92, v174
	v_sub_f32_e32 v89, v93, v174
	s_cmp_lt_i32 s47, 2
	s_cselect_b64 vcc, -1, s[10:11]
	s_cmp_lt_i32 s47, -6
	s_cselect_b64 vcc, s[6:7], vcc
	v_cndmask_b32_e32 v232, v252, v90, vcc
	v_cndmask_b32_e32 v233, v252, v91, vcc
	v_cndmask_b32_e32 v234, v252, v92, vcc
	v_cndmask_b32_e32 v235, v252, v93, vcc
	s_waitcnt lgkmcnt(2)
	v_mfma_f32_16x16x32_bf16 v[50:53], v[148:151], v[196:199], v[232:235]
	v_mfma_f32_16x16x32_bf16 v[50:53], v[152:155], v[200:203], v[50:53]
	ds_read_b128 v[148:151], v164 offset:36864
	ds_read_b128 v[152:155], v164 offset:36928
	v_sub_f32_e32 v90, v86, v174
	v_sub_f32_e32 v91, v87, v174
	v_sub_f32_e32 v92, v88, v174
	v_sub_f32_e32 v93, v89, v174
	s_cmp_lt_i32 s47, 1
	s_cselect_b64 vcc, -1, s[10:11]
	s_cmp_lt_i32 s47, -7
	s_cselect_b64 vcc, s[6:7], vcc
	v_cndmask_b32_e32 v236, v252, v86, vcc
	v_cndmask_b32_e32 v237, v252, v87, vcc
	v_cndmask_b32_e32 v238, v252, v88, vcc
	v_cndmask_b32_e32 v239, v252, v89, vcc
	s_waitcnt lgkmcnt(2)
	v_mfma_f32_16x16x32_bf16 v[54:57], v[156:159], v[196:199], v[236:239]
	v_mfma_f32_16x16x32_bf16 v[54:57], v[160:163], v[200:203], v[54:57]
	ds_read_b128 v[156:159], v164 offset:39168
	ds_read_b128 v[160:163], v164 offset:39232
	v_sub_f32_e32 v86, v90, v174
	v_sub_f32_e32 v87, v91, v174
	v_sub_f32_e32 v88, v92, v174
	v_sub_f32_e32 v89, v93, v174
	s_cmp_lt_i32 s47, 0
	s_cselect_b64 vcc, -1, s[10:11]
	s_cmp_lt_i32 s47, -8
	s_cselect_b64 vcc, s[6:7], vcc
	v_cndmask_b32_e32 v232, v252, v90, vcc
	v_cndmask_b32_e32 v233, v252, v91, vcc
	v_cndmask_b32_e32 v234, v252, v92, vcc
	v_cndmask_b32_e32 v235, v252, v93, vcc
	s_waitcnt lgkmcnt(2)
	v_mfma_f32_16x16x32_bf16 v[58:61], v[148:151], v[196:199], v[232:235]
	v_mfma_f32_16x16x32_bf16 v[58:61], v[152:155], v[200:203], v[58:61]
	ds_read_b128 v[148:151], v164 offset:41472
	ds_read_b128 v[152:155], v164 offset:41536
	v_sub_f32_e32 v90, v86, v174
	v_sub_f32_e32 v91, v87, v174
	v_sub_f32_e32 v92, v88, v174
	v_sub_f32_e32 v93, v89, v174
	v_cmp_le_i32_e32 vcc, 0, v108
	s_nop 1
	v_cndmask_b32_e32 v212, v252, v90, vcc
	v_cmp_le_i32_e32 vcc, 0, v110
	s_nop 1
	v_cndmask_b32_e32 v213, v252, v91, vcc
	v_cmp_le_i32_e32 vcc, 0, v111
	s_nop 1
	v_cndmask_b32_e32 v214, v252, v92, vcc
	v_cmp_le_i32_e32 vcc, 0, v177
	s_nop 1
	v_cndmask_b32_e32 v215, v252, v93, vcc
	s_cmp_lt_i32 s47, -1
	s_cselect_b64 vcc, -1, s[10:11]
	s_cmp_lt_i32 s47, -9
	s_cselect_b64 vcc, s[6:7], vcc
	v_cndmask_b32_e32 v236, v252, v86, vcc
	v_cndmask_b32_e32 v237, v252, v87, vcc
	v_cndmask_b32_e32 v238, v252, v88, vcc
	v_cndmask_b32_e32 v239, v252, v89, vcc
	s_waitcnt lgkmcnt(2)
; __device__ void att_phase(int wv, const Params& p, unsigned char* lds) {
;     ...
;             float mx = sink;
; #pragma unroll
;             for (int cb = 0; cb < 24; ++cb) { const int kb = B - 1 + (cb >> 3); const bool bval = (kb >= sb && kb < se);
; #pragma unroll
;                 for (int j = 0; j < 4; ++j) { const int krel = 16 * cb + 4 * lq + j - 128;
;                     int dist = qrow - krel; dist = dist < 0 ? -dist : dist;
;                     const float v = (bval && dist <= 128) ? sc[cb][j] * 0.125f - slope * (float)dist : -1e30f;
;                     sc[cb][j] = v; mx = fmaxf(mx, v); } }
;             mx = fmaxf(mx, __shfl_xor(mx, 16)); mx = fmaxf(mx, __shfl_xor(mx, 32));
;             float sum = 0.f;
; #pragma unroll
;             for (int cb = 0; cb < 24; ++cb)
; #pragma unroll
;                 for (int j = 0; j < 4; ++j) { const float e = __expf(sc[cb][j] - mx); sc[cb][j] = e; sum += e; }
	v_mfma_f32_16x16x32_bf16 v[62:65], v[156:159], v[196:199], v[236:239]
	v_mfma_f32_16x16x32_bf16 v[62:65], v[160:163], v[200:203], v[62:65]
	s_cmp_lt_i32 s47, -2
	s_cselect_b64 vcc, -1, s[10:11]
	s_cmp_lt_i32 s47, -10
	s_cselect_b64 vcc, s[6:7], vcc
	v_cndmask_b32_e32 v232, v252, v212, vcc
	v_cndmask_b32_e32 v233, v252, v213, vcc
	v_cndmask_b32_e32 v234, v252, v214, vcc
	v_cndmask_b32_e32 v235, v252, v215, vcc
	s_waitcnt lgkmcnt(0)
	v_mfma_f32_16x16x32_bf16 v[66:69], v[148:151], v[196:199], v[232:235]
	v_mfma_f32_16x16x32_bf16 v[66:69], v[152:155], v[200:203], v[66:69]
	ds_read2_b64 v[216:219], v165 offset0:8 offset1:12
	ds_read2_b64 v[220:223], v166 offset0:8 offset1:12
	ds_read2_b64 v[224:227], v167 offset0:8 offset1:12
	ds_read2_b64 v[228:231], v168 offset0:8 offset1:12
	v_max3_f32 v169, v2, v3, v4
	v_max3_f32 v172, v5, v6, v7
	v_max3_f32 v169, v8, v9, v169
	v_max3_f32 v172, v10, v11, v172
	v_max3_f32 v169, v12, v13, v169
	v_max3_f32 v172, v14, v15, v172
	v_max3_f32 v169, v16, v17, v169
	v_max3_f32 v172, v18, v19, v172
	v_max3_f32 v169, v20, v21, v169
	v_max3_f32 v172, v22, v23, v172
	v_max3_f32 v169, v24, v25, v169
	v_max3_f32 v172, v26, v27, v172
	v_max3_f32 v169, v28, v29, v169
	v_max3_f32 v172, v30, v31, v172
	v_max3_f32 v169, v32, v33, v169
	v_max3_f32 v172, v34, v35, v172
	v_max3_f32 v169, v36, v37, v169
	v_max3_f32 v172, v38, v39, v172
	v_max3_f32 v169, v40, v41, v169
	v_max3_f32 v172, v42, v43, v172
	v_max3_f32 v169, v44, v45, v169
	v_max3_f32 v172, v46, v47, v172
	v_max3_f32 v169, v48, v49, v169
	v_max3_f32 v172, v50, v51, v172
	v_max3_f32 v169, v52, v53, v169
	v_max3_f32 v172, v54, v55, v172
	v_max3_f32 v169, v56, v57, v169
	v_max3_f32 v172, v58, v59, v172
	v_max3_f32 v169, v60, v61, v169
	v_max3_f32 v172, v62, v63, v172
	v_max3_f32 v169, v64, v65, v169
	v_max3_f32 v172, v66, v67, v172
	v_max3_f32 v169, v68, v69, v169
	v_max_f32_e32 v169, v169, v172
	v_mul_f32_e32 v169, 0x3e000000, v169
	v_max_f32_e32 v169, v169, v146
	ds_bpermute_b32 v172, v1, v169
	s_waitcnt lgkmcnt(0)
	v_max_f32_e32 v169, v169, v172
	ds_bpermute_b32 v172, v114, v169
	s_waitcnt lgkmcnt(0)
	v_max_f32_e32 v169, v169, v172
	v_mul_f32_e32 v175, 0xbfb8aa3b, v169
	v_mov_b32_e32 v170, 0
	v_mov_b32_e32 v171, 0
	v_fma_f32 v2, v2, s46, v175
	v_fma_f32 v3, v3, s46, v175
	v_fma_f32 v4, v4, s46, v175
	v_fma_f32 v5, v5, s46, v175
	v_exp_f32_e32 v2, v2
	v_exp_f32_e32 v3, v3
	v_exp_f32_e32 v4, v4
	v_exp_f32_e32 v5, v5
	v_fma_f32 v6, v6, s46, v175
	v_fma_f32 v7, v7, s46, v175
	v_fma_f32 v8, v8, s46, v175
	v_fma_f32 v9, v9, s46, v175
	v_exp_f32_e32 v6, v6
	v_exp_f32_e32 v7, v7
	v_exp_f32_e32 v8, v8
	v_exp_f32_e32 v9, v9
	v_add_f32_e32 v171, v171, v2
	v_add_f32_e32 v170, v170, v3
	v_add_f32_e32 v171, v171, v4
	v_add_f32_e32 v170, v170, v5
	v_fma_f32 v10, v10, s46, v175
	v_fma_f32 v11, v11, s46, v175
	v_fma_f32 v12, v12, s46, v175
	v_fma_f32 v13, v13, s46, v175
	v_exp_f32_e32 v10, v10
	v_exp_f32_e32 v11, v11
	v_exp_f32_e32 v12, v12
	v_exp_f32_e32 v13, v13
	v_add_f32_e32 v171, v171, v6
	v_add_f32_e32 v170, v170, v7
	v_add_f32_e32 v171, v171, v8
	v_add_f32_e32 v170, v170, v9
	v_fma_f32 v14, v14, s46, v175
	v_fma_f32 v15, v15, s46, v175
	v_fma_f32 v16, v16, s46, v175
	v_fma_f32 v17, v17, s46, v175
	v_exp_f32_e32 v14, v14
	v_exp_f32_e32 v15, v15
	v_exp_f32_e32 v16, v16
	v_exp_f32_e32 v17, v17
	v_add_f32_e32 v171, v171, v10
	v_add_f32_e32 v170, v170, v11
	v_add_f32_e32 v171, v171, v12
	v_add_f32_e32 v170, v170, v13
	v_fma_f32 v18, v18, s46, v175
	v_fma_f32 v19, v19, s46, v175
	v_fma_f32 v20, v20, s46, v175
	v_fma_f32 v21, v21, s46, v175
	v_exp_f32_e32 v18, v18
	v_exp_f32_e32 v19, v19
	v_exp_f32_e32 v20, v20
	v_exp_f32_e32 v21, v21
	v_add_f32_e32 v171, v171, v14
	v_add_f32_e32 v170, v170, v15
	v_add_f32_e32 v171, v171, v16
	v_add_f32_e32 v170, v170, v17
	v_fma_f32 v22, v22, s46, v175
	v_fma_f32 v23, v23, s46, v175
	v_fma_f32 v24, v24, s46, v175
	v_fma_f32 v25, v25, s46, v175
	v_exp_f32_e32 v22, v22
	v_exp_f32_e32 v23, v23
	v_exp_f32_e32 v24, v24
	v_exp_f32_e32 v25, v25
	v_add_f32_e32 v171, v171, v18
	v_add_f32_e32 v170, v170, v19
	v_add_f32_e32 v171, v171, v20
	v_add_f32_e32 v170, v170, v21
	v_fma_f32 v26, v26, s46, v175
	v_fma_f32 v27, v27, s46, v175
	v_fma_f32 v28, v28, s46, v175
	v_fma_f32 v29, v29, s46, v175
	v_exp_f32_e32 v26, v26
	v_exp_f32_e32 v27, v27
	v_exp_f32_e32 v28, v28
	v_exp_f32_e32 v29, v29
	v_add_f32_e32 v171, v171, v22
	v_add_f32_e32 v170, v170, v23
	v_add_f32_e32 v171, v171, v24
	v_add_f32_e32 v170, v170, v25
	v_fma_f32 v30, v30, s46, v175
	v_fma_f32 v31, v31, s46, v175
	v_fma_f32 v32, v32, s46, v175
	v_fma_f32 v33, v33, s46, v175
	v_exp_f32_e32 v30, v30
	v_exp_f32_e32 v31, v31
	v_exp_f32_e32 v32, v32
	v_exp_f32_e32 v33, v33
	v_add_f32_e32 v171, v171, v26
	v_add_f32_e32 v170, v170, v27
	v_add_f32_e32 v171, v171, v28
	v_add_f32_e32 v170, v170, v29
	v_fma_f32 v34, v34, s46, v175
	v_fma_f32 v35, v35, s46, v175
	v_fma_f32 v36, v36, s46, v175
	v_fma_f32 v37, v37, s46, v175
	v_exp_f32_e32 v34, v34
	v_exp_f32_e32 v35, v35
	v_exp_f32_e32 v36, v36
	v_exp_f32_e32 v37, v37
	v_add_f32_e32 v171, v171, v30
	v_add_f32_e32 v170, v170, v31
	v_add_f32_e32 v171, v171, v32
	v_add_f32_e32 v170, v170, v33
	v_fma_f32 v38, v38, s46, v175
	v_fma_f32 v39, v39, s46, v175
	v_fma_f32 v40, v40, s46, v175
	v_fma_f32 v41, v41, s46, v175
	v_exp_f32_e32 v38, v38
	v_exp_f32_e32 v39, v39
	v_exp_f32_e32 v40, v40
	v_exp_f32_e32 v41, v41
	v_add_f32_e32 v171, v171, v34
	v_add_f32_e32 v170, v170, v35
	v_add_f32_e32 v171, v171, v36
	v_add_f32_e32 v170, v170, v37
	v_fma_f32 v42, v42, s46, v175
	v_fma_f32 v43, v43, s46, v175
	v_fma_f32 v44, v44, s46, v175
	v_fma_f32 v45, v45, s46, v175
	v_exp_f32_e32 v42, v42
; __device__ __forceinline__ unsigned cvt_pk_bf16_asm(float lo, float hi) { unsigned r; asm volatile("v_cvt_pk_bf16_f32 %0, %1, %2" : "=v"(r) : "v"(lo), "v"(hi)); return r; }
; __device__ __forceinline__ f32x4 mfma16(bf16x8 a, bf16x8 b, f32x4 c) { return __builtin_amdgcn_mfma_f32_16x16x32_bf16(a, b, c, 0, 0, 0); }
; __device__ void att_phase(int wv, const Params& p, unsigned char* lds) {
;     ...
;             for (int cb = 0; cb < 24; ++cb)
; #pragma unroll
;                 for (int j = 0; j < 4; ++j) { const float e = __expf(sc[cb][j] - mx); sc[cb][j] = e; sum += e; }
;             sum += __shfl_xor(sum, 16); sum += __shfl_xor(sum, 32);
;             sum += __expf(sink - mx);
;             const float inv = 1.0f / sum;
;             f32x4 oa[4];
; #pragma unroll
;             for (int db = 0; db < 4; ++db) oa[db] = (f32x4){0, 0, 0, 0};
; #pragma unroll
;             for (int ks = 0; ks < 12; ++ks) {
;                 union { bf16x8 v; unsigned u[4]; } pf;
;                 pf.u[0] = cvt_pk_bf16_asm(sc[2 * ks][0], sc[2 * ks][1]); pf.u[1] = cvt_pk_bf16_asm(sc[2 * ks][2], sc[2 * ks][3]);
;                 pf.u[2] = cvt_pk_bf16_asm(sc[2 * ks + 1][0], sc[2 * ks + 1][1]); pf.u[3] = cvt_pk_bf16_asm(sc[2 * ks + 1][2], sc[2 * ks + 1][3]);
; #pragma unroll
;                 for (int db = 0; db < 4; ++db) {
;                     union { bf16x8 v; u32x2 h2[2]; } vf;
;                     const bf16_t* vp = VTL + (16 * db + lr) * VP + 32 * ks + 4 * lq;
;                     vf.h2[0] = *(const u32x2*)vp; vf.h2[1] = *(const u32x2*)(vp + 16);
;                     oa[db] = mfma16(vf.v, pf.v, oa[db]); } }
	v_exp_f32_e32 v43, v43
	v_exp_f32_e32 v44, v44
	v_exp_f32_e32 v45, v45
	v_add_f32_e32 v171, v171, v38
	v_add_f32_e32 v170, v170, v39
	v_add_f32_e32 v171, v171, v40
	v_add_f32_e32 v170, v170, v41
	v_fma_f32 v46, v46, s46, v175
	v_fma_f32 v47, v47, s46, v175
	v_fma_f32 v48, v48, s46, v175
	v_fma_f32 v49, v49, s46, v175
	v_exp_f32_e32 v46, v46
	v_exp_f32_e32 v47, v47
	v_exp_f32_e32 v48, v48
	v_exp_f32_e32 v49, v49
	v_add_f32_e32 v171, v171, v42
	v_add_f32_e32 v170, v170, v43
	v_add_f32_e32 v171, v171, v44
	v_add_f32_e32 v170, v170, v45
	v_fma_f32 v50, v50, s46, v175
	v_fma_f32 v51, v51, s46, v175
	v_fma_f32 v52, v52, s46, v175
	v_fma_f32 v53, v53, s46, v175
	v_exp_f32_e32 v50, v50
	v_exp_f32_e32 v51, v51
	v_exp_f32_e32 v52, v52
	v_exp_f32_e32 v53, v53
	v_add_f32_e32 v171, v171, v46
	v_add_f32_e32 v170, v170, v47
	v_add_f32_e32 v171, v171, v48
	v_add_f32_e32 v170, v170, v49
	v_fma_f32 v54, v54, s46, v175
	v_fma_f32 v55, v55, s46, v175
	v_fma_f32 v56, v56, s46, v175
	v_fma_f32 v57, v57, s46, v175
	v_exp_f32_e32 v54, v54
	v_exp_f32_e32 v55, v55
	v_exp_f32_e32 v56, v56
	v_exp_f32_e32 v57, v57
	v_add_f32_e32 v171, v171, v50
	v_add_f32_e32 v170, v170, v51
	v_add_f32_e32 v171, v171, v52
	v_add_f32_e32 v170, v170, v53
	v_fma_f32 v58, v58, s46, v175
	v_fma_f32 v59, v59, s46, v175
	v_fma_f32 v60, v60, s46, v175
	v_fma_f32 v61, v61, s46, v175
	v_exp_f32_e32 v58, v58
	v_exp_f32_e32 v59, v59
	v_exp_f32_e32 v60, v60
	v_exp_f32_e32 v61, v61
	v_add_f32_e32 v171, v171, v54
	v_add_f32_e32 v170, v170, v55
	v_add_f32_e32 v171, v171, v56
	v_add_f32_e32 v170, v170, v57
	v_fma_f32 v62, v62, s46, v175
	v_fma_f32 v63, v63, s46, v175
	v_fma_f32 v64, v64, s46, v175
	v_fma_f32 v65, v65, s46, v175
	v_exp_f32_e32 v62, v62
	v_exp_f32_e32 v63, v63
	v_exp_f32_e32 v64, v64
	v_exp_f32_e32 v65, v65
	v_add_f32_e32 v171, v171, v58
	v_add_f32_e32 v170, v170, v59
	v_add_f32_e32 v171, v171, v60
	v_add_f32_e32 v170, v170, v61
	v_fma_f32 v66, v66, s46, v175
	v_fma_f32 v67, v67, s46, v175
	v_fma_f32 v68, v68, s46, v175
	v_fma_f32 v69, v69, s46, v175
	v_exp_f32_e32 v66, v66
	v_exp_f32_e32 v67, v67
	v_exp_f32_e32 v68, v68
	v_exp_f32_e32 v69, v69
	v_add_f32_e32 v171, v171, v62
	v_add_f32_e32 v170, v170, v63
	v_add_f32_e32 v171, v171, v64
	v_add_f32_e32 v170, v170, v65
	v_add_f32_e32 v171, v171, v66
	v_add_f32_e32 v170, v170, v67
	v_add_f32_e32 v171, v171, v68
	v_add_f32_e32 v170, v170, v69
	v_add_f32_e32 v170, v170, v171
	v_cvt_pk_bf16_f32 v2, v2, v3
	v_cvt_pk_bf16_f32 v3, v4, v5
	v_cvt_pk_bf16_f32 v4, v6, v7
	v_cvt_pk_bf16_f32 v5, v8, v9
	v_cvt_pk_bf16_f32 v10, v10, v11
	v_cvt_pk_bf16_f32 v11, v12, v13
	v_cvt_pk_bf16_f32 v12, v14, v15
	v_cvt_pk_bf16_f32 v13, v16, v17
	v_cvt_pk_bf16_f32 v18, v18, v19
	v_cvt_pk_bf16_f32 v19, v20, v21
	v_cvt_pk_bf16_f32 v20, v22, v23
	v_cvt_pk_bf16_f32 v21, v24, v25
	v_cvt_pk_bf16_f32 v26, v26, v27
	v_cvt_pk_bf16_f32 v27, v28, v29
	v_cvt_pk_bf16_f32 v28, v30, v31
	v_cvt_pk_bf16_f32 v29, v32, v33
	v_cvt_pk_bf16_f32 v34, v34, v35
	v_cvt_pk_bf16_f32 v35, v36, v37
	v_cvt_pk_bf16_f32 v36, v38, v39
	v_cvt_pk_bf16_f32 v37, v40, v41
	v_cvt_pk_bf16_f32 v42, v42, v43
	v_cvt_pk_bf16_f32 v43, v44, v45
	v_cvt_pk_bf16_f32 v44, v46, v47
	v_cvt_pk_bf16_f32 v45, v48, v49
	v_cvt_pk_bf16_f32 v50, v50, v51
	v_cvt_pk_bf16_f32 v51, v52, v53
	v_cvt_pk_bf16_f32 v52, v54, v55
	v_cvt_pk_bf16_f32 v53, v56, v57
	v_cvt_pk_bf16_f32 v58, v58, v59
	v_cvt_pk_bf16_f32 v59, v60, v61
	v_cvt_pk_bf16_f32 v60, v62, v63
	v_cvt_pk_bf16_f32 v61, v64, v65
	v_cvt_pk_bf16_f32 v66, v66, v67
	v_cvt_pk_bf16_f32 v67, v68, v69
	v_mov_b32_e32 v68, 0
	v_mov_b32_e32 v69, 0
	ds_bpermute_b32 v172, v1, v170
	v_sub_f32_e32 v173, v146, v169
	v_mul_f32_e32 v173, 0x3fb8aa3b, v173
	v_exp_f32_e32 v173, v173
	s_waitcnt lgkmcnt(0)
	v_add_f32_e32 v170, v170, v172
	ds_bpermute_b32 v172, v114, v170
	ds_read2_b64 v[232:235], v165 offset0:16 offset1:20
	ds_read2_b64 v[236:239], v166 offset0:16 offset1:20
	ds_read2_b64 v[240:243], v167 offset0:16 offset1:20
	ds_read2_b64 v[244:247], v168 offset0:16 offset1:20
	s_waitcnt lgkmcnt(4)
	v_mfma_f32_16x16x32_bf16 v[70:73], v[216:219], v[2:5], 0
	v_mfma_f32_16x16x32_bf16 v[74:77], v[220:223], v[2:5], 0
	v_mfma_f32_16x16x32_bf16 v[78:81], v[224:227], v[2:5], 0
	v_mfma_f32_16x16x32_bf16 v[82:85], v[228:231], v[2:5], 0
	v_add_f32_e32 v170, v170, v172
	v_add_f32_e32 v170, v170, v173
	v_rcp_f32_e32 v147, v170
	s_nop 0
	v_fma_f32 v179, -v170, v147, 1.0
	v_fmac_f32_e32 v147, v179, v147
	ds_read2_b64 v[216:219], v165 offset0:24 offset1:28
	ds_read2_b64 v[220:223], v166 offset0:24 offset1:28
	ds_read2_b64 v[224:227], v167 offset0:24 offset1:28
	ds_read2_b64 v[228:231], v168 offset0:24 offset1:28
	s_waitcnt lgkmcnt(4)
	v_mfma_f32_16x16x32_bf16 v[70:73], v[232:235], v[10:13], v[70:73]
	v_mfma_f32_16x16x32_bf16 v[74:77], v[236:239], v[10:13], v[74:77]
	v_mfma_f32_16x16x32_bf16 v[78:81], v[240:243], v[10:13], v[78:81]
	v_mfma_f32_16x16x32_bf16 v[82:85], v[244:247], v[10:13], v[82:85]
	ds_read2_b64 v[232:235], v165 offset0:32 offset1:36
	ds_read2_b64 v[236:239], v166 offset0:32 offset1:36
	ds_read2_b64 v[240:243], v167 offset0:32 offset1:36
	ds_read2_b64 v[244:247], v168 offset0:32 offset1:36
	s_waitcnt lgkmcnt(4)
	v_mfma_f32_16x16x32_bf16 v[70:73], v[216:219], v[18:21], v[70:73]
	v_mfma_f32_16x16x32_bf16 v[74:77], v[220:223], v[18:21], v[74:77]
	v_mfma_f32_16x16x32_bf16 v[78:81], v[224:227], v[18:21], v[78:81]
	v_mfma_f32_16x16x32_bf16 v[82:85], v[228:231], v[18:21], v[82:85]
	ds_read2_b64 v[216:219], v165 offset0:40 offset1:44
	ds_read2_b64 v[220:223], v166 offset0:40 offset1:44
	ds_read2_b64 v[224:227], v167 offset0:40 offset1:44
	ds_read2_b64 v[228:231], v168 offset0:40 offset1:44
	s_waitcnt lgkmcnt(4)
; __device__ __forceinline__ unsigned cvt_pk_bf16_asm(float lo, float hi) { unsigned r; asm volatile("v_cvt_pk_bf16_f32 %0, %1, %2" : "=v"(r) : "v"(lo), "v"(hi)); return r; }
; __device__ __forceinline__ f32x4 mfma16(bf16x8 a, bf16x8 b, f32x4 c) { return __builtin_amdgcn_mfma_f32_16x16x32_bf16(a, b, c, 0, 0, 0); }
; __device__ void att_phase(int wv, const Params& p, unsigned char* lds) {
;     ...
;         for (int rb = 0; rb < 4; ++rb) {
;             const int qrow = 64 * (w & 1) + 16 * rb + lr;
;             const size_t tokq = (size_t)B * 128 + qrow;
;             bf16x8 qf[2];
; #pragma unroll
;             for (int kk = 0; kk < 2; ++kk) qf[kk] = *(const bf16x8*)(qkv + tokq * 1536 + 64 * h + 32 * kk + 8 * lq);
;             f32x4 sc[24];
; #pragma unroll
;             for (int cb = 0; cb < 24; ++cb) { f32x4 a = {0, 0, 0, 0};
; #pragma unroll
;                 for (int kk = 0; kk < 2; ++kk) { const bf16x8 kf = *(const bf16x8*)(KL + (16 * cb + lr) * KP + 32 * kk + 8 * lq); a = mfma16(kf, qf[kk], a); }
;                 sc[cb] = a; }
;             float mx = sink;
; #pragma unroll
;             for (int cb = 0; cb < 24; ++cb) { const int kb = B - 1 + (cb >> 3); const bool bval = (kb >= sb && kb < se);
; #pragma unroll
;                 for (int j = 0; j < 4; ++j) { const int krel = 16 * cb + 4 * lq + j - 128;
;                     int dist = qrow - krel; dist = dist < 0 ? -dist : dist;
;                     const float v = (bval && dist <= 128) ? sc[cb][j] * 0.125f - slope * (float)dist : -1e30f;
;                     sc[cb][j] = v; mx = fmaxf(mx, v); } }
;     ...
;                 for (int db = 0; db < 4; ++db) {
;                     union { bf16x8 v; u32x2 h2[2]; } vf;
;                     const bf16_t* vp = VTL + (16 * db + lr) * VP + 32 * ks + 4 * lq;
;                     vf.h2[0] = *(const u32x2*)vp; vf.h2[1] = *(const u32x2*)(vp + 16);
;                     oa[db] = mfma16(vf.v, pf.v, oa[db]); } }
; #pragma unroll
;             for (int db = 0; db < 4; ++db) { const f32x4 o = oa[db] * inv; u32x2 wv; wv.x = cvt_pk_bf16_asm(o[0], o[1]); wv.y = cvt_pk_bf16_asm(o[2], o[3]);
;                 *(u32x2*)(qkv + tokq * 1536 + 64 * h + 16 * db + 4 * lq) = wv; }
	v_mfma_f32_16x16x32_bf16 v[70:73], v[232:235], v[26:29], v[70:73]
	v_mfma_f32_16x16x32_bf16 v[74:77], v[236:239], v[26:29], v[74:77]
	v_mfma_f32_16x16x32_bf16 v[78:81], v[240:243], v[26:29], v[78:81]
	v_mfma_f32_16x16x32_bf16 v[82:85], v[244:247], v[26:29], v[82:85]
	ds_read2_b64 v[232:235], v165 offset0:48 offset1:52
	ds_read2_b64 v[236:239], v166 offset0:48 offset1:52
	ds_read2_b64 v[240:243], v167 offset0:48 offset1:52
	ds_read2_b64 v[244:247], v168 offset0:48 offset1:52
	s_waitcnt lgkmcnt(4)
	v_mfma_f32_16x16x32_bf16 v[70:73], v[216:219], v[34:37], v[70:73]
	v_mfma_f32_16x16x32_bf16 v[74:77], v[220:223], v[34:37], v[74:77]
	v_mfma_f32_16x16x32_bf16 v[78:81], v[224:227], v[34:37], v[78:81]
	v_mfma_f32_16x16x32_bf16 v[82:85], v[228:231], v[34:37], v[82:85]
	ds_read2_b64 v[216:219], v165 offset0:56 offset1:60
	ds_read2_b64 v[220:223], v166 offset0:56 offset1:60
	ds_read2_b64 v[224:227], v167 offset0:56 offset1:60
	ds_read2_b64 v[228:231], v168 offset0:56 offset1:60
	s_waitcnt lgkmcnt(4)
	v_mfma_f32_16x16x32_bf16 v[70:73], v[232:235], v[42:45], v[70:73]
	v_mfma_f32_16x16x32_bf16 v[74:77], v[236:239], v[42:45], v[74:77]
	v_mfma_f32_16x16x32_bf16 v[78:81], v[240:243], v[42:45], v[78:81]
	v_mfma_f32_16x16x32_bf16 v[82:85], v[244:247], v[42:45], v[82:85]
	ds_read2_b64 v[232:235], v165 offset0:64 offset1:68
	ds_read2_b64 v[236:239], v166 offset0:64 offset1:68
	ds_read2_b64 v[240:243], v167 offset0:64 offset1:68
	ds_read2_b64 v[244:247], v168 offset0:64 offset1:68
	s_waitcnt lgkmcnt(4)
	v_mfma_f32_16x16x32_bf16 v[70:73], v[216:219], v[50:53], v[70:73]
	v_mfma_f32_16x16x32_bf16 v[74:77], v[220:223], v[50:53], v[74:77]
	v_mfma_f32_16x16x32_bf16 v[78:81], v[224:227], v[50:53], v[78:81]
	v_mfma_f32_16x16x32_bf16 v[82:85], v[228:231], v[50:53], v[82:85]
	ds_read2_b64 v[216:219], v165 offset0:72 offset1:72
	ds_read2_b64 v[220:223], v166 offset0:72 offset1:72
	ds_read2_b64 v[224:227], v167 offset0:72 offset1:72
	ds_read2_b64 v[228:231], v168 offset0:72 offset1:72
	s_waitcnt lgkmcnt(4)
	v_mfma_f32_16x16x32_bf16 v[70:73], v[232:235], v[58:61], v[70:73]
	v_mfma_f32_16x16x32_bf16 v[74:77], v[236:239], v[58:61], v[74:77]
	v_mfma_f32_16x16x32_bf16 v[78:81], v[240:243], v[58:61], v[78:81]
	v_mfma_f32_16x16x32_bf16 v[82:85], v[244:247], v[58:61], v[82:85]
	s_waitcnt lgkmcnt(0)
	v_mfma_f32_16x16x32_bf16 v[70:73], v[216:219], v[66:69], v[70:73]
	v_mfma_f32_16x16x32_bf16 v[74:77], v[220:223], v[66:69], v[74:77]
	v_mfma_f32_16x16x32_bf16 v[78:81], v[224:227], v[66:69], v[78:81]
	v_mfma_f32_16x16x32_bf16 v[82:85], v[228:231], v[66:69], v[82:85]
	s_nop 7
	s_nop 1
	v_mul_f32_e32 v70, v70, v147
	v_mul_f32_e32 v71, v71, v147
	v_mul_f32_e32 v72, v72, v147
	v_mul_f32_e32 v73, v73, v147
	v_mul_f32_e32 v74, v74, v147
	v_mul_f32_e32 v75, v75, v147
	v_mul_f32_e32 v76, v76, v147
	v_mul_f32_e32 v77, v77, v147
	v_mul_f32_e32 v78, v78, v147
	v_mul_f32_e32 v79, v79, v147
	v_mul_f32_e32 v80, v80, v147
	v_mul_f32_e32 v81, v81, v147
	v_mul_f32_e32 v82, v82, v147
	v_mul_f32_e32 v83, v83, v147
	v_mul_f32_e32 v84, v84, v147
	v_mul_f32_e32 v85, v85, v147
	v_cvt_pk_bf16_f32 v70, v70, v71
	v_cvt_pk_bf16_f32 v71, v72, v73
	v_cvt_pk_bf16_f32 v74, v74, v75
	v_cvt_pk_bf16_f32 v75, v76, v77
	v_cvt_pk_bf16_f32 v78, v78, v79
	v_cvt_pk_bf16_f32 v79, v80, v81
	v_cvt_pk_bf16_f32 v82, v82, v83
	v_cvt_pk_bf16_f32 v83, v84, v85
	global_store_dwordx2 v[248:249], v[70:71], off offset:-64
	global_store_dwordx2 v[248:249], v[74:75], off offset:-32
	global_store_dwordx2 v[248:249], v[78:79], off
	global_store_dwordx2 v[248:249], v[82:83], off offset:32
	v_lshl_add_u64 v[248:249], v[248:249], 0, s[48:49]
	v_sub_f32_e32 v86, v94, v176
	v_sub_f32_e32 v87, v95, v176
	v_sub_f32_e32 v88, v96, v176
	v_sub_f32_e32 v89, v97, v176
	v_cmp_ge_i32_e32 vcc, 0, v108
	s_nop 1
	v_cndmask_b32_e32 v212, v252, v86, vcc
	v_cmp_ge_i32_e32 vcc, 0, v110
	s_nop 1
	v_cndmask_b32_e32 v213, v252, v87, vcc
	v_cmp_ge_i32_e32 vcc, 0, v111
	s_nop 1
	v_cndmask_b32_e32 v214, v252, v88, vcc
	v_cmp_ge_i32_e32 vcc, 0, v177
	s_nop 1
	v_cndmask_b32_e32 v215, v252, v89, vcc
	ds_read_b128 v[148:151], v164 offset:6912
	ds_read_b128 v[152:155], v164 offset:6976
	ds_read_b128 v[156:159], v164 offset:9216
	ds_read_b128 v[160:163], v164 offset:9280
	v_add_f32_e32 v90, v86, v174
	v_add_f32_e32 v91, v87, v174
	v_add_f32_e32 v92, v88, v174
	v_add_f32_e32 v93, v89, v174
	s_cmp_lt_i32 s47, 13
	s_cselect_b64 vcc, -1, s[10:11]
	s_cmp_lt_i32 s47, 5
	s_cselect_b64 vcc, s[6:7], vcc
	v_cndmask_b32_e32 v232, v252, v212, vcc
	v_cndmask_b32_e32 v233, v252, v213, vcc
	v_cndmask_b32_e32 v234, v252, v214, vcc
	v_cndmask_b32_e32 v235, v252, v215, vcc
	s_waitcnt lgkmcnt(2)
	v_mfma_f32_16x16x32_bf16 v[2:5], v[148:151], v[204:207], v[232:235]
	v_mfma_f32_16x16x32_bf16 v[2:5], v[152:155], v[208:211], v[2:5]
	ds_read_b128 v[148:151], v164 offset:11520
	ds_read_b128 v[152:155], v164 offset:11584
	v_add_f32_e32 v86, v90, v174
	v_add_f32_e32 v87, v91, v174
	v_add_f32_e32 v88, v92, v174
	v_add_f32_e32 v89, v93, v174
	s_cmp_lt_i32 s47, 12
	s_cselect_b64 vcc, -1, s[10:11]
	s_cmp_lt_i32 s47, 4
	s_cselect_b64 vcc, s[6:7], vcc
	v_cndmask_b32_e32 v236, v252, v90, vcc
	v_cndmask_b32_e32 v237, v252, v91, vcc
	v_cndmask_b32_e32 v238, v252, v92, vcc
	v_cndmask_b32_e32 v239, v252, v93, vcc
	s_waitcnt lgkmcnt(2)
	v_mfma_f32_16x16x32_bf16 v[6:9], v[156:159], v[204:207], v[236:239]
	v_mfma_f32_16x16x32_bf16 v[6:9], v[160:163], v[208:211], v[6:9]
	ds_read_b128 v[156:159], v164 offset:13824
	ds_read_b128 v[160:163], v164 offset:13888
	v_add_f32_e32 v90, v86, v174
	v_add_f32_e32 v91, v87, v174
	v_add_f32_e32 v92, v88, v174
	v_add_f32_e32 v93, v89, v174
	s_cmp_lt_i32 s47, 11
	s_cselect_b64 vcc, -1, s[10:11]
	s_cmp_lt_i32 s47, 3
	s_cselect_b64 vcc, s[6:7], vcc
	v_cndmask_b32_e32 v232, v252, v86, vcc
	v_cndmask_b32_e32 v233, v252, v87, vcc
	v_cndmask_b32_e32 v234, v252, v88, vcc
	v_cndmask_b32_e32 v235, v252, v89, vcc
	s_waitcnt lgkmcnt(2)
; __device__ __forceinline__ f32x4 mfma16(bf16x8 a, bf16x8 b, f32x4 c) { return __builtin_amdgcn_mfma_f32_16x16x32_bf16(a, b, c, 0, 0, 0); }
; __device__ void att_phase(int wv, const Params& p, unsigned char* lds) {
;     ...
; #pragma unroll
;             for (int cb = 0; cb < 24; ++cb) { f32x4 a = {0, 0, 0, 0};
; #pragma unroll
;                 for (int kk = 0; kk < 2; ++kk) { const bf16x8 kf = *(const bf16x8*)(KL + (16 * cb + lr) * KP + 32 * kk + 8 * lq); a = mfma16(kf, qf[kk], a); }
;                 sc[cb] = a; }
;             float mx = sink;
; #pragma unroll
;             for (int cb = 0; cb < 24; ++cb) { const int kb = B - 1 + (cb >> 3); const bool bval = (kb >= sb && kb < se);
; #pragma unroll
;                 for (int j = 0; j < 4; ++j) { const int krel = 16 * cb + 4 * lq + j - 128;
;                     int dist = qrow - krel; dist = dist < 0 ? -dist : dist;
;                     const float v = (bval && dist <= 128) ? sc[cb][j] * 0.125f - slope * (float)dist : -1e30f;
;                     sc[cb][j] = v; mx = fmaxf(mx, v); } }
	v_mfma_f32_16x16x32_bf16 v[10:13], v[148:151], v[204:207], v[232:235]
	v_mfma_f32_16x16x32_bf16 v[10:13], v[152:155], v[208:211], v[10:13]
	ds_read_b128 v[148:151], v164 offset:16128
	ds_read_b128 v[152:155], v164 offset:16192
	v_add_f32_e32 v86, v90, v174
	v_add_f32_e32 v87, v91, v174
	v_add_f32_e32 v88, v92, v174
	v_add_f32_e32 v89, v93, v174
	s_cmp_lt_i32 s47, 10
	s_cselect_b64 vcc, -1, s[10:11]
	s_cmp_lt_i32 s47, 2
	s_cselect_b64 vcc, s[6:7], vcc
	v_cndmask_b32_e32 v236, v252, v90, vcc
	v_cndmask_b32_e32 v237, v252, v91, vcc
	v_cndmask_b32_e32 v238, v252, v92, vcc
	v_cndmask_b32_e32 v239, v252, v93, vcc
	s_waitcnt lgkmcnt(2)
	v_mfma_f32_16x16x32_bf16 v[14:17], v[156:159], v[204:207], v[236:239]
	v_mfma_f32_16x16x32_bf16 v[14:17], v[160:163], v[208:211], v[14:17]
	ds_read_b128 v[156:159], v164 offset:18432
	ds_read_b128 v[160:163], v164 offset:18496
	v_add_f32_e32 v90, v86, v174
	v_add_f32_e32 v91, v87, v174
	v_add_f32_e32 v92, v88, v174
	v_add_f32_e32 v93, v89, v174
	s_cmp_lt_i32 s47, 9
	s_cselect_b64 vcc, -1, s[10:11]
	s_cmp_lt_i32 s47, 1
	s_cselect_b64 vcc, s[6:7], vcc
	v_cndmask_b32_e32 v232, v252, v86, vcc
	v_cndmask_b32_e32 v233, v252, v87, vcc
	v_cndmask_b32_e32 v234, v252, v88, vcc
	v_cndmask_b32_e32 v235, v252, v89, vcc
	s_waitcnt lgkmcnt(2)
	v_mfma_f32_16x16x32_bf16 v[18:21], v[148:151], v[204:207], v[232:235]
	v_mfma_f32_16x16x32_bf16 v[18:21], v[152:155], v[208:211], v[18:21]
	ds_read_b128 v[148:151], v164 offset:20736
	ds_read_b128 v[152:155], v164 offset:20800
	v_add_f32_e32 v86, v90, v174
	v_add_f32_e32 v87, v91, v174
	v_add_f32_e32 v88, v92, v174
	v_add_f32_e32 v89, v93, v174
	s_waitcnt lgkmcnt(2)
	v_mfma_f32_16x16x32_bf16 v[22:25], v[156:159], v[204:207], v[90:93]
	v_mfma_f32_16x16x32_bf16 v[22:25], v[160:163], v[208:211], v[22:25]
	ds_read_b128 v[156:159], v164 offset:23040
	ds_read_b128 v[160:163], v164 offset:23104
	v_add_f32_e32 v90, v86, v174
	v_add_f32_e32 v91, v87, v174
	v_add_f32_e32 v92, v88, v174
	v_add_f32_e32 v93, v89, v174
	s_waitcnt lgkmcnt(2)
	v_mfma_f32_16x16x32_bf16 v[26:29], v[148:151], v[204:207], v[86:89]
	v_mfma_f32_16x16x32_bf16 v[26:29], v[152:155], v[208:211], v[26:29]
	ds_read_b128 v[148:151], v164 offset:25344
	ds_read_b128 v[152:155], v164 offset:25408
	s_waitcnt lgkmcnt(2)
	v_mfma_f32_16x16x32_bf16 v[30:33], v[156:159], v[204:207], v[90:93]
	v_mfma_f32_16x16x32_bf16 v[30:33], v[160:163], v[208:211], v[30:33]
	ds_read_b128 v[156:159], v164 offset:27648
	ds_read_b128 v[160:163], v164 offset:27712
	v_sub_f32_e64 v86, -v94, v174
	v_sub_f32_e64 v87, -v95, v174
	v_sub_f32_e64 v88, -v96, v174
	v_sub_f32_e64 v89, -v97, v174
	s_waitcnt lgkmcnt(2)
	v_mfma_f32_16x16x32_bf16 v[34:37], v[148:151], v[204:207], v[98:101]
	v_mfma_f32_16x16x32_bf16 v[34:37], v[152:155], v[208:211], v[34:37]
	ds_read_b128 v[148:151], v164 offset:29952
	ds_read_b128 v[152:155], v164 offset:30016
	v_sub_f32_e32 v90, v86, v174
	v_sub_f32_e32 v91, v87, v174
	v_sub_f32_e32 v92, v88, v174
	v_sub_f32_e32 v93, v89, v174
	s_cmp_lt_i32 s47, 4
	s_cselect_b64 vcc, -1, s[10:11]
	s_cmp_lt_i32 s47, -4
	s_cselect_b64 vcc, s[6:7], vcc
	v_cndmask_b32_e32 v236, v252, v86, vcc
	v_cndmask_b32_e32 v237, v252, v87, vcc
	v_cndmask_b32_e32 v238, v252, v88, vcc
	v_cndmask_b32_e32 v239, v252, v89, vcc
	s_waitcnt lgkmcnt(2)
	v_mfma_f32_16x16x32_bf16 v[38:41], v[156:159], v[204:207], v[236:239]
	v_mfma_f32_16x16x32_bf16 v[38:41], v[160:163], v[208:211], v[38:41]
	ds_read_b128 v[156:159], v164 offset:32256
	ds_read_b128 v[160:163], v164 offset:32320
	v_sub_f32_e32 v86, v90, v174
	v_sub_f32_e32 v87, v91, v174
	v_sub_f32_e32 v88, v92, v174
	v_sub_f32_e32 v89, v93, v174
	s_cmp_lt_i32 s47, 3
	s_cselect_b64 vcc, -1, s[10:11]
	s_cmp_lt_i32 s47, -5
	s_cselect_b64 vcc, s[6:7], vcc
	v_cndmask_b32_e32 v232, v252, v90, vcc
	v_cndmask_b32_e32 v233, v252, v91, vcc
	v_cndmask_b32_e32 v234, v252, v92, vcc
	v_cndmask_b32_e32 v235, v252, v93, vcc
	s_waitcnt lgkmcnt(2)
	v_mfma_f32_16x16x32_bf16 v[42:45], v[148:151], v[204:207], v[232:235]
	v_mfma_f32_16x16x32_bf16 v[42:45], v[152:155], v[208:211], v[42:45]
	ds_read_b128 v[148:151], v164 offset:34560
	ds_read_b128 v[152:155], v164 offset:34624
	v_sub_f32_e32 v90, v86, v174
	v_sub_f32_e32 v91, v87, v174
	v_sub_f32_e32 v92, v88, v174
	v_sub_f32_e32 v93, v89, v174
	s_cmp_lt_i32 s47, 2
	s_cselect_b64 vcc, -1, s[10:11]
	s_cmp_lt_i32 s47, -6
	s_cselect_b64 vcc, s[6:7], vcc
	v_cndmask_b32_e32 v236, v252, v86, vcc
	v_cndmask_b32_e32 v237, v252, v87, vcc
	v_cndmask_b32_e32 v238, v252, v88, vcc
	v_cndmask_b32_e32 v239, v252, v89, vcc
	s_waitcnt lgkmcnt(2)
	v_mfma_f32_16x16x32_bf16 v[46:49], v[156:159], v[204:207], v[236:239]
	v_mfma_f32_16x16x32_bf16 v[46:49], v[160:163], v[208:211], v[46:49]
	ds_read_b128 v[156:159], v164 offset:36864
	ds_read_b128 v[160:163], v164 offset:36928
	v_sub_f32_e32 v86, v90, v174
	v_sub_f32_e32 v87, v91, v174
	v_sub_f32_e32 v88, v92, v174
	v_sub_f32_e32 v89, v93, v174
	s_cmp_lt_i32 s47, 1
	s_cselect_b64 vcc, -1, s[10:11]
	s_cmp_lt_i32 s47, -7
	s_cselect_b64 vcc, s[6:7], vcc
	v_cndmask_b32_e32 v232, v252, v90, vcc
	v_cndmask_b32_e32 v233, v252, v91, vcc
	v_cndmask_b32_e32 v234, v252, v92, vcc
	v_cndmask_b32_e32 v235, v252, v93, vcc
	s_waitcnt lgkmcnt(2)
	v_mfma_f32_16x16x32_bf16 v[50:53], v[148:151], v[204:207], v[232:235]
	v_mfma_f32_16x16x32_bf16 v[50:53], v[152:155], v[208:211], v[50:53]
	ds_read_b128 v[148:151], v164 offset:39168
	ds_read_b128 v[152:155], v164 offset:39232
	v_sub_f32_e32 v90, v86, v174
	v_sub_f32_e32 v91, v87, v174
	v_sub_f32_e32 v92, v88, v174
	v_sub_f32_e32 v93, v89, v174
	s_cmp_lt_i32 s47, 0
	s_cselect_b64 vcc, -1, s[10:11]
	s_cmp_lt_i32 s47, -8
	s_cselect_b64 vcc, s[6:7], vcc
	v_cndmask_b32_e32 v236, v252, v86, vcc
	v_cndmask_b32_e32 v237, v252, v87, vcc
	v_cndmask_b32_e32 v238, v252, v88, vcc
	v_cndmask_b32_e32 v239, v252, v89, vcc
	s_waitcnt lgkmcnt(2)
; __device__ void att_phase(int wv, const Params& p, unsigned char* lds) {
;     ...
;             float mx = sink;
; #pragma unroll
;             for (int cb = 0; cb < 24; ++cb) { const int kb = B - 1 + (cb >> 3); const bool bval = (kb >= sb && kb < se);
; #pragma unroll
;                 for (int j = 0; j < 4; ++j) { const int krel = 16 * cb + 4 * lq + j - 128;
;                     int dist = qrow - krel; dist = dist < 0 ? -dist : dist;
;                     const float v = (bval && dist <= 128) ? sc[cb][j] * 0.125f - slope * (float)dist : -1e30f;
;                     sc[cb][j] = v; mx = fmaxf(mx, v); } }
;             mx = fmaxf(mx, __shfl_xor(mx, 16)); mx = fmaxf(mx, __shfl_xor(mx, 32));
;             float sum = 0.f;
; #pragma unroll
;             for (int cb = 0; cb < 24; ++cb)
; #pragma unroll
;                 for (int j = 0; j < 4; ++j) { const float e = __expf(sc[cb][j] - mx); sc[cb][j] = e; sum += e; }
	v_mfma_f32_16x16x32_bf16 v[54:57], v[156:159], v[204:207], v[236:239]
	v_mfma_f32_16x16x32_bf16 v[54:57], v[160:163], v[208:211], v[54:57]
	ds_read_b128 v[156:159], v164 offset:41472
	ds_read_b128 v[160:163], v164 offset:41536
	v_sub_f32_e32 v86, v90, v174
	v_sub_f32_e32 v87, v91, v174
	v_sub_f32_e32 v88, v92, v174
	v_sub_f32_e32 v89, v93, v174
	s_cmp_lt_i32 s47, -1
	s_cselect_b64 vcc, -1, s[10:11]
	s_cmp_lt_i32 s47, -9
	s_cselect_b64 vcc, s[6:7], vcc
	v_cndmask_b32_e32 v232, v252, v90, vcc
	v_cndmask_b32_e32 v233, v252, v91, vcc
	v_cndmask_b32_e32 v234, v252, v92, vcc
	v_cndmask_b32_e32 v235, v252, v93, vcc
	s_waitcnt lgkmcnt(2)
	v_mfma_f32_16x16x32_bf16 v[58:61], v[148:151], v[204:207], v[232:235]
	v_mfma_f32_16x16x32_bf16 v[58:61], v[152:155], v[208:211], v[58:61]
	ds_read_b128 v[148:151], v164 offset:43776
	ds_read_b128 v[152:155], v164 offset:43840
	v_sub_f32_e32 v90, v86, v174
	v_sub_f32_e32 v91, v87, v174
	v_sub_f32_e32 v92, v88, v174
	v_sub_f32_e32 v93, v89, v174
	v_cmp_le_i32_e32 vcc, 0, v108
	s_nop 1
	v_cndmask_b32_e32 v212, v252, v90, vcc
	v_cmp_le_i32_e32 vcc, 0, v110
	s_nop 1
	v_cndmask_b32_e32 v213, v252, v91, vcc
	v_cmp_le_i32_e32 vcc, 0, v111
	s_nop 1
	v_cndmask_b32_e32 v214, v252, v92, vcc
	v_cmp_le_i32_e32 vcc, 0, v177
	s_nop 1
	v_cndmask_b32_e32 v215, v252, v93, vcc
	s_cmp_lt_i32 s47, -2
	s_cselect_b64 vcc, -1, s[10:11]
	s_cmp_lt_i32 s47, -10
	s_cselect_b64 vcc, s[6:7], vcc
	v_cndmask_b32_e32 v236, v252, v86, vcc
	v_cndmask_b32_e32 v237, v252, v87, vcc
	v_cndmask_b32_e32 v238, v252, v88, vcc
	v_cndmask_b32_e32 v239, v252, v89, vcc
	s_waitcnt lgkmcnt(2)
	v_mfma_f32_16x16x32_bf16 v[62:65], v[156:159], v[204:207], v[236:239]
	v_mfma_f32_16x16x32_bf16 v[62:65], v[160:163], v[208:211], v[62:65]
	s_cmp_lt_i32 s47, -3
	s_cselect_b64 vcc, -1, s[10:11]
	s_cmp_lt_i32 s47, -11
	s_cselect_b64 vcc, s[6:7], vcc
	v_cndmask_b32_e32 v232, v252, v212, vcc
	v_cndmask_b32_e32 v233, v252, v213, vcc
	v_cndmask_b32_e32 v234, v252, v214, vcc
	v_cndmask_b32_e32 v235, v252, v215, vcc
	s_waitcnt lgkmcnt(0)
	v_mfma_f32_16x16x32_bf16 v[66:69], v[148:151], v[204:207], v[232:235]
	v_mfma_f32_16x16x32_bf16 v[66:69], v[152:155], v[208:211], v[66:69]
	ds_read2_b64 v[216:219], v165 offset0:12 offset1:16
	ds_read2_b64 v[220:223], v166 offset0:12 offset1:16
	ds_read2_b64 v[224:227], v167 offset0:12 offset1:16
	ds_read2_b64 v[228:231], v168 offset0:12 offset1:16
	v_max3_f32 v169, v2, v3, v4
	v_max3_f32 v172, v5, v6, v7
	v_max3_f32 v169, v8, v9, v169
	v_max3_f32 v172, v10, v11, v172
	v_max3_f32 v169, v12, v13, v169
	v_max3_f32 v172, v14, v15, v172
	v_max3_f32 v169, v16, v17, v169
	v_max3_f32 v172, v18, v19, v172
	v_max3_f32 v169, v20, v21, v169
	v_max3_f32 v172, v22, v23, v172
	v_max3_f32 v169, v24, v25, v169
	v_max3_f32 v172, v26, v27, v172
	v_max3_f32 v169, v28, v29, v169
	v_max3_f32 v172, v30, v31, v172
	v_max3_f32 v169, v32, v33, v169
	v_max3_f32 v172, v34, v35, v172
	v_max3_f32 v169, v36, v37, v169
	v_max3_f32 v172, v38, v39, v172
	v_max3_f32 v169, v40, v41, v169
	v_max3_f32 v172, v42, v43, v172
	v_max3_f32 v169, v44, v45, v169
	v_max3_f32 v172, v46, v47, v172
	v_max3_f32 v169, v48, v49, v169
	v_max3_f32 v172, v50, v51, v172
	v_max3_f32 v169, v52, v53, v169
	v_max3_f32 v172, v54, v55, v172
	v_max3_f32 v169, v56, v57, v169
	v_max3_f32 v172, v58, v59, v172
	v_max3_f32 v169, v60, v61, v169
	v_max3_f32 v172, v62, v63, v172
	v_max3_f32 v169, v64, v65, v169
	v_max3_f32 v172, v66, v67, v172
	v_max3_f32 v169, v68, v69, v169
	v_max_f32_e32 v169, v169, v172
	v_mul_f32_e32 v169, 0x3e000000, v169
	v_max_f32_e32 v169, v169, v146
	ds_bpermute_b32 v172, v1, v169
	s_waitcnt lgkmcnt(0)
	v_max_f32_e32 v169, v169, v172
	ds_bpermute_b32 v172, v114, v169
	s_waitcnt lgkmcnt(0)
	v_max_f32_e32 v169, v169, v172
	v_mul_f32_e32 v175, 0xbfb8aa3b, v169
	v_mov_b32_e32 v170, 0
	v_mov_b32_e32 v171, 0
	v_fma_f32 v2, v2, s46, v175
	v_fma_f32 v3, v3, s46, v175
	v_fma_f32 v4, v4, s46, v175
	v_fma_f32 v5, v5, s46, v175
	v_exp_f32_e32 v2, v2
	v_exp_f32_e32 v3, v3
	v_exp_f32_e32 v4, v4
	v_exp_f32_e32 v5, v5
	v_fma_f32 v6, v6, s46, v175
	v_fma_f32 v7, v7, s46, v175
	v_fma_f32 v8, v8, s46, v175
	v_fma_f32 v9, v9, s46, v175
	v_exp_f32_e32 v6, v6
	v_exp_f32_e32 v7, v7
	v_exp_f32_e32 v8, v8
	v_exp_f32_e32 v9, v9
	v_add_f32_e32 v171, v171, v2
	v_add_f32_e32 v170, v170, v3
	v_add_f32_e32 v171, v171, v4
	v_add_f32_e32 v170, v170, v5
	v_fma_f32 v10, v10, s46, v175
	v_fma_f32 v11, v11, s46, v175
	v_fma_f32 v12, v12, s46, v175
	v_fma_f32 v13, v13, s46, v175
	v_exp_f32_e32 v10, v10
	v_exp_f32_e32 v11, v11
	v_exp_f32_e32 v12, v12
	v_exp_f32_e32 v13, v13
	v_add_f32_e32 v171, v171, v6
	v_add_f32_e32 v170, v170, v7
	v_add_f32_e32 v171, v171, v8
	v_add_f32_e32 v170, v170, v9
	v_fma_f32 v14, v14, s46, v175
	v_fma_f32 v15, v15, s46, v175
	v_fma_f32 v16, v16, s46, v175
	v_fma_f32 v17, v17, s46, v175
	v_exp_f32_e32 v14, v14
	v_exp_f32_e32 v15, v15
	v_exp_f32_e32 v16, v16
	v_exp_f32_e32 v17, v17
	v_add_f32_e32 v171, v171, v10
	v_add_f32_e32 v170, v170, v11
	v_add_f32_e32 v171, v171, v12
	v_add_f32_e32 v170, v170, v13
	v_fma_f32 v18, v18, s46, v175
	v_fma_f32 v19, v19, s46, v175
	v_fma_f32 v20, v20, s46, v175
	v_fma_f32 v21, v21, s46, v175
	v_exp_f32_e32 v18, v18
	v_exp_f32_e32 v19, v19
	v_exp_f32_e32 v20, v20
	v_exp_f32_e32 v21, v21
	v_add_f32_e32 v171, v171, v14
	v_add_f32_e32 v170, v170, v15
	v_add_f32_e32 v171, v171, v16
	v_add_f32_e32 v170, v170, v17
	v_fma_f32 v22, v22, s46, v175
	v_fma_f32 v23, v23, s46, v175
	v_fma_f32 v24, v24, s46, v175
	v_fma_f32 v25, v25, s46, v175
	v_exp_f32_e32 v22, v22
	v_exp_f32_e32 v23, v23
	v_exp_f32_e32 v24, v24
	v_exp_f32_e32 v25, v25
	v_add_f32_e32 v171, v171, v18
; __device__ __forceinline__ unsigned cvt_pk_bf16_asm(float lo, float hi) { unsigned r; asm volatile("v_cvt_pk_bf16_f32 %0, %1, %2" : "=v"(r) : "v"(lo), "v"(hi)); return r; }
; __device__ void att_phase(int wv, const Params& p, unsigned char* lds) {
;     ...
;             for (int cb = 0; cb < 24; ++cb)
; #pragma unroll
;                 for (int j = 0; j < 4; ++j) { const float e = __expf(sc[cb][j] - mx); sc[cb][j] = e; sum += e; }
;             sum += __shfl_xor(sum, 16); sum += __shfl_xor(sum, 32);
;             sum += __expf(sink - mx);
;             const float inv = 1.0f / sum;
;             f32x4 oa[4];
; #pragma unroll
;             for (int db = 0; db < 4; ++db) oa[db] = (f32x4){0, 0, 0, 0};
; #pragma unroll
;             for (int ks = 0; ks < 12; ++ks) {
;                 union { bf16x8 v; unsigned u[4]; } pf;
;                 pf.u[0] = cvt_pk_bf16_asm(sc[2 * ks][0], sc[2 * ks][1]); pf.u[1] = cvt_pk_bf16_asm(sc[2 * ks][2], sc[2 * ks][3]);
;                 pf.u[2] = cvt_pk_bf16_asm(sc[2 * ks + 1][0], sc[2 * ks + 1][1]); pf.u[3] = cvt_pk_bf16_asm(sc[2 * ks + 1][2], sc[2 * ks + 1][3]);
	v_add_f32_e32 v170, v170, v19
	v_add_f32_e32 v171, v171, v20
	v_add_f32_e32 v170, v170, v21
	v_fma_f32 v26, v26, s46, v175
	v_fma_f32 v27, v27, s46, v175
	v_fma_f32 v28, v28, s46, v175
	v_fma_f32 v29, v29, s46, v175
	v_exp_f32_e32 v26, v26
	v_exp_f32_e32 v27, v27
	v_exp_f32_e32 v28, v28
	v_exp_f32_e32 v29, v29
	v_add_f32_e32 v171, v171, v22
	v_add_f32_e32 v170, v170, v23
	v_add_f32_e32 v171, v171, v24
	v_add_f32_e32 v170, v170, v25
	v_fma_f32 v30, v30, s46, v175
	v_fma_f32 v31, v31, s46, v175
	v_fma_f32 v32, v32, s46, v175
	v_fma_f32 v33, v33, s46, v175
	v_exp_f32_e32 v30, v30
	v_exp_f32_e32 v31, v31
	v_exp_f32_e32 v32, v32
	v_exp_f32_e32 v33, v33
	v_add_f32_e32 v171, v171, v26
	v_add_f32_e32 v170, v170, v27
	v_add_f32_e32 v171, v171, v28
	v_add_f32_e32 v170, v170, v29
	v_fma_f32 v34, v34, s46, v175
	v_fma_f32 v35, v35, s46, v175
	v_fma_f32 v36, v36, s46, v175
	v_fma_f32 v37, v37, s46, v175
	v_exp_f32_e32 v34, v34
	v_exp_f32_e32 v35, v35
	v_exp_f32_e32 v36, v36
	v_exp_f32_e32 v37, v37
	v_add_f32_e32 v171, v171, v30
	v_add_f32_e32 v170, v170, v31
	v_add_f32_e32 v171, v171, v32
	v_add_f32_e32 v170, v170, v33
	v_fma_f32 v38, v38, s46, v175
	v_fma_f32 v39, v39, s46, v175
	v_fma_f32 v40, v40, s46, v175
	v_fma_f32 v41, v41, s46, v175
	v_exp_f32_e32 v38, v38
	v_exp_f32_e32 v39, v39
	v_exp_f32_e32 v40, v40
	v_exp_f32_e32 v41, v41
	v_add_f32_e32 v171, v171, v34
	v_add_f32_e32 v170, v170, v35
	v_add_f32_e32 v171, v171, v36
	v_add_f32_e32 v170, v170, v37
	v_fma_f32 v42, v42, s46, v175
	v_fma_f32 v43, v43, s46, v175
	v_fma_f32 v44, v44, s46, v175
	v_fma_f32 v45, v45, s46, v175
	v_exp_f32_e32 v42, v42
	v_exp_f32_e32 v43, v43
	v_exp_f32_e32 v44, v44
	v_exp_f32_e32 v45, v45
	v_add_f32_e32 v171, v171, v38
	v_add_f32_e32 v170, v170, v39
	v_add_f32_e32 v171, v171, v40
	v_add_f32_e32 v170, v170, v41
	v_fma_f32 v46, v46, s46, v175
	v_fma_f32 v47, v47, s46, v175
	v_fma_f32 v48, v48, s46, v175
	v_fma_f32 v49, v49, s46, v175
	v_exp_f32_e32 v46, v46
	v_exp_f32_e32 v47, v47
	v_exp_f32_e32 v48, v48
	v_exp_f32_e32 v49, v49
	v_add_f32_e32 v171, v171, v42
	v_add_f32_e32 v170, v170, v43
	v_add_f32_e32 v171, v171, v44
	v_add_f32_e32 v170, v170, v45
	v_fma_f32 v50, v50, s46, v175
	v_fma_f32 v51, v51, s46, v175
	v_fma_f32 v52, v52, s46, v175
	v_fma_f32 v53, v53, s46, v175
	v_exp_f32_e32 v50, v50
	v_exp_f32_e32 v51, v51
	v_exp_f32_e32 v52, v52
	v_exp_f32_e32 v53, v53
	v_add_f32_e32 v171, v171, v46
	v_add_f32_e32 v170, v170, v47
	v_add_f32_e32 v171, v171, v48
	v_add_f32_e32 v170, v170, v49
	v_fma_f32 v54, v54, s46, v175
	v_fma_f32 v55, v55, s46, v175
	v_fma_f32 v56, v56, s46, v175
	v_fma_f32 v57, v57, s46, v175
	v_exp_f32_e32 v54, v54
	v_exp_f32_e32 v55, v55
	v_exp_f32_e32 v56, v56
	v_exp_f32_e32 v57, v57
	v_add_f32_e32 v171, v171, v50
	v_add_f32_e32 v170, v170, v51
	v_add_f32_e32 v171, v171, v52
	v_add_f32_e32 v170, v170, v53
	v_fma_f32 v58, v58, s46, v175
	v_fma_f32 v59, v59, s46, v175
	v_fma_f32 v60, v60, s46, v175
	v_fma_f32 v61, v61, s46, v175
	v_exp_f32_e32 v58, v58
	v_exp_f32_e32 v59, v59
	v_exp_f32_e32 v60, v60
	v_exp_f32_e32 v61, v61
	v_add_f32_e32 v171, v171, v54
	v_add_f32_e32 v170, v170, v55
	v_add_f32_e32 v171, v171, v56
	v_add_f32_e32 v170, v170, v57
	v_fma_f32 v62, v62, s46, v175
	v_fma_f32 v63, v63, s46, v175
	v_fma_f32 v64, v64, s46, v175
	v_fma_f32 v65, v65, s46, v175
	v_exp_f32_e32 v62, v62
	v_exp_f32_e32 v63, v63
	v_exp_f32_e32 v64, v64
	v_exp_f32_e32 v65, v65
	v_add_f32_e32 v171, v171, v58
	v_add_f32_e32 v170, v170, v59
	v_add_f32_e32 v171, v171, v60
	v_add_f32_e32 v170, v170, v61
	v_fma_f32 v66, v66, s46, v175
	v_fma_f32 v67, v67, s46, v175
	v_fma_f32 v68, v68, s46, v175
	v_fma_f32 v69, v69, s46, v175
	v_exp_f32_e32 v66, v66
	v_exp_f32_e32 v67, v67
	v_exp_f32_e32 v68, v68
	v_exp_f32_e32 v69, v69
	v_add_f32_e32 v171, v171, v62
	v_add_f32_e32 v170, v170, v63
	v_add_f32_e32 v171, v171, v64
	v_add_f32_e32 v170, v170, v65
	v_add_f32_e32 v171, v171, v66
	v_add_f32_e32 v170, v170, v67
	v_add_f32_e32 v171, v171, v68
	v_add_f32_e32 v170, v170, v69
	v_add_f32_e32 v170, v170, v171
	v_cvt_pk_bf16_f32 v2, v2, v3
	v_cvt_pk_bf16_f32 v3, v4, v5
	v_cvt_pk_bf16_f32 v4, v6, v7
	v_cvt_pk_bf16_f32 v5, v8, v9
	v_cvt_pk_bf16_f32 v10, v10, v11
	v_cvt_pk_bf16_f32 v11, v12, v13
	v_cvt_pk_bf16_f32 v12, v14, v15
	v_cvt_pk_bf16_f32 v13, v16, v17
	v_cvt_pk_bf16_f32 v18, v18, v19
	v_cvt_pk_bf16_f32 v19, v20, v21
	v_cvt_pk_bf16_f32 v20, v22, v23
	v_cvt_pk_bf16_f32 v21, v24, v25
	v_cvt_pk_bf16_f32 v26, v26, v27
	v_cvt_pk_bf16_f32 v27, v28, v29
	v_cvt_pk_bf16_f32 v28, v30, v31
	v_cvt_pk_bf16_f32 v29, v32, v33
	v_cvt_pk_bf16_f32 v34, v34, v35
	v_cvt_pk_bf16_f32 v35, v36, v37
	v_cvt_pk_bf16_f32 v36, v38, v39
	v_cvt_pk_bf16_f32 v37, v40, v41
	v_cvt_pk_bf16_f32 v42, v42, v43
	v_cvt_pk_bf16_f32 v43, v44, v45
	v_cvt_pk_bf16_f32 v44, v46, v47
	v_cvt_pk_bf16_f32 v45, v48, v49
	v_cvt_pk_bf16_f32 v50, v50, v51
	v_cvt_pk_bf16_f32 v51, v52, v53
	v_cvt_pk_bf16_f32 v52, v54, v55
	v_cvt_pk_bf16_f32 v53, v56, v57
	v_cvt_pk_bf16_f32 v58, v58, v59
	v_cvt_pk_bf16_f32 v59, v60, v61
	v_cvt_pk_bf16_f32 v60, v62, v63
	v_cvt_pk_bf16_f32 v61, v64, v65
	v_cvt_pk_bf16_f32 v66, v66, v67
	v_cvt_pk_bf16_f32 v67, v68, v69
	v_mov_b32_e32 v68, 0
	v_mov_b32_e32 v69, 0
	ds_bpermute_b32 v172, v1, v170
	v_sub_f32_e32 v173, v146, v169
	v_mul_f32_e32 v173, 0x3fb8aa3b, v173
	v_exp_f32_e32 v173, v173
	s_waitcnt lgkmcnt(0)
; __device__ __forceinline__ unsigned cvt_pk_bf16_asm(float lo, float hi) { unsigned r; asm volatile("v_cvt_pk_bf16_f32 %0, %1, %2" : "=v"(r) : "v"(lo), "v"(hi)); return r; }
; __device__ __forceinline__ f32x4 mfma16(bf16x8 a, bf16x8 b, f32x4 c) { return __builtin_amdgcn_mfma_f32_16x16x32_bf16(a, b, c, 0, 0, 0); }
; __device__ void att_phase(int wv, const Params& p, unsigned char* lds) {
;     ...
;             sum += __shfl_xor(sum, 16); sum += __shfl_xor(sum, 32);
;             sum += __expf(sink - mx);
;             const float inv = 1.0f / sum;
;             f32x4 oa[4];
; #pragma unroll
;             for (int db = 0; db < 4; ++db) oa[db] = (f32x4){0, 0, 0, 0};
; #pragma unroll
;             for (int ks = 0; ks < 12; ++ks) {
;                 union { bf16x8 v; unsigned u[4]; } pf;
;                 pf.u[0] = cvt_pk_bf16_asm(sc[2 * ks][0], sc[2 * ks][1]); pf.u[1] = cvt_pk_bf16_asm(sc[2 * ks][2], sc[2 * ks][3]);
;                 pf.u[2] = cvt_pk_bf16_asm(sc[2 * ks + 1][0], sc[2 * ks + 1][1]); pf.u[3] = cvt_pk_bf16_asm(sc[2 * ks + 1][2], sc[2 * ks + 1][3]);
; #pragma unroll
;                 for (int db = 0; db < 4; ++db) {
;                     union { bf16x8 v; u32x2 h2[2]; } vf;
;                     const bf16_t* vp = VTL + (16 * db + lr) * VP + 32 * ks + 4 * lq;
;                     vf.h2[0] = *(const u32x2*)vp; vf.h2[1] = *(const u32x2*)(vp + 16);
;                     oa[db] = mfma16(vf.v, pf.v, oa[db]); } }
; #pragma unroll
;             for (int db = 0; db < 4; ++db) { const f32x4 o = oa[db] * inv; u32x2 wv; wv.x = cvt_pk_bf16_asm(o[0], o[1]); wv.y = cvt_pk_bf16_asm(o[2], o[3]);
;                 *(u32x2*)(qkv + tokq * 1536 + 64 * h + 16 * db + 4 * lq) = wv; }
	v_add_f32_e32 v170, v170, v172
	ds_bpermute_b32 v172, v114, v170
	ds_read2_b64 v[232:235], v165 offset0:20 offset1:24
	ds_read2_b64 v[236:239], v166 offset0:20 offset1:24
	ds_read2_b64 v[240:243], v167 offset0:20 offset1:24
	ds_read2_b64 v[244:247], v168 offset0:20 offset1:24
	s_waitcnt lgkmcnt(4)
	v_mfma_f32_16x16x32_bf16 v[70:73], v[216:219], v[2:5], 0
	v_mfma_f32_16x16x32_bf16 v[74:77], v[220:223], v[2:5], 0
	v_mfma_f32_16x16x32_bf16 v[78:81], v[224:227], v[2:5], 0
	v_mfma_f32_16x16x32_bf16 v[82:85], v[228:231], v[2:5], 0
	v_add_f32_e32 v170, v170, v172
	v_add_f32_e32 v170, v170, v173
	v_rcp_f32_e32 v147, v170
	s_nop 0
	v_fma_f32 v179, -v170, v147, 1.0
	v_fmac_f32_e32 v147, v179, v147
	ds_read2_b64 v[216:219], v165 offset0:28 offset1:32
	ds_read2_b64 v[220:223], v166 offset0:28 offset1:32
	ds_read2_b64 v[224:227], v167 offset0:28 offset1:32
	ds_read2_b64 v[228:231], v168 offset0:28 offset1:32
	s_waitcnt lgkmcnt(4)
	v_mfma_f32_16x16x32_bf16 v[70:73], v[232:235], v[10:13], v[70:73]
	v_mfma_f32_16x16x32_bf16 v[74:77], v[236:239], v[10:13], v[74:77]
	v_mfma_f32_16x16x32_bf16 v[78:81], v[240:243], v[10:13], v[78:81]
	v_mfma_f32_16x16x32_bf16 v[82:85], v[244:247], v[10:13], v[82:85]
	ds_read2_b64 v[232:235], v165 offset0:36 offset1:40
	ds_read2_b64 v[236:239], v166 offset0:36 offset1:40
	ds_read2_b64 v[240:243], v167 offset0:36 offset1:40
	ds_read2_b64 v[244:247], v168 offset0:36 offset1:40
	s_waitcnt lgkmcnt(4)
	v_mfma_f32_16x16x32_bf16 v[70:73], v[216:219], v[18:21], v[70:73]
	v_mfma_f32_16x16x32_bf16 v[74:77], v[220:223], v[18:21], v[74:77]
	v_mfma_f32_16x16x32_bf16 v[78:81], v[224:227], v[18:21], v[78:81]
	v_mfma_f32_16x16x32_bf16 v[82:85], v[228:231], v[18:21], v[82:85]
	ds_read2_b64 v[216:219], v165 offset0:44 offset1:48
	ds_read2_b64 v[220:223], v166 offset0:44 offset1:48
	ds_read2_b64 v[224:227], v167 offset0:44 offset1:48
	ds_read2_b64 v[228:231], v168 offset0:44 offset1:48
	s_waitcnt lgkmcnt(4)
	v_mfma_f32_16x16x32_bf16 v[70:73], v[232:235], v[26:29], v[70:73]
	v_mfma_f32_16x16x32_bf16 v[74:77], v[236:239], v[26:29], v[74:77]
	v_mfma_f32_16x16x32_bf16 v[78:81], v[240:243], v[26:29], v[78:81]
	v_mfma_f32_16x16x32_bf16 v[82:85], v[244:247], v[26:29], v[82:85]
	ds_read2_b64 v[232:235], v165 offset0:52 offset1:56
	ds_read2_b64 v[236:239], v166 offset0:52 offset1:56
	ds_read2_b64 v[240:243], v167 offset0:52 offset1:56
	ds_read2_b64 v[244:247], v168 offset0:52 offset1:56
	s_waitcnt lgkmcnt(4)
	v_mfma_f32_16x16x32_bf16 v[70:73], v[216:219], v[34:37], v[70:73]
	v_mfma_f32_16x16x32_bf16 v[74:77], v[220:223], v[34:37], v[74:77]
	v_mfma_f32_16x16x32_bf16 v[78:81], v[224:227], v[34:37], v[78:81]
	v_mfma_f32_16x16x32_bf16 v[82:85], v[228:231], v[34:37], v[82:85]
	ds_read2_b64 v[216:219], v165 offset0:60 offset1:64
	ds_read2_b64 v[220:223], v166 offset0:60 offset1:64
	ds_read2_b64 v[224:227], v167 offset0:60 offset1:64
	ds_read2_b64 v[228:231], v168 offset0:60 offset1:64
	s_waitcnt lgkmcnt(4)
	v_mfma_f32_16x16x32_bf16 v[70:73], v[232:235], v[42:45], v[70:73]
	v_mfma_f32_16x16x32_bf16 v[74:77], v[236:239], v[42:45], v[74:77]
	v_mfma_f32_16x16x32_bf16 v[78:81], v[240:243], v[42:45], v[78:81]
	v_mfma_f32_16x16x32_bf16 v[82:85], v[244:247], v[42:45], v[82:85]
	ds_read2_b64 v[232:235], v165 offset0:68 offset1:72
	ds_read2_b64 v[236:239], v166 offset0:68 offset1:72
	ds_read2_b64 v[240:243], v167 offset0:68 offset1:72
	ds_read2_b64 v[244:247], v168 offset0:68 offset1:72
	s_waitcnt lgkmcnt(4)
	v_mfma_f32_16x16x32_bf16 v[70:73], v[216:219], v[50:53], v[70:73]
	v_mfma_f32_16x16x32_bf16 v[74:77], v[220:223], v[50:53], v[74:77]
	v_mfma_f32_16x16x32_bf16 v[78:81], v[224:227], v[50:53], v[78:81]
	v_mfma_f32_16x16x32_bf16 v[82:85], v[228:231], v[50:53], v[82:85]
	ds_read2_b64 v[216:219], v165 offset0:76 offset1:76
	ds_read2_b64 v[220:223], v166 offset0:76 offset1:76
	ds_read2_b64 v[224:227], v167 offset0:76 offset1:76
	ds_read2_b64 v[228:231], v168 offset0:76 offset1:76
	s_waitcnt lgkmcnt(4)
	v_mfma_f32_16x16x32_bf16 v[70:73], v[232:235], v[58:61], v[70:73]
	v_mfma_f32_16x16x32_bf16 v[74:77], v[236:239], v[58:61], v[74:77]
	v_mfma_f32_16x16x32_bf16 v[78:81], v[240:243], v[58:61], v[78:81]
	v_mfma_f32_16x16x32_bf16 v[82:85], v[244:247], v[58:61], v[82:85]
	s_waitcnt lgkmcnt(0)
	v_mfma_f32_16x16x32_bf16 v[70:73], v[216:219], v[66:69], v[70:73]
	v_mfma_f32_16x16x32_bf16 v[74:77], v[220:223], v[66:69], v[74:77]
	v_mfma_f32_16x16x32_bf16 v[78:81], v[224:227], v[66:69], v[78:81]
	v_mfma_f32_16x16x32_bf16 v[82:85], v[228:231], v[66:69], v[82:85]
	s_nop 7
	s_nop 1
	v_mul_f32_e32 v70, v70, v147
	v_mul_f32_e32 v71, v71, v147
	v_mul_f32_e32 v72, v72, v147
	v_mul_f32_e32 v73, v73, v147
	v_mul_f32_e32 v74, v74, v147
	v_mul_f32_e32 v75, v75, v147
	v_mul_f32_e32 v76, v76, v147
	v_mul_f32_e32 v77, v77, v147
	v_mul_f32_e32 v78, v78, v147
	v_mul_f32_e32 v79, v79, v147
	v_mul_f32_e32 v80, v80, v147
	v_mul_f32_e32 v81, v81, v147
	v_mul_f32_e32 v82, v82, v147
	v_mul_f32_e32 v83, v83, v147
	v_mul_f32_e32 v84, v84, v147
	v_mul_f32_e32 v85, v85, v147
	v_cvt_pk_bf16_f32 v70, v70, v71
	v_cvt_pk_bf16_f32 v71, v72, v73
	v_cvt_pk_bf16_f32 v74, v74, v75
	v_cvt_pk_bf16_f32 v75, v76, v77
	v_cvt_pk_bf16_f32 v78, v78, v79
	v_cvt_pk_bf16_f32 v79, v80, v81
	v_cvt_pk_bf16_f32 v82, v82, v83
	v_cvt_pk_bf16_f32 v83, v84, v85
	global_store_dwordx2 v[248:249], v[70:71], off offset:-64
	global_store_dwordx2 v[248:249], v[74:75], off offset:-32
	global_store_dwordx2 v[248:249], v[78:79], off
	global_store_dwordx2 v[248:249], v[82:83], off offset:32
	s_branch .Latt_done
